# fragment reads hoisted above the unit decode in all 12 GEMM loops; phase-13 tile-to-expert table kept in registers (no per-unit reload or drain)
# baseline (speedup 1.0000x reference)
; #define PG8_STAGE(bufoff, gbase, voff) do { _Pragma("unroll") for (int _i = 0; _i < 2; ++_i) \
;         __builtin_amdgcn_global_load_lds((const unsigned*)((const char*)(gbase) + (voff)[_i]), (LAS unsigned*)(lds + (bufoff) + ldsw + _i * 8192), 16, 0, 0); } while (0)
; #define PG8_LDA(dst, b, h) do { _Pragma("unroll") for (int m = 0; m < 4; ++m) _Pragma("unroll") for (int k = 0; k < 2; ++k) dst[m][k] = *(const LAS bf16x8*)(lds + PG8_SA(b, h) + aoff + m * 2048 + k * 1024); } while (0)
; #define PG8_LDB(dst, b, h) do { _Pragma("unroll") for (int n = 0; n < 2; ++n) _Pragma("unroll") for (int k = 0; k < 2; ++k) dst[n][k] = *(const LAS bf16x8*)(lds + PG8_SB(b, h) + boff + n * 2048 + k * 1024); } while (0)
; #define PG8_SCHED __builtin_amdgcn_sched_barrier(0)
;     __device__ __forceinline__ bool next(int i, Unit& u) const {
;         const long L = (long)i * G + c; if (L >= nwg) return false;
;         int wgid = (int)L; { const int q = nwg / NXCD, r = nwg % NXCD, xcd = wgid % NXCD, off = wgid / NXCD; wgid = (xcd < r ? xcd * (q + 1) : r * (q + 1) + (xcd - r) * q) + off; }
;         const int nig = WGM * nN, gid = wgid / nig, fm = gid * WGM, gsz = (nM - fm) < WGM ? (nM - fm) : WGM;
;         u.pm = fm + ((wgid % nig) % gsz); u.pn = (wgid % nig) / gsz; u.e = 0; u.kt0 = 0; u.nkt = nt; u.buf = 0;
;     ...
;     for (;;) {
;         const bool has_next = S.next(ui + 1, nxt);
;         const char* nA = has_next ? (const char*)g.A + (size_t)nxt.pm * tstep + (size_t)nxt.kt0 * kstep : cA; const char* nB = has_next ? (const char*)g.Bt + (size_t)nxt.e * g.estride + (size_t)nxt.pn * tstep + (size_t)nxt.kt0 * kstep : cB;
;         const int nt = cur.nkt;
;         for (int t = 0; t < nt; t += 2) {
;             const bool last = (t == nt - 2);
;             const char* a1 = cA + (size_t)(t + 1) * kstep;
;             const char* a2 = last ? nA : cA + (size_t)(t + 2) * kstep; const char* b2 = last ? nB : cB + (size_t)(t + 2) * kstep;
;             const char* a3 = a2 + kstep; const char* b3 = b2 + kstep;
;             PG8_LDB(B0, 0, 0); PG8_LDB(B1, 0, 1); PG8_SCHED; PG8_LDA(At, 0, 0); PG8_STAGE(PG8_SA(1, 1), a1 + hstep, voffA);
.LBB0_3679:
	ds_read_b128 v[24:27], v187
	ds_read_b128 v[28:31], v187 offset:1024
	ds_read_b128 v[16:19], v187 offset:2048
	ds_read_b128 v[20:23], v187 offset:3072
	ds_read_b128 v[8:11], v188
	ds_read_b128 v[12:15], v188 offset:1024
	ds_read_b128 v[4:7], v188 offset:3072
	ds_read_b128 v[176:179], v189
	ds_read_b128 v[180:183], v189 offset:1024
	ds_read_b128 v[194:197], v189 offset:2048
	ds_read_b128 v[198:201], v189 offset:3072
	ds_read_b128 v[202:205], v189 offset:4096
	ds_read_b128 v[206:209], v189 offset:5120
	ds_read_b128 v[210:213], v189 offset:6144
	ds_read_b128 v[214:217], v189 offset:7168
	s_add_i32 s54, s54, 1
	s_mul_i32 s4, s54, s59
	s_mul_hi_u32 s5, s54, s33
	s_add_i32 s5, s5, s4
	s_mul_i32 s4, s54, s33
	s_add_u32 s36, s4, s22
	s_addc_u32 s37, s5, s60
	v_cmp_gt_i64_e32 vcc, s[36:37], v[174:175]
	v_cmp_lt_i64_e64 s[4:5], s[36:37], v[172:173]
	s_cbranch_vccnz .LBB0_3685
	s_ashr_i32 s28, s36, 31
	s_lshr_b32 s28, s28, 29
	s_add_i32 s30, s36, s28
	s_and_b32 s28, s30, -8
	s_sub_i32 s31, s36, s28
	s_cmp_gt_i32 s31, -1
	s_mov_b64 s[28:29], -1
	s_cbranch_scc0 .LBB0_3682
	s_lshl_b32 s36, s31, 6
	s_mov_b64 s[28:29], 0

; #define PG8_STAGE(bufoff, gbase, voff) do { _Pragma("unroll") for (int _i = 0; _i < 2; ++_i) \
;         __builtin_amdgcn_global_load_lds((const unsigned*)((const char*)(gbase) + (voff)[_i]), (LAS unsigned*)(lds + (bufoff) + ldsw + _i * 8192), 16, 0, 0); } while (0)
; #define PG8_LDA(dst, b, h) do { _Pragma("unroll") for (int m = 0; m < 4; ++m) _Pragma("unroll") for (int k = 0; k < 2; ++k) dst[m][k] = *(const LAS bf16x8*)(lds + PG8_SA(b, h) + aoff + m * 2048 + k * 1024); } while (0)
; #define PG8_LDB(dst, b, h) do { _Pragma("unroll") for (int n = 0; n < 2; ++n) _Pragma("unroll") for (int k = 0; k < 2; ++k) dst[n][k] = *(const LAS bf16x8*)(lds + PG8_SB(b, h) + boff + n * 2048 + k * 1024); } while (0)
; #define PG8_WAIT_V(n) asm volatile("s_waitcnt vmcnt(" #n ")" ::: "memory")
; #define PG8_WAIT_L(n) asm volatile("s_waitcnt lgkmcnt(" #n ")" ::: "memory")
; #define PG8_BAR __builtin_amdgcn_s_barrier()
; #define PG8_SCHED __builtin_amdgcn_sched_barrier(0)
;     ...
;         const char* nA = has_next ? (const char*)g.A + (size_t)nxt.pm * tstep + (size_t)nxt.kt0 * kstep : cA; const char* nB = has_next ? (const char*)g.Bt + (size_t)nxt.e * g.estride + (size_t)nxt.pn * tstep + (size_t)nxt.kt0 * kstep : cB;
;         const int nt = cur.nkt;
;         for (int t = 0; t < nt; t += 2) {
;             const bool last = (t == nt - 2);
;             const char* a1 = cA + (size_t)(t + 1) * kstep;
;             const char* a2 = last ? nA : cA + (size_t)(t + 2) * kstep; const char* b2 = last ? nB : cB + (size_t)(t + 2) * kstep;
;             const char* a3 = a2 + kstep; const char* b3 = b2 + kstep;
;             PG8_LDB(B0, 0, 0); PG8_LDB(B1, 0, 1); PG8_SCHED; PG8_LDA(At, 0, 0); PG8_STAGE(PG8_SA(1, 1), a1 + hstep, voffA);
;             PG8_WAIT_V(8); PG8_WAIT_L(0); PG8_BAR; PG8_MMA(0, 0, At, B0); PG8_MMA(0, 1, At, B1); PG8_BAR; PG8_SCHED;
;             PG8_LDA(At, 0, 1); PG8_STAGE(PG8_SB(0, 0), b2, voffB); PG8_STAGE(PG8_SB(0, 1), b2 + hstep, voffB); PG8_STAGE(PG8_SA(0, 0), a2, voffA);
;             PG8_WAIT_V(8); PG8_WAIT_L(0); PG8_BAR; PG8_MMA(1, 0, At, B0); PG8_MMA(1, 1, At, B1); PG8_BAR; PG8_SCHED;
.LBB0_3685:
	s_ashr_i32 s31, s30, 31
	s_lshl_b64 s[36:37], s[30:31], 19
	s_add_u32 s36, s21, s36
	s_addc_u32 s37, s23, s37
	s_and_b64 s[38:39], s[4:5], exec
	s_cselect_b32 s31, s37, s45
	s_cselect_b32 s41, s36, s44
	s_ashr_i32 s29, s28, 31
	s_lshl_b64 s[38:39], s[28:29], 19
	s_add_u32 s38, s25, s38
	s_addc_u32 s39, s27, s39
	s_and_b64 s[48:49], s[4:5], exec
	s_cselect_b32 s29, s39, s47
	s_cselect_b32 s66, s38, s46
	s_add_u32 s44, s44, 0x40080
	s_addc_u32 s45, s45, 0
	s_add_u32 s67, s46, 0x100
	s_addc_u32 s68, s47, 0
	s_mov_b32 s69, -2
	s_waitcnt lgkmcnt(0)
	ds_read_b128 v[0:3], v188 offset:2048
	s_add_u32 s46, s44, 0xfffc0080
	s_addc_u32 s47, s45, -1
	s_cmp_eq_u32 s69, 12
	s_cselect_b32 s49, s31, s47
	s_cselect_b32 s48, s41, s46
	s_cselect_b32 s47, s29, s68
	s_cselect_b32 s46, s66, s67
	v_lshl_add_u64 v[218:219], s[44:45], 0, v[168:169]
	s_add_i32 m0, s35, 0xc000
	global_load_lds_dwordx4 v[218:219], off
	v_lshl_add_u64 v[218:219], s[44:45], 0, v[170:171]
	s_add_i32 m0, s35, 0xe000
	s_nop 0
	global_load_lds_dwordx4 v[218:219], off
	s_waitcnt vmcnt(8)
	s_waitcnt lgkmcnt(0)
	s_barrier
	s_setprio 1
	s_waitcnt lgkmcnt(0)
	v_mfma_scale_f32_16x16x128_f8f6f4 v[156:159], v[24:31], v[176:183], 0, v190, v190 op_sel_hi:[0,0,0]
	v_mfma_scale_f32_16x16x128_f8f6f4 v[152:155], v[16:23], v[176:183], 0, v190, v190 op_sel_hi:[0,0,0]
	v_mfma_scale_f32_16x16x128_f8f6f4 v[140:143], v[24:31], v[194:201], 0, v190, v190 op_sel_hi:[0,0,0]
	v_mfma_scale_f32_16x16x128_f8f6f4 v[136:139], v[16:23], v[194:201], 0, v190, v190 op_sel_hi:[0,0,0]
	v_mfma_scale_f32_16x16x128_f8f6f4 v[124:127], v[24:31], v[202:209], 0, v190, v190 op_sel_hi:[0,0,0]
	v_mfma_scale_f32_16x16x128_f8f6f4 v[120:123], v[16:23], v[202:209], 0, v190, v190 op_sel_hi:[0,0,0]
	v_mfma_scale_f32_16x16x128_f8f6f4 v[108:111], v[24:31], v[210:217], 0, v190, v190 op_sel_hi:[0,0,0]
	v_mfma_scale_f32_16x16x128_f8f6f4 v[104:107], v[16:23], v[210:217], 0, v190, v190 op_sel_hi:[0,0,0]
	s_setprio 0
	s_setprio 1
	v_mfma_scale_f32_16x16x128_f8f6f4 v[148:151], v[8:15], v[176:183], 0, v190, v190 op_sel_hi:[0,0,0]
	v_mfma_scale_f32_16x16x128_f8f6f4 v[144:147], v[0:7], v[176:183], 0, v190, v190 op_sel_hi:[0,0,0]
	v_mfma_scale_f32_16x16x128_f8f6f4 v[132:135], v[8:15], v[194:201], 0, v190, v190 op_sel_hi:[0,0,0]
	v_mfma_scale_f32_16x16x128_f8f6f4 v[128:131], v[0:7], v[194:201], 0, v190, v190 op_sel_hi:[0,0,0]
	v_mfma_scale_f32_16x16x128_f8f6f4 v[116:119], v[8:15], v[202:209], 0, v190, v190 op_sel_hi:[0,0,0]
	v_mfma_scale_f32_16x16x128_f8f6f4 v[112:115], v[0:7], v[202:209], 0, v190, v190 op_sel_hi:[0,0,0]
	v_mfma_scale_f32_16x16x128_f8f6f4 v[100:103], v[8:15], v[210:217], 0, v190, v190 op_sel_hi:[0,0,0]
	v_mfma_scale_f32_16x16x128_f8f6f4 v[96:99], v[0:7], v[210:217], 0, v190, v190 op_sel_hi:[0,0,0]
	s_setprio 0
	s_barrier
	s_add_i32 s70, s61, s34
	v_lshl_add_u64 v[176:177], s[46:47], 0, v[162:163]
	s_mov_b32 m0, s70
	ds_read_b128 v[194:197], v189 offset:16384
	ds_read_b128 v[198:201], v189 offset:17408
	ds_read_b128 v[202:205], v189 offset:18432
	ds_read_b128 v[206:209], v189 offset:19456
	ds_read_b128 v[210:213], v189 offset:20480
	ds_read_b128 v[214:217], v189 offset:21504
	ds_read_b128 v[218:221], v189 offset:22528
	ds_read_b128 v[222:225], v189 offset:23552
	global_load_lds_dwordx4 v[176:177], off
	s_add_i32 m0, s70, 0x2000
	s_add_u32 s70, s46, 0x40000
	v_lshl_add_u64 v[178:179], s[46:47], 0, v[166:167]
	s_addc_u32 s71, s47, 0
	s_add_i32 s72, s62, s34
	global_load_lds_dwordx4 v[178:179], off
	v_lshl_add_u64 v[180:181], s[70:71], 0, v[162:163]
	s_mov_b32 m0, s72
	v_lshl_add_u64 v[182:183], s[48:49], 0, v[164:165]
	global_load_lds_dwordx4 v[180:181], off
	v_lshl_add_u64 v[180:181], s[70:71], 0, v[166:167]
	s_add_i32 m0, s72, 0x2000
	s_nop 0
	global_load_lds_dwordx4 v[180:181], off
	v_lshl_add_u64 v[180:181], s[48:49], 0, v[160:161]
	s_mov_b32 m0, s35
	s_nop 0
	global_load_lds_dwordx4 v[180:181], off
	s_mov_b32 m0, s43
	s_nop 0
	global_load_lds_dwordx4 v[182:183], off
	s_waitcnt vmcnt(8)
	s_waitcnt lgkmcnt(0)
	s_barrier
	s_setprio 1
	s_waitcnt lgkmcnt(0)
	v_mfma_scale_f32_16x16x128_f8f6f4 v[92:95], v[24:31], v[194:201], 0, v190, v190 op_sel_hi:[0,0,0]
	v_mfma_scale_f32_16x16x128_f8f6f4 v[88:91], v[16:23], v[194:201], 0, v190, v190 op_sel_hi:[0,0,0]
	v_mfma_scale_f32_16x16x128_f8f6f4 v[76:79], v[24:31], v[202:209], 0, v190, v190 op_sel_hi:[0,0,0]
	v_mfma_scale_f32_16x16x128_f8f6f4 v[72:75], v[16:23], v[202:209], 0, v190, v190 op_sel_hi:[0,0,0]
	v_mfma_scale_f32_16x16x128_f8f6f4 v[60:63], v[24:31], v[210:217], 0, v190, v190 op_sel_hi:[0,0,0]
	v_mfma_scale_f32_16x16x128_f8f6f4 v[56:59], v[16:23], v[210:217], 0, v190, v190 op_sel_hi:[0,0,0]
	v_mfma_scale_f32_16x16x128_f8f6f4 v[44:47], v[24:31], v[218:225], 0, v190, v190 op_sel_hi:[0,0,0]
	v_mfma_scale_f32_16x16x128_f8f6f4 v[40:43], v[16:23], v[218:225], 0, v190, v190 op_sel_hi:[0,0,0]
	s_setprio 0
	s_setprio 1
	v_mfma_scale_f32_16x16x128_f8f6f4 v[84:87], v[8:15], v[194:201], 0, v190, v190 op_sel_hi:[0,0,0]
	v_mfma_scale_f32_16x16x128_f8f6f4 v[80:83], v[0:7], v[194:201], 0, v190, v190 op_sel_hi:[0,0,0]
	v_mfma_scale_f32_16x16x128_f8f6f4 v[68:71], v[8:15], v[202:209], 0, v190, v190 op_sel_hi:[0,0,0]
	v_mfma_scale_f32_16x16x128_f8f6f4 v[64:67], v[0:7], v[202:209], 0, v190, v190 op_sel_hi:[0,0,0]
	v_mfma_scale_f32_16x16x128_f8f6f4 v[52:55], v[8:15], v[210:217], 0, v190, v190 op_sel_hi:[0,0,0]
	v_mfma_scale_f32_16x16x128_f8f6f4 v[48:51], v[0:7], v[210:217], 0, v190, v190 op_sel_hi:[0,0,0]
	v_mfma_scale_f32_16x16x128_f8f6f4 v[36:39], v[8:15], v[218:225], 0, v190, v190 op_sel_hi:[0,0,0]
	v_mfma_scale_f32_16x16x128_f8f6f4 v[32:35], v[0:7], v[218:225], 0, v190, v190 op_sel_hi:[0,0,0]
	s_setprio 0
	s_barrier
; #define PG8_STAGE(bufoff, gbase, voff) do { _Pragma("unroll") for (int _i = 0; _i < 2; ++_i) \
;         __builtin_amdgcn_global_load_lds((const unsigned*)((const char*)(gbase) + (voff)[_i]), (LAS unsigned*)(lds + (bufoff) + ldsw + _i * 8192), 16, 0, 0); } while (0)
; #define PG8_LDA(dst, b, h) do { _Pragma("unroll") for (int m = 0; m < 4; ++m) _Pragma("unroll") for (int k = 0; k < 2; ++k) dst[m][k] = *(const LAS bf16x8*)(lds + PG8_SA(b, h) + aoff + m * 2048 + k * 1024); } while (0)
; #define PG8_LDB(dst, b, h) do { _Pragma("unroll") for (int n = 0; n < 2; ++n) _Pragma("unroll") for (int k = 0; k < 2; ++k) dst[n][k] = *(const LAS bf16x8*)(lds + PG8_SB(b, h) + boff + n * 2048 + k * 1024); } while (0)
; #define PG8_WAIT_V(n) asm volatile("s_waitcnt vmcnt(" #n ")" ::: "memory")
; #define PG8_WAIT_L(n) asm volatile("s_waitcnt lgkmcnt(" #n ")" ::: "memory")
; #define PG8_BAR __builtin_amdgcn_s_barrier()
; #define PG8_SCHED __builtin_amdgcn_sched_barrier(0)
;     ...
;             PG8_LDB(B0, 1, 0); PG8_LDB(B1, 1, 1); PG8_SCHED; PG8_LDA(At, 1, 0); PG8_STAGE(PG8_SA(0, 1), a2 + hstep, voffA);
;             PG8_WAIT_V(8); PG8_WAIT_L(0); PG8_BAR; PG8_MMA(0, 0, At, B0); PG8_MMA(0, 1, At, B1); PG8_BAR; PG8_SCHED;
;             PG8_LDA(At, 1, 1); PG8_STAGE(PG8_SB(1, 0), b3, voffB); PG8_STAGE(PG8_SB(1, 1), b3 + hstep, voffB); PG8_STAGE(PG8_SA(1, 0), a3, voffA);
;             PG8_WAIT_V(8); PG8_WAIT_L(0); PG8_BAR; PG8_MMA(1, 0, At, B0); PG8_MMA(1, 1, At, B1); PG8_BAR; PG8_SCHED;
;         }
	s_add_i32 s70, 0, 0x18000
	s_add_i32 s71, 0, 0x1c000
	v_add_u32_e32 v12, s70, v185
	v_add_u32_e32 v28, s71, v185
	ds_read_b128 v[0:3], v12
	ds_read_b128 v[4:7], v12 offset:1024
	ds_read_b128 v[8:11], v12 offset:2048
	ds_read_b128 v[12:15], v12 offset:3072
	ds_read_b128 v[16:19], v28
	ds_read_b128 v[20:23], v28 offset:1024
	ds_read_b128 v[24:27], v28 offset:2048
	ds_read_b128 v[28:31], v28 offset:3072
	s_add_u32 s48, s48, 0x40000
	s_addc_u32 s49, s49, 0
	s_mov_b32 m0, s50
	v_lshl_add_u64 v[226:227], s[48:49], 0, v[160:161]
	ds_read_b128 v[194:197], v189 offset:32768
	ds_read_b128 v[198:201], v189 offset:33792
	ds_read_b128 v[202:205], v189 offset:34816
	ds_read_b128 v[206:209], v189 offset:35840
	ds_read_b128 v[210:213], v189 offset:36864
	ds_read_b128 v[214:217], v189 offset:37888
	ds_read_b128 v[218:221], v189 offset:38912
	ds_read_b128 v[222:225], v189 offset:39936
	global_load_lds_dwordx4 v[226:227], off
	v_lshl_add_u64 v[226:227], s[48:49], 0, v[164:165]
	s_mov_b32 m0, s51
	s_nop 0
	global_load_lds_dwordx4 v[226:227], off
	s_waitcnt vmcnt(8)
	s_waitcnt lgkmcnt(0)
	s_barrier
	s_setprio 1
	s_waitcnt lgkmcnt(0)
	v_mfma_scale_f32_16x16x128_f8f6f4 v[156:159], v[0:7], v[194:201], v[156:159], v190, v190 op_sel_hi:[0,0,0]
	v_mfma_scale_f32_16x16x128_f8f6f4 v[152:155], v[8:15], v[194:201], v[152:155], v190, v190 op_sel_hi:[0,0,0]
	v_mfma_scale_f32_16x16x128_f8f6f4 v[140:143], v[0:7], v[202:209], v[140:143], v190, v190 op_sel_hi:[0,0,0]
	v_mfma_scale_f32_16x16x128_f8f6f4 v[136:139], v[8:15], v[202:209], v[136:139], v190, v190 op_sel_hi:[0,0,0]
	v_mfma_scale_f32_16x16x128_f8f6f4 v[124:127], v[0:7], v[210:217], v[124:127], v190, v190 op_sel_hi:[0,0,0]
	v_mfma_scale_f32_16x16x128_f8f6f4 v[120:123], v[8:15], v[210:217], v[120:123], v190, v190 op_sel_hi:[0,0,0]
	v_mfma_scale_f32_16x16x128_f8f6f4 v[108:111], v[0:7], v[218:225], v[108:111], v190, v190 op_sel_hi:[0,0,0]
	v_mfma_scale_f32_16x16x128_f8f6f4 v[104:107], v[8:15], v[218:225], v[104:107], v190, v190 op_sel_hi:[0,0,0]
	s_setprio 0
	s_setprio 1
	v_mfma_scale_f32_16x16x128_f8f6f4 v[148:151], v[16:23], v[194:201], v[148:151], v190, v190 op_sel_hi:[0,0,0]
	v_mfma_scale_f32_16x16x128_f8f6f4 v[144:147], v[24:31], v[194:201], v[144:147], v190, v190 op_sel_hi:[0,0,0]
	v_mfma_scale_f32_16x16x128_f8f6f4 v[132:135], v[16:23], v[202:209], v[132:135], v190, v190 op_sel_hi:[0,0,0]
	v_mfma_scale_f32_16x16x128_f8f6f4 v[128:131], v[24:31], v[202:209], v[128:131], v190, v190 op_sel_hi:[0,0,0]
	v_mfma_scale_f32_16x16x128_f8f6f4 v[116:119], v[16:23], v[210:217], v[116:119], v190, v190 op_sel_hi:[0,0,0]
	v_mfma_scale_f32_16x16x128_f8f6f4 v[112:115], v[24:31], v[210:217], v[112:115], v190, v190 op_sel_hi:[0,0,0]
	v_mfma_scale_f32_16x16x128_f8f6f4 v[100:103], v[16:23], v[218:225], v[100:103], v190, v190 op_sel_hi:[0,0,0]
	v_mfma_scale_f32_16x16x128_f8f6f4 v[96:99], v[24:31], v[218:225], v[96:99], v190, v190 op_sel_hi:[0,0,0]
	s_setprio 0
	s_barrier
	s_add_i32 s48, s70, s34
	v_lshl_add_u64 v[176:177], v[176:177], 0, s[16:17]
	s_mov_b32 m0, s48
	ds_read_b128 v[194:197], v189 offset:49152
	ds_read_b128 v[198:201], v189 offset:50176
	ds_read_b128 v[202:205], v189 offset:51200
	ds_read_b128 v[206:209], v189 offset:52224
	ds_read_b128 v[210:213], v189 offset:53248
	ds_read_b128 v[214:217], v189 offset:54272
	ds_read_b128 v[218:221], v189 offset:55296
	ds_read_b128 v[222:225], v189 offset:56320
	global_load_lds_dwordx4 v[176:177], off
	s_add_i32 m0, s48, 0x2000
	s_add_u32 s46, s46, 0x40080
	v_lshl_add_u64 v[176:177], v[178:179], 0, s[16:17]
	s_addc_u32 s47, s47, 0
	s_add_i32 s48, s71, s34
	global_load_lds_dwordx4 v[176:177], off
	v_lshl_add_u64 v[176:177], s[46:47], 0, v[162:163]
	s_mov_b32 m0, s48
	s_nop 0
	global_load_lds_dwordx4 v[176:177], off
	v_lshl_add_u64 v[176:177], s[46:47], 0, v[166:167]
	s_add_i32 m0, s48, 0x2000
	s_nop 0
	global_load_lds_dwordx4 v[176:177], off
	v_lshl_add_u64 v[176:177], v[180:181], 0, s[16:17]
	s_mov_b32 m0, s55
	s_nop 0
	global_load_lds_dwordx4 v[176:177], off
	v_lshl_add_u64 v[176:177], v[182:183], 0, s[16:17]
	s_mov_b32 m0, s58
	s_nop 0
	global_load_lds_dwordx4 v[176:177], off
	s_waitcnt vmcnt(8)
	s_waitcnt lgkmcnt(0)
	s_barrier
	s_setprio 1
	s_waitcnt lgkmcnt(0)
	v_mfma_scale_f32_16x16x128_f8f6f4 v[92:95], v[0:7], v[194:201], v[92:95], v190, v190 op_sel_hi:[0,0,0]
	v_mfma_scale_f32_16x16x128_f8f6f4 v[88:91], v[8:15], v[194:201], v[88:91], v190, v190 op_sel_hi:[0,0,0]
	v_mfma_scale_f32_16x16x128_f8f6f4 v[76:79], v[0:7], v[202:209], v[76:79], v190, v190 op_sel_hi:[0,0,0]
	v_mfma_scale_f32_16x16x128_f8f6f4 v[72:75], v[8:15], v[202:209], v[72:75], v190, v190 op_sel_hi:[0,0,0]
	v_mfma_scale_f32_16x16x128_f8f6f4 v[60:63], v[0:7], v[210:217], v[60:63], v190, v190 op_sel_hi:[0,0,0]
	v_mfma_scale_f32_16x16x128_f8f6f4 v[56:59], v[8:15], v[210:217], v[56:59], v190, v190 op_sel_hi:[0,0,0]
	v_mfma_scale_f32_16x16x128_f8f6f4 v[44:47], v[0:7], v[218:225], v[44:47], v190, v190 op_sel_hi:[0,0,0]
	v_mfma_scale_f32_16x16x128_f8f6f4 v[40:43], v[8:15], v[218:225], v[40:43], v190, v190 op_sel_hi:[0,0,0]
	s_setprio 0
	s_setprio 1
	v_mfma_scale_f32_16x16x128_f8f6f4 v[84:87], v[16:23], v[194:201], v[84:87], v190, v190 op_sel_hi:[0,0,0]
	v_mfma_scale_f32_16x16x128_f8f6f4 v[80:83], v[24:31], v[194:201], v[80:83], v190, v190 op_sel_hi:[0,0,0]
	v_mfma_scale_f32_16x16x128_f8f6f4 v[68:71], v[16:23], v[202:209], v[68:71], v190, v190 op_sel_hi:[0,0,0]
	v_mfma_scale_f32_16x16x128_f8f6f4 v[64:67], v[24:31], v[202:209], v[64:67], v190, v190 op_sel_hi:[0,0,0]
	v_mfma_scale_f32_16x16x128_f8f6f4 v[52:55], v[16:23], v[210:217], v[52:55], v190, v190 op_sel_hi:[0,0,0]
	v_mfma_scale_f32_16x16x128_f8f6f4 v[48:51], v[24:31], v[210:217], v[48:51], v190, v190 op_sel_hi:[0,0,0]
	v_mfma_scale_f32_16x16x128_f8f6f4 v[36:39], v[16:23], v[218:225], v[36:39], v190, v190 op_sel_hi:[0,0,0]
	v_mfma_scale_f32_16x16x128_f8f6f4 v[32:35], v[24:31], v[218:225], v[32:35], v190, v190 op_sel_hi:[0,0,0]
	s_setprio 0
	s_barrier
	s_add_i32 s69, s69, 2
	s_add_u32 s44, s44, 0x100
	s_addc_u32 s45, s45, 0
	s_add_u32 s67, s67, 0x100
	s_addc_u32 s68, s68, 0
	s_cmp_gt_u32 s69, 13
	s_cbranch_scc0 .LBB0_3686

; #define PG8_STAGE(bufoff, gbase, voff) do { _Pragma("unroll") for (int _i = 0; _i < 2; ++_i) \
;         __builtin_amdgcn_global_load_lds((const unsigned*)((const char*)(gbase) + (voff)[_i]), (LAS unsigned*)(lds + (bufoff) + ldsw + _i * 8192), 16, 0, 0); } while (0)
; #define PG8_LDA(dst, b, h) do { _Pragma("unroll") for (int m = 0; m < 4; ++m) _Pragma("unroll") for (int k = 0; k < 2; ++k) dst[m][k] = *(const LAS bf16x8*)(lds + PG8_SA(b, h) + aoff + m * 2048 + k * 1024); } while (0)
; #define PG8_LDB(dst, b, h) do { _Pragma("unroll") for (int n = 0; n < 2; ++n) _Pragma("unroll") for (int k = 0; k < 2; ++k) dst[n][k] = *(const LAS bf16x8*)(lds + PG8_SB(b, h) + boff + n * 2048 + k * 1024); } while (0)
; #define PG8_SCHED __builtin_amdgcn_sched_barrier(0)
;     __device__ __forceinline__ bool next(int i, Unit& u) const {
;         const long L = (long)i * G + c; if (L >= nwg) return false;
;         int wgid = (int)L; { const int q = nwg / NXCD, r = nwg % NXCD, xcd = wgid % NXCD, off = wgid / NXCD; wgid = (xcd < r ? xcd * (q + 1) : r * (q + 1) + (xcd - r) * q) + off; }
;         const int nig = WGM * nN, gid = wgid / nig, fm = gid * WGM, gsz = (nM - fm) < WGM ? (nM - fm) : WGM;
;         u.pm = fm + ((wgid % nig) % gsz); u.pn = (wgid % nig) / gsz; u.e = 0; u.kt0 = 0; u.nkt = nt; u.buf = 0;
;     ...
;     for (;;) {
;         const bool has_next = S.next(ui + 1, nxt);
;         const char* nA = has_next ? (const char*)g.A + (size_t)nxt.pm * tstep + (size_t)nxt.kt0 * kstep : cA; const char* nB = has_next ? (const char*)g.Bt + (size_t)nxt.e * g.estride + (size_t)nxt.pn * tstep + (size_t)nxt.kt0 * kstep : cB;
;         const int nt = cur.nkt;
;         for (int t = 0; t < nt; t += 2) {
;             const bool last = (t == nt - 2);
;             const char* a1 = cA + (size_t)(t + 1) * kstep;
;             const char* a2 = last ? nA : cA + (size_t)(t + 2) * kstep; const char* b2 = last ? nB : cB + (size_t)(t + 2) * kstep;
;             const char* a3 = a2 + kstep; const char* b3 = b2 + kstep;
;             PG8_LDB(B0, 0, 0); PG8_LDB(B1, 0, 1); PG8_SCHED; PG8_LDA(At, 0, 0); PG8_STAGE(PG8_SA(1, 1), a1 + hstep, voffA);
.LBB0_3847:
	ds_read_b128 v[24:27], v189
	ds_read_b128 v[28:31], v189 offset:1024
	ds_read_b128 v[16:19], v189 offset:2048
	ds_read_b128 v[20:23], v189 offset:3072
	ds_read_b128 v[8:11], v190
	ds_read_b128 v[12:15], v190 offset:1024
	ds_read_b128 v[4:7], v190 offset:3072
	ds_read_b128 v[176:179], v191
	ds_read_b128 v[180:183], v191 offset:1024
	ds_read_b128 v[196:199], v191 offset:2048
	ds_read_b128 v[200:203], v191 offset:3072
	ds_read_b128 v[204:207], v191 offset:4096
	ds_read_b128 v[208:211], v191 offset:5120
	ds_read_b128 v[212:215], v191 offset:6144
	ds_read_b128 v[216:219], v191 offset:7168
	s_add_i32 s54, s54, 1
	s_mul_i32 s4, s54, s59
	s_mul_hi_u32 s5, s54, s33
	s_add_i32 s5, s5, s4
	s_mul_i32 s4, s54, s33
	s_add_u32 s4, s4, s22
	s_addc_u32 s5, s5, s60
	v_cmp_gt_i64_e32 vcc, s[4:5], v[174:175]
	v_cmp_lt_i64_e64 s[6:7], s[4:5], v[172:173]
	s_cbranch_vccnz .LBB0_3853
	s_ashr_i32 s5, s4, 31
	s_lshr_b32 s5, s5, 29
	s_add_i32 s40, s4, s5
	s_and_b32 s5, s40, -8
	s_sub_i32 s41, s4, s5
	s_cmp_gt_i32 s41, -1
	s_mov_b64 s[4:5], -1
	s_cbranch_scc0 .LBB0_3850
	s_lshl_b32 s42, s41, 6
	s_mov_b64 s[4:5], 0

; #define PG8_STAGE(bufoff, gbase, voff) do { _Pragma("unroll") for (int _i = 0; _i < 2; ++_i) \
;         __builtin_amdgcn_global_load_lds((const unsigned*)((const char*)(gbase) + (voff)[_i]), (LAS unsigned*)(lds + (bufoff) + ldsw + _i * 8192), 16, 0, 0); } while (0)
; #define PG8_LDA(dst, b, h) do { _Pragma("unroll") for (int m = 0; m < 4; ++m) _Pragma("unroll") for (int k = 0; k < 2; ++k) dst[m][k] = *(const LAS bf16x8*)(lds + PG8_SA(b, h) + aoff + m * 2048 + k * 1024); } while (0)
; #define PG8_LDB(dst, b, h) do { _Pragma("unroll") for (int n = 0; n < 2; ++n) _Pragma("unroll") for (int k = 0; k < 2; ++k) dst[n][k] = *(const LAS bf16x8*)(lds + PG8_SB(b, h) + boff + n * 2048 + k * 1024); } while (0)
; #define PG8_WAIT_V(n) asm volatile("s_waitcnt vmcnt(" #n ")" ::: "memory")
; #define PG8_WAIT_L(n) asm volatile("s_waitcnt lgkmcnt(" #n ")" ::: "memory")
; #define PG8_BAR __builtin_amdgcn_s_barrier()
; #define PG8_SCHED __builtin_amdgcn_sched_barrier(0)
;     ...
;         const char* nA = has_next ? (const char*)g.A + (size_t)nxt.pm * tstep + (size_t)nxt.kt0 * kstep : cA; const char* nB = has_next ? (const char*)g.Bt + (size_t)nxt.e * g.estride + (size_t)nxt.pn * tstep + (size_t)nxt.kt0 * kstep : cB;
;         const int nt = cur.nkt;
;         for (int t = 0; t < nt; t += 2) {
;             const bool last = (t == nt - 2);
;             const char* a1 = cA + (size_t)(t + 1) * kstep;
;             const char* a2 = last ? nA : cA + (size_t)(t + 2) * kstep; const char* b2 = last ? nB : cB + (size_t)(t + 2) * kstep;
;             const char* a3 = a2 + kstep; const char* b3 = b2 + kstep;
;             PG8_LDB(B0, 0, 0); PG8_LDB(B1, 0, 1); PG8_SCHED; PG8_LDA(At, 0, 0); PG8_STAGE(PG8_SA(1, 1), a1 + hstep, voffA);
;             PG8_WAIT_V(8); PG8_WAIT_L(0); PG8_BAR; PG8_MMA(0, 0, At, B0); PG8_MMA(0, 1, At, B1); PG8_BAR; PG8_SCHED;
;             PG8_LDA(At, 0, 1); PG8_STAGE(PG8_SB(0, 0), b2, voffB); PG8_STAGE(PG8_SB(0, 1), b2 + hstep, voffB); PG8_STAGE(PG8_SA(0, 0), a2, voffA);
;             PG8_WAIT_V(8); PG8_WAIT_L(0); PG8_BAR; PG8_MMA(1, 0, At, B0); PG8_MMA(1, 1, At, B1); PG8_BAR; PG8_SCHED;
.LBB0_3857:
	s_add_u32 s71, s46, 0x100
	s_addc_u32 s72, s47, 0
	s_mov_b32 s73, -2
	s_waitcnt lgkmcnt(0)
	ds_read_b128 v[0:3], v190 offset:2048
	s_add_u32 s6, s44, 0x100
	s_addc_u32 s7, s45, 0
	s_cmp_eq_u32 s73, 40
	s_cselect_b32 s49, s41, s7
	s_cselect_b32 s48, s40, s6
	s_cselect_b32 s47, s43, s72
	s_cselect_b32 s46, s42, s71
	v_lshl_add_u64 v[184:185], s[44:45], 0, v[168:169]
	s_add_i32 m0, s37, 0xc000
	global_load_lds_dwordx4 v[184:185], off
	v_lshl_add_u64 v[184:185], s[44:45], 0, v[170:171]
	s_add_i32 m0, s37, 0xe000
	s_nop 0
	global_load_lds_dwordx4 v[184:185], off
	s_waitcnt vmcnt(8)
	s_waitcnt lgkmcnt(0)
	s_barrier
	s_setprio 1
	s_waitcnt lgkmcnt(0)
	v_mfma_scale_f32_16x16x128_f8f6f4 v[156:159], v[24:31], v[176:183], 0, v192, v192 op_sel_hi:[0,0,0]
	v_mfma_scale_f32_16x16x128_f8f6f4 v[152:155], v[16:23], v[176:183], 0, v192, v192 op_sel_hi:[0,0,0]
	v_mfma_scale_f32_16x16x128_f8f6f4 v[140:143], v[24:31], v[196:203], 0, v192, v192 op_sel_hi:[0,0,0]
	v_mfma_scale_f32_16x16x128_f8f6f4 v[136:139], v[16:23], v[196:203], 0, v192, v192 op_sel_hi:[0,0,0]
	v_mfma_scale_f32_16x16x128_f8f6f4 v[124:127], v[24:31], v[204:211], 0, v192, v192 op_sel_hi:[0,0,0]
	v_mfma_scale_f32_16x16x128_f8f6f4 v[120:123], v[16:23], v[204:211], 0, v192, v192 op_sel_hi:[0,0,0]
	v_mfma_scale_f32_16x16x128_f8f6f4 v[108:111], v[24:31], v[212:219], 0, v192, v192 op_sel_hi:[0,0,0]
	v_mfma_scale_f32_16x16x128_f8f6f4 v[104:107], v[16:23], v[212:219], 0, v192, v192 op_sel_hi:[0,0,0]
	s_setprio 0
	s_setprio 1
	v_mfma_scale_f32_16x16x128_f8f6f4 v[148:151], v[8:15], v[176:183], 0, v192, v192 op_sel_hi:[0,0,0]
	v_mfma_scale_f32_16x16x128_f8f6f4 v[144:147], v[0:7], v[176:183], 0, v192, v192 op_sel_hi:[0,0,0]
	v_mfma_scale_f32_16x16x128_f8f6f4 v[132:135], v[8:15], v[196:203], 0, v192, v192 op_sel_hi:[0,0,0]
	v_mfma_scale_f32_16x16x128_f8f6f4 v[128:131], v[0:7], v[196:203], 0, v192, v192 op_sel_hi:[0,0,0]
	v_mfma_scale_f32_16x16x128_f8f6f4 v[116:119], v[8:15], v[204:211], 0, v192, v192 op_sel_hi:[0,0,0]
	v_mfma_scale_f32_16x16x128_f8f6f4 v[112:115], v[0:7], v[204:211], 0, v192, v192 op_sel_hi:[0,0,0]
	v_mfma_scale_f32_16x16x128_f8f6f4 v[100:103], v[8:15], v[212:219], 0, v192, v192 op_sel_hi:[0,0,0]
	v_mfma_scale_f32_16x16x128_f8f6f4 v[96:99], v[0:7], v[212:219], 0, v192, v192 op_sel_hi:[0,0,0]
	s_setprio 0
	s_barrier
	s_add_i32 s44, s61, s35
	v_lshl_add_u64 v[176:177], s[46:47], 0, v[162:163]
	s_mov_b32 m0, s44
	ds_read_b128 v[196:199], v191 offset:16384
	ds_read_b128 v[200:203], v191 offset:17408
	ds_read_b128 v[204:207], v191 offset:18432
	ds_read_b128 v[208:211], v191 offset:19456
	ds_read_b128 v[212:215], v191 offset:20480
	ds_read_b128 v[216:219], v191 offset:21504
	ds_read_b128 v[220:223], v191 offset:22528
	ds_read_b128 v[224:227], v191 offset:23552
	global_load_lds_dwordx4 v[176:177], off
	s_add_i32 m0, s44, 0x2000
	s_add_u32 s44, s46, 0xb0000
	v_lshl_add_u64 v[178:179], s[46:47], 0, v[166:167]
	s_addc_u32 s45, s47, 0
	s_add_i32 s74, s62, s35
	global_load_lds_dwordx4 v[178:179], off
	v_lshl_add_u64 v[180:181], s[44:45], 0, v[162:163]
	s_mov_b32 m0, s74
	v_lshl_add_u64 v[182:183], s[48:49], 0, v[164:165]
	global_load_lds_dwordx4 v[180:181], off
	v_lshl_add_u64 v[180:181], s[44:45], 0, v[166:167]
	s_add_i32 m0, s74, 0x2000
	s_nop 0
	global_load_lds_dwordx4 v[180:181], off
	v_lshl_add_u64 v[180:181], s[48:49], 0, v[160:161]
	s_mov_b32 m0, s37
	s_nop 0
	global_load_lds_dwordx4 v[180:181], off
	s_mov_b32 m0, s39
	s_nop 0
	global_load_lds_dwordx4 v[182:183], off
	s_waitcnt vmcnt(8)
	s_waitcnt lgkmcnt(0)
	s_barrier
	s_setprio 1
	s_waitcnt lgkmcnt(0)
	v_mfma_scale_f32_16x16x128_f8f6f4 v[92:95], v[24:31], v[196:203], 0, v192, v192 op_sel_hi:[0,0,0]
	v_mfma_scale_f32_16x16x128_f8f6f4 v[88:91], v[16:23], v[196:203], 0, v192, v192 op_sel_hi:[0,0,0]
	v_mfma_scale_f32_16x16x128_f8f6f4 v[76:79], v[24:31], v[204:211], 0, v192, v192 op_sel_hi:[0,0,0]
	v_mfma_scale_f32_16x16x128_f8f6f4 v[72:75], v[16:23], v[204:211], 0, v192, v192 op_sel_hi:[0,0,0]
	v_mfma_scale_f32_16x16x128_f8f6f4 v[60:63], v[24:31], v[212:219], 0, v192, v192 op_sel_hi:[0,0,0]
	v_mfma_scale_f32_16x16x128_f8f6f4 v[56:59], v[16:23], v[212:219], 0, v192, v192 op_sel_hi:[0,0,0]
	v_mfma_scale_f32_16x16x128_f8f6f4 v[44:47], v[24:31], v[220:227], 0, v192, v192 op_sel_hi:[0,0,0]
	v_mfma_scale_f32_16x16x128_f8f6f4 v[40:43], v[16:23], v[220:227], 0, v192, v192 op_sel_hi:[0,0,0]
	s_setprio 0
	s_setprio 1
	v_mfma_scale_f32_16x16x128_f8f6f4 v[84:87], v[8:15], v[196:203], 0, v192, v192 op_sel_hi:[0,0,0]
	v_mfma_scale_f32_16x16x128_f8f6f4 v[80:83], v[0:7], v[196:203], 0, v192, v192 op_sel_hi:[0,0,0]
	v_mfma_scale_f32_16x16x128_f8f6f4 v[68:71], v[8:15], v[204:211], 0, v192, v192 op_sel_hi:[0,0,0]
	v_mfma_scale_f32_16x16x128_f8f6f4 v[64:67], v[0:7], v[204:211], 0, v192, v192 op_sel_hi:[0,0,0]
	v_mfma_scale_f32_16x16x128_f8f6f4 v[52:55], v[8:15], v[212:219], 0, v192, v192 op_sel_hi:[0,0,0]
	v_mfma_scale_f32_16x16x128_f8f6f4 v[48:51], v[0:7], v[212:219], 0, v192, v192 op_sel_hi:[0,0,0]
	v_mfma_scale_f32_16x16x128_f8f6f4 v[36:39], v[8:15], v[220:227], 0, v192, v192 op_sel_hi:[0,0,0]
	v_mfma_scale_f32_16x16x128_f8f6f4 v[32:35], v[0:7], v[220:227], 0, v192, v192 op_sel_hi:[0,0,0]
	s_setprio 0
	s_barrier
; #define PG8_STAGE(bufoff, gbase, voff) do { _Pragma("unroll") for (int _i = 0; _i < 2; ++_i) \
;         __builtin_amdgcn_global_load_lds((const unsigned*)((const char*)(gbase) + (voff)[_i]), (LAS unsigned*)(lds + (bufoff) + ldsw + _i * 8192), 16, 0, 0); } while (0)
; #define PG8_LDA(dst, b, h) do { _Pragma("unroll") for (int m = 0; m < 4; ++m) _Pragma("unroll") for (int k = 0; k < 2; ++k) dst[m][k] = *(const LAS bf16x8*)(lds + PG8_SA(b, h) + aoff + m * 2048 + k * 1024); } while (0)
; #define PG8_LDB(dst, b, h) do { _Pragma("unroll") for (int n = 0; n < 2; ++n) _Pragma("unroll") for (int k = 0; k < 2; ++k) dst[n][k] = *(const LAS bf16x8*)(lds + PG8_SB(b, h) + boff + n * 2048 + k * 1024); } while (0)
; #define PG8_WAIT_V(n) asm volatile("s_waitcnt vmcnt(" #n ")" ::: "memory")
; #define PG8_WAIT_L(n) asm volatile("s_waitcnt lgkmcnt(" #n ")" ::: "memory")
; #define PG8_BAR __builtin_amdgcn_s_barrier()
; #define PG8_SCHED __builtin_amdgcn_sched_barrier(0)
;     ...
;             PG8_LDB(B0, 1, 0); PG8_LDB(B1, 1, 1); PG8_SCHED; PG8_LDA(At, 1, 0); PG8_STAGE(PG8_SA(0, 1), a2 + hstep, voffA);
;             PG8_WAIT_V(8); PG8_WAIT_L(0); PG8_BAR; PG8_MMA(0, 0, At, B0); PG8_MMA(0, 1, At, B1); PG8_BAR; PG8_SCHED;
;             PG8_LDA(At, 1, 1); PG8_STAGE(PG8_SB(1, 0), b3, voffB); PG8_STAGE(PG8_SB(1, 1), b3 + hstep, voffB); PG8_STAGE(PG8_SA(1, 0), a3, voffA);
;             PG8_WAIT_V(8); PG8_WAIT_L(0); PG8_BAR; PG8_MMA(1, 0, At, B0); PG8_MMA(1, 1, At, B1); PG8_BAR; PG8_SCHED;
;         }
	s_add_i32 s74, 0, 0x18000
	s_add_i32 s75, 0, 0x1c000
	v_add_u32_e32 v12, s74, v187
	v_add_u32_e32 v28, s75, v187
	ds_read_b128 v[0:3], v12
	ds_read_b128 v[4:7], v12 offset:1024
	ds_read_b128 v[8:11], v12 offset:2048
	ds_read_b128 v[12:15], v12 offset:3072
	ds_read_b128 v[16:19], v28
	ds_read_b128 v[20:23], v28 offset:1024
	ds_read_b128 v[24:27], v28 offset:2048
	ds_read_b128 v[28:31], v28 offset:3072
	s_add_u32 s44, s48, 0xb0000
	s_addc_u32 s45, s49, 0
	s_mov_b32 m0, s50
	v_lshl_add_u64 v[184:185], s[44:45], 0, v[160:161]
	ds_read_b128 v[196:199], v191 offset:32768
	ds_read_b128 v[200:203], v191 offset:33792
	ds_read_b128 v[204:207], v191 offset:34816
	ds_read_b128 v[208:211], v191 offset:35840
	ds_read_b128 v[212:215], v191 offset:36864
	ds_read_b128 v[216:219], v191 offset:37888
	ds_read_b128 v[220:223], v191 offset:38912
	ds_read_b128 v[224:227], v191 offset:39936
	global_load_lds_dwordx4 v[184:185], off
	v_lshl_add_u64 v[184:185], s[44:45], 0, v[164:165]
	s_mov_b32 m0, s51
	s_nop 0
	global_load_lds_dwordx4 v[184:185], off
	s_waitcnt vmcnt(8)
	s_waitcnt lgkmcnt(0)
	s_barrier
	s_setprio 1
	s_waitcnt lgkmcnt(0)
	v_mfma_scale_f32_16x16x128_f8f6f4 v[156:159], v[0:7], v[196:203], v[156:159], v192, v192 op_sel_hi:[0,0,0]
	v_mfma_scale_f32_16x16x128_f8f6f4 v[152:155], v[8:15], v[196:203], v[152:155], v192, v192 op_sel_hi:[0,0,0]
	v_mfma_scale_f32_16x16x128_f8f6f4 v[140:143], v[0:7], v[204:211], v[140:143], v192, v192 op_sel_hi:[0,0,0]
	v_mfma_scale_f32_16x16x128_f8f6f4 v[136:139], v[8:15], v[204:211], v[136:139], v192, v192 op_sel_hi:[0,0,0]
	v_mfma_scale_f32_16x16x128_f8f6f4 v[124:127], v[0:7], v[212:219], v[124:127], v192, v192 op_sel_hi:[0,0,0]
	v_mfma_scale_f32_16x16x128_f8f6f4 v[120:123], v[8:15], v[212:219], v[120:123], v192, v192 op_sel_hi:[0,0,0]
	v_mfma_scale_f32_16x16x128_f8f6f4 v[108:111], v[0:7], v[220:227], v[108:111], v192, v192 op_sel_hi:[0,0,0]
	v_mfma_scale_f32_16x16x128_f8f6f4 v[104:107], v[8:15], v[220:227], v[104:107], v192, v192 op_sel_hi:[0,0,0]
	s_setprio 0
	s_setprio 1
	v_mfma_scale_f32_16x16x128_f8f6f4 v[148:151], v[16:23], v[196:203], v[148:151], v192, v192 op_sel_hi:[0,0,0]
	v_mfma_scale_f32_16x16x128_f8f6f4 v[144:147], v[24:31], v[196:203], v[144:147], v192, v192 op_sel_hi:[0,0,0]
	v_mfma_scale_f32_16x16x128_f8f6f4 v[132:135], v[16:23], v[204:211], v[132:135], v192, v192 op_sel_hi:[0,0,0]
	v_mfma_scale_f32_16x16x128_f8f6f4 v[128:131], v[24:31], v[204:211], v[128:131], v192, v192 op_sel_hi:[0,0,0]
	v_mfma_scale_f32_16x16x128_f8f6f4 v[116:119], v[16:23], v[212:219], v[116:119], v192, v192 op_sel_hi:[0,0,0]
	v_mfma_scale_f32_16x16x128_f8f6f4 v[112:115], v[24:31], v[212:219], v[112:115], v192, v192 op_sel_hi:[0,0,0]
	v_mfma_scale_f32_16x16x128_f8f6f4 v[100:103], v[16:23], v[220:227], v[100:103], v192, v192 op_sel_hi:[0,0,0]
	v_mfma_scale_f32_16x16x128_f8f6f4 v[96:99], v[24:31], v[220:227], v[96:99], v192, v192 op_sel_hi:[0,0,0]
	s_setprio 0
	s_barrier
	s_add_i32 s44, s74, s35
	v_lshl_add_u64 v[176:177], v[176:177], 0, s[24:25]
	s_mov_b32 m0, s44
	ds_read_b128 v[196:199], v191 offset:49152
	ds_read_b128 v[200:203], v191 offset:50176
	ds_read_b128 v[204:207], v191 offset:51200
	ds_read_b128 v[208:211], v191 offset:52224
	ds_read_b128 v[212:215], v191 offset:53248
	ds_read_b128 v[216:219], v191 offset:54272
	ds_read_b128 v[220:223], v191 offset:55296
	ds_read_b128 v[224:227], v191 offset:56320
	global_load_lds_dwordx4 v[176:177], off
	s_add_i32 m0, s44, 0x2000
	s_add_u32 s44, s46, 0xb0080
	v_lshl_add_u64 v[176:177], v[178:179], 0, s[24:25]
	s_addc_u32 s45, s47, 0
	s_add_i32 s46, s75, s35
	global_load_lds_dwordx4 v[176:177], off
	v_lshl_add_u64 v[176:177], s[44:45], 0, v[162:163]
	s_mov_b32 m0, s46
	s_nop 0
	global_load_lds_dwordx4 v[176:177], off
	v_lshl_add_u64 v[176:177], s[44:45], 0, v[166:167]
	s_add_i32 m0, s46, 0x2000
	s_nop 0
	global_load_lds_dwordx4 v[176:177], off
	v_lshl_add_u64 v[176:177], v[180:181], 0, s[24:25]
	s_mov_b32 m0, s55
	s_nop 0
	global_load_lds_dwordx4 v[176:177], off
	v_lshl_add_u64 v[176:177], v[182:183], 0, s[24:25]
	s_mov_b32 m0, s58
	s_nop 0
	global_load_lds_dwordx4 v[176:177], off
	s_waitcnt vmcnt(8)
	s_waitcnt lgkmcnt(0)
	s_barrier
	s_setprio 1
	s_waitcnt lgkmcnt(0)
	v_mfma_scale_f32_16x16x128_f8f6f4 v[92:95], v[0:7], v[196:203], v[92:95], v192, v192 op_sel_hi:[0,0,0]
	v_mfma_scale_f32_16x16x128_f8f6f4 v[88:91], v[8:15], v[196:203], v[88:91], v192, v192 op_sel_hi:[0,0,0]
	v_mfma_scale_f32_16x16x128_f8f6f4 v[76:79], v[0:7], v[204:211], v[76:79], v192, v192 op_sel_hi:[0,0,0]
	v_mfma_scale_f32_16x16x128_f8f6f4 v[72:75], v[8:15], v[204:211], v[72:75], v192, v192 op_sel_hi:[0,0,0]
	v_mfma_scale_f32_16x16x128_f8f6f4 v[60:63], v[0:7], v[212:219], v[60:63], v192, v192 op_sel_hi:[0,0,0]
	v_mfma_scale_f32_16x16x128_f8f6f4 v[56:59], v[8:15], v[212:219], v[56:59], v192, v192 op_sel_hi:[0,0,0]
	v_mfma_scale_f32_16x16x128_f8f6f4 v[44:47], v[0:7], v[220:227], v[44:47], v192, v192 op_sel_hi:[0,0,0]
	v_mfma_scale_f32_16x16x128_f8f6f4 v[40:43], v[8:15], v[220:227], v[40:43], v192, v192 op_sel_hi:[0,0,0]
	s_setprio 0
	s_setprio 1
	v_mfma_scale_f32_16x16x128_f8f6f4 v[84:87], v[16:23], v[196:203], v[84:87], v192, v192 op_sel_hi:[0,0,0]
	v_mfma_scale_f32_16x16x128_f8f6f4 v[80:83], v[24:31], v[196:203], v[80:83], v192, v192 op_sel_hi:[0,0,0]
	v_mfma_scale_f32_16x16x128_f8f6f4 v[68:71], v[16:23], v[204:211], v[68:71], v192, v192 op_sel_hi:[0,0,0]
	v_mfma_scale_f32_16x16x128_f8f6f4 v[64:67], v[24:31], v[204:211], v[64:67], v192, v192 op_sel_hi:[0,0,0]
	v_mfma_scale_f32_16x16x128_f8f6f4 v[52:55], v[16:23], v[212:219], v[52:55], v192, v192 op_sel_hi:[0,0,0]
	v_mfma_scale_f32_16x16x128_f8f6f4 v[48:51], v[24:31], v[212:219], v[48:51], v192, v192 op_sel_hi:[0,0,0]
	v_mfma_scale_f32_16x16x128_f8f6f4 v[36:39], v[16:23], v[220:227], v[36:39], v192, v192 op_sel_hi:[0,0,0]
	v_mfma_scale_f32_16x16x128_f8f6f4 v[32:35], v[24:31], v[220:227], v[32:35], v192, v192 op_sel_hi:[0,0,0]
	s_setprio 0
	s_barrier
	s_add_i32 s73, s73, 2
	s_add_u32 s71, s71, 0x100
	s_addc_u32 s72, s72, 0
	s_cmp_gt_u32 s73, 41
	s_mov_b64 s[44:45], s[6:7]
	s_cbranch_scc0 .LBB0_3858

; #define PG8_STAGE(bufoff, gbase, voff) do { _Pragma("unroll") for (int _i = 0; _i < 2; ++_i) \
;         __builtin_amdgcn_global_load_lds((const unsigned*)((const char*)(gbase) + (voff)[_i]), (LAS unsigned*)(lds + (bufoff) + ldsw + _i * 8192), 16, 0, 0); } while (0)
; #define PG8_LDA(dst, b, h) do { _Pragma("unroll") for (int m = 0; m < 4; ++m) _Pragma("unroll") for (int k = 0; k < 2; ++k) dst[m][k] = *(const LAS bf16x8*)(lds + PG8_SA(b, h) + aoff + m * 2048 + k * 1024); } while (0)
; #define PG8_LDB(dst, b, h) do { _Pragma("unroll") for (int n = 0; n < 2; ++n) _Pragma("unroll") for (int k = 0; k < 2; ++k) dst[n][k] = *(const LAS bf16x8*)(lds + PG8_SB(b, h) + boff + n * 2048 + k * 1024); } while (0)
; #define PG8_WAIT_V(n) asm volatile("s_waitcnt vmcnt(" #n ")" ::: "memory")
; #define PG8_WAIT_L(n) asm volatile("s_waitcnt lgkmcnt(" #n ")" ::: "memory")
;     __device__ __forceinline__ bool next(int i, Unit& u) const {
;         const long L = (long)i * G + c; if (L >= nwg) return false;
;         int wgid = (int)L; { const int q = nwg / NXCD, r = nwg % NXCD, xcd = wgid % NXCD, off = wgid / NXCD; wgid = (xcd < r ? xcd * (q + 1) : r * (q + 1) + (xcd - r) * q) + off; }
;         const int nig = WGM * nN, gid = wgid / nig, fm = gid * WGM, gsz = (nM - fm) < WGM ? (nM - fm) : WGM;
;         u.pm = fm + ((wgid % nig) % gsz); u.pn = (wgid % nig) / gsz; u.e = 0; u.kt0 = 0; u.nkt = nt; u.buf = 0;
;     ...
;     for (;;) {
;         const bool has_next = S.next(ui + 1, nxt);
;         const char* nA = has_next ? (const char*)g.A + (size_t)nxt.pm * tstep + (size_t)nxt.kt0 * kstep : cA; const char* nB = has_next ? (const char*)g.Bt + (size_t)nxt.e * g.estride + (size_t)nxt.pn * tstep + (size_t)nxt.kt0 * kstep : cB;
;         const int nt = cur.nkt;
;         for (int t = 0; t < nt; t += 2) {
;             const bool last = (t == nt - 2);
;             const char* a1 = cA + (size_t)(t + 1) * kstep;
;             const char* a2 = last ? nA : cA + (size_t)(t + 2) * kstep; const char* b2 = last ? nB : cB + (size_t)(t + 2) * kstep;
;             const char* a3 = a2 + kstep; const char* b3 = b2 + kstep;
;             PG8_LDB(B0, 0, 0); PG8_LDB(B1, 0, 1); PG8_SCHED; PG8_LDA(At, 0, 0); PG8_STAGE(PG8_SA(1, 1), a1 + hstep, voffA);
;             PG8_WAIT_V(8); PG8_WAIT_L(0); PG8_BAR; PG8_MMA(0, 0, At, B0); PG8_MMA(0, 1, At, B1); PG8_BAR; PG8_SCHED;
.LBB0_4051:
	v_add_u32_e32 v136, s78, v160
	ds_read_b128 v[152:155], v136
	ds_read_b128 v[156:159], v136 offset:1024
	ds_read_b128 v[164:167], v136 offset:2048
	ds_read_b128 v[168:171], v136 offset:3072
	v_add_u32_e32 v136, s79, v160
	ds_read_b128 v[172:175], v136
	ds_read_b128 v[176:179], v136 offset:1024
	ds_read_b128 v[180:183], v136 offset:2048
	ds_read_b128 v[184:187], v136 offset:3072
	ds_read_b128 v[188:191], v161
	ds_read_b128 v[192:195], v161 offset:1024
	ds_read_b128 v[196:199], v161 offset:2048
	ds_read_b128 v[200:203], v161 offset:3072
	ds_read_b128 v[204:207], v161 offset:4096
	ds_read_b128 v[208:211], v161 offset:5120
	ds_read_b128 v[212:215], v161 offset:6144
	ds_read_b128 v[216:219], v161 offset:7168
	s_add_i32 s70, s70, 1
	s_mul_i32 s2, s70, s75
	s_mul_hi_u32 s3, s70, s71
	s_add_i32 s3, s3, s2
	s_mul_i32 s2, s70, s71
	s_add_u32 s36, s2, s27
	s_addc_u32 s37, s3, s76
	v_cmp_gt_i64_e32 vcc, s[36:37], v[150:151]
	v_cmp_lt_i64_e64 s[2:3], s[36:37], v[148:149]
	s_cbranch_vccnz .LBB0_4053
	s_ashr_i32 s5, s36, 31
	s_lshr_b32 s5, s5, 29
	s_add_i32 s5, s36, s5
	s_ashr_i32 s28, s5, 3
	s_and_b32 s5, s5, -8
	s_sub_i32 s5, s36, s5
	s_cmp_lt_i32 s5, 0
	s_cselect_b32 s29, s77, 0x60
	s_mul_i32 s5, s5, s29
	s_add_i32 s5, s5, s28
	s_mul_hi_i32 s28, s5, 0x2aaaaaab
	s_lshr_b32 s29, s28, 31
	s_ashr_i32 s28, s28, 4
	s_add_i32 s28, s28, s29
	s_lshl_b32 s29, s28, 3
	s_sub_i32 s30, 64, s29
	s_min_i32 s30, s30, 8
	s_abs_i32 s31, s30
	v_cvt_f32_u32_e32 v0, s31
	s_sub_i32 s37, 0, s31
	s_mulk_i32 s28, 0x60
	s_sub_i32 s5, s5, s28
	v_rcp_iflag_f32_e32 v0, v0
	s_abs_i32 s28, s5
	s_xor_b32 s36, s5, s30
	s_ashr_i32 s36, s36, 31
	v_mul_f32_e32 v0, 0x4f7ffffe, v0
	v_cvt_u32_f32_e32 v0, v0
	s_nop 0
	v_readfirstlane_b32 s38, v0
	s_mul_i32 s37, s37, s38
	s_mul_hi_u32 s37, s38, s37
	s_add_i32 s38, s38, s37
	s_mul_hi_u32 s37, s28, s38
	s_mul_i32 s38, s37, s31
	s_sub_i32 s28, s28, s38
	s_add_i32 s39, s37, 1
	s_sub_i32 s38, s28, s31
	s_cmp_ge_u32 s28, s31
	s_cselect_b32 s37, s39, s37
	s_cselect_b32 s28, s38, s28
	s_add_i32 s38, s37, 1
	s_cmp_ge_u32 s28, s31
	s_cselect_b32 s28, s38, s37
	s_xor_b32 s28, s28, s36
	s_sub_i32 s28, s28, s36
	s_mul_i32 s30, s28, s30
	s_sub_i32 s5, s5, s30
	s_add_i32 s30, s29, s5
.LBB0_4053:
	s_ashr_i32 s31, s30, 31
	s_lshl_b64 s[36:37], s[30:31], 17
	s_add_u32 s36, s34, s36
	s_addc_u32 s37, s35, s37
	s_and_b64 s[38:39], s[2:3], exec
	s_cselect_b32 s5, s37, s41
	s_cselect_b32 s31, s36, s40
	s_ashr_i32 s29, s28, 31
	s_lshl_b64 s[38:39], s[28:29], 17
	s_add_u32 s38, s55, s38
	s_addc_u32 s39, s64, s39
	s_and_b64 s[44:45], s[2:3], exec
	s_cselect_b32 s29, s39, s7
	s_cselect_b32 s43, s38, s6
	s_mov_b32 s48, 0
	s_mov_b64 s[44:45], -1
	s_mov_b64 s[46:47], 0
	s_add_u32 s49, s40, s48
	s_addc_u32 s60, s41, 0
	s_add_u32 s58, s49, 0x100
	s_addc_u32 s59, s60, 0
	s_and_b64 s[50:51], s[46:47], exec
	s_cselect_b32 s51, s5, s59
	s_cselect_b32 s50, s31, s58
	s_add_u32 s48, s6, s48
	s_addc_u32 s58, s7, 0
	s_add_u32 s48, s48, 0x100
	s_addc_u32 s58, s58, 0
	s_and_b64 s[46:47], s[46:47], exec
	s_cselect_b32 s59, s29, s58
	s_cselect_b32 s58, s43, s48
	s_add_u32 s62, s49, 0x10080
	s_addc_u32 s63, s60, 0
	s_add_i32 s89, s78, s65
	s_add_i32 m0, s66, 0xc000
	s_add_i32 s92, s66, 0xe000
	s_add_i32 s86, s89, 0x2000
	s_add_u32 s60, s58, 0x10000
	s_addc_u32 s61, s59, 0
	s_add_i32 s88, s79, s65
	s_add_i32 s87, s88, 0x2000
	s_add_i32 s85, 0, 0x18000
	s_add_i32 s84, 0, 0x1c000
	s_add_u32 s48, s50, 0x10000
	s_addc_u32 s49, s51, 0
	s_add_i32 s83, s85, s65
	s_add_i32 s82, s83, 0x2000
	s_add_u32 s46, s58, 0x10080
	s_addc_u32 s47, s59, 0
	s_add_i32 s91, s84, s65
	s_add_i32 s90, s91, 0x2000
	v_lshl_add_u64 v[220:221], s[62:63], 0, v[128:129]
	global_load_lds_dwordx4 v[220:221], off
	v_lshl_add_u64 v[220:221], s[62:63], 0, v[132:133]
	s_mov_b32 m0, s92
	s_nop 0
	global_load_lds_dwordx4 v[220:221], off
	s_waitcnt vmcnt(8)
	s_waitcnt lgkmcnt(0)
	s_barrier
	s_setprio 1
	s_waitcnt lgkmcnt(0)
	v_mfma_i32_16x16x64_i8 v[124:127], v[152:155], v[188:191], 0
	v_mfma_i32_16x16x64_i8 v[120:123], v[164:167], v[188:191], 0
	v_mfma_i32_16x16x64_i8 v[108:111], v[152:155], v[196:199], 0
	v_mfma_i32_16x16x64_i8 v[104:107], v[164:167], v[196:199], 0
	v_mfma_i32_16x16x64_i8 v[92:95], v[152:155], v[204:207], 0
	v_mfma_i32_16x16x64_i8 v[88:91], v[164:167], v[204:207], 0
	v_mfma_i32_16x16x64_i8 v[76:79], v[152:155], v[212:215], 0
	v_mfma_i32_16x16x64_i8 v[72:75], v[164:167], v[212:215], 0
	v_mfma_i32_16x16x64_i8 v[124:127], v[156:159], v[192:195], v[124:127]
	v_mfma_i32_16x16x64_i8 v[120:123], v[168:171], v[192:195], v[120:123]
	v_mfma_i32_16x16x64_i8 v[108:111], v[156:159], v[200:203], v[108:111]
	v_mfma_i32_16x16x64_i8 v[104:107], v[168:171], v[200:203], v[104:107]
	v_mfma_i32_16x16x64_i8 v[92:95], v[156:159], v[208:211], v[92:95]
	v_mfma_i32_16x16x64_i8 v[88:91], v[168:171], v[208:211], v[88:91]
	v_mfma_i32_16x16x64_i8 v[76:79], v[156:159], v[216:219], v[76:79]
	v_mfma_i32_16x16x64_i8 v[72:75], v[168:171], v[216:219], v[72:75]
	s_setprio 0
	s_setprio 1
	v_mfma_i32_16x16x64_i8 v[116:119], v[172:175], v[188:191], 0
	v_mfma_i32_16x16x64_i8 v[112:115], v[180:183], v[188:191], 0
	v_mfma_i32_16x16x64_i8 v[100:103], v[172:175], v[196:199], 0
	v_mfma_i32_16x16x64_i8 v[96:99], v[180:183], v[196:199], 0
	v_mfma_i32_16x16x64_i8 v[84:87], v[172:175], v[204:207], 0
	v_mfma_i32_16x16x64_i8 v[80:83], v[180:183], v[204:207], 0
	v_mfma_i32_16x16x64_i8 v[68:71], v[172:175], v[212:215], 0
	v_mfma_i32_16x16x64_i8 v[64:67], v[180:183], v[212:215], 0
	v_mfma_i32_16x16x64_i8 v[116:119], v[176:179], v[192:195], v[116:119]
	v_mfma_i32_16x16x64_i8 v[112:115], v[184:187], v[192:195], v[112:115]
	v_mfma_i32_16x16x64_i8 v[100:103], v[176:179], v[200:203], v[100:103]
	v_mfma_i32_16x16x64_i8 v[96:99], v[184:187], v[200:203], v[96:99]
	v_mfma_i32_16x16x64_i8 v[84:87], v[176:179], v[208:211], v[84:87]
	v_mfma_i32_16x16x64_i8 v[80:83], v[184:187], v[208:211], v[80:83]
	v_mfma_i32_16x16x64_i8 v[68:71], v[176:179], v[216:219], v[68:71]
	v_mfma_i32_16x16x64_i8 v[64:67], v[184:187], v[216:219], v[64:67]
	s_setprio 0
	s_barrier
; #define PG8_STAGE(bufoff, gbase, voff) do { _Pragma("unroll") for (int _i = 0; _i < 2; ++_i) \
;         __builtin_amdgcn_global_load_lds((const unsigned*)((const char*)(gbase) + (voff)[_i]), (LAS unsigned*)(lds + (bufoff) + ldsw + _i * 8192), 16, 0, 0); } while (0)
; #define PG8_LDA(dst, b, h) do { _Pragma("unroll") for (int m = 0; m < 4; ++m) _Pragma("unroll") for (int k = 0; k < 2; ++k) dst[m][k] = *(const LAS bf16x8*)(lds + PG8_SA(b, h) + aoff + m * 2048 + k * 1024); } while (0)
; #define PG8_LDB(dst, b, h) do { _Pragma("unroll") for (int n = 0; n < 2; ++n) _Pragma("unroll") for (int k = 0; k < 2; ++k) dst[n][k] = *(const LAS bf16x8*)(lds + PG8_SB(b, h) + boff + n * 2048 + k * 1024); } while (0)
; #define PG8_WAIT_V(n) asm volatile("s_waitcnt vmcnt(" #n ")" ::: "memory")
; #define PG8_WAIT_L(n) asm volatile("s_waitcnt lgkmcnt(" #n ")" ::: "memory")
; #define PG8_BAR __builtin_amdgcn_s_barrier()
; #define PG8_SCHED __builtin_amdgcn_sched_barrier(0)
;     ...
;             PG8_LDA(At, 0, 1); PG8_STAGE(PG8_SB(0, 0), b2, voffB); PG8_STAGE(PG8_SB(0, 1), b2 + hstep, voffB); PG8_STAGE(PG8_SA(0, 0), a2, voffA);
;             PG8_WAIT_V(8); PG8_WAIT_L(0); PG8_BAR; PG8_MMA(1, 0, At, B0); PG8_MMA(1, 1, At, B1); PG8_BAR; PG8_SCHED;
;             PG8_LDB(B0, 1, 0); PG8_LDB(B1, 1, 1); PG8_SCHED; PG8_LDA(At, 1, 0); PG8_STAGE(PG8_SA(0, 1), a2 + hstep, voffA);
;             PG8_WAIT_V(8); PG8_WAIT_L(0); PG8_BAR; PG8_MMA(0, 0, At, B0); PG8_MMA(0, 1, At, B1); PG8_BAR; PG8_SCHED;
	s_mov_b32 m0, s89
	v_lshl_add_u64 v[220:221], s[58:59], 0, v[130:131]
	ds_read_b128 v[188:191], v161 offset:16384
	ds_read_b128 v[192:195], v161 offset:17408
	ds_read_b128 v[196:199], v161 offset:18432
	ds_read_b128 v[200:203], v161 offset:19456
	ds_read_b128 v[204:207], v161 offset:20480
	ds_read_b128 v[208:211], v161 offset:21504
	ds_read_b128 v[212:215], v161 offset:22528
	ds_read_b128 v[216:219], v161 offset:23552
	global_load_lds_dwordx4 v[220:221], off
	v_lshl_add_u64 v[222:223], s[58:59], 0, v[134:135]
	s_mov_b32 m0, s86
	v_lshl_add_u64 v[224:225], s[60:61], 0, v[130:131]
	global_load_lds_dwordx4 v[222:223], off
	s_mov_b32 m0, s88
	v_lshl_add_u64 v[226:227], s[50:51], 0, v[132:133]
	global_load_lds_dwordx4 v[224:225], off
	v_lshl_add_u64 v[224:225], s[60:61], 0, v[134:135]
	s_mov_b32 m0, s87
	s_nop 0
	global_load_lds_dwordx4 v[224:225], off
	v_lshl_add_u64 v[224:225], s[50:51], 0, v[128:129]
	s_mov_b32 m0, s66
	s_nop 0
	global_load_lds_dwordx4 v[224:225], off
	s_mov_b32 m0, s67
	s_nop 0
	global_load_lds_dwordx4 v[226:227], off
	s_waitcnt vmcnt(8)
	s_waitcnt lgkmcnt(0)
	s_barrier
	s_setprio 1
	s_waitcnt lgkmcnt(0)
	v_mfma_i32_16x16x64_i8 v[60:63], v[152:155], v[188:191], 0
	v_mfma_i32_16x16x64_i8 v[56:59], v[164:167], v[188:191], 0
	v_mfma_i32_16x16x64_i8 v[44:47], v[152:155], v[196:199], 0
	v_mfma_i32_16x16x64_i8 v[40:43], v[164:167], v[196:199], 0
	v_mfma_i32_16x16x64_i8 v[28:31], v[152:155], v[204:207], 0
	v_mfma_i32_16x16x64_i8 v[24:27], v[164:167], v[204:207], 0
	v_mfma_i32_16x16x64_i8 v[12:15], v[152:155], v[212:215], 0
	v_mfma_i32_16x16x64_i8 v[8:11], v[164:167], v[212:215], 0
	v_mfma_i32_16x16x64_i8 v[60:63], v[156:159], v[192:195], v[60:63]
	v_mfma_i32_16x16x64_i8 v[56:59], v[168:171], v[192:195], v[56:59]
	v_mfma_i32_16x16x64_i8 v[44:47], v[156:159], v[200:203], v[44:47]
	v_mfma_i32_16x16x64_i8 v[40:43], v[168:171], v[200:203], v[40:43]
	v_mfma_i32_16x16x64_i8 v[28:31], v[156:159], v[208:211], v[28:31]
	v_mfma_i32_16x16x64_i8 v[24:27], v[168:171], v[208:211], v[24:27]
	v_mfma_i32_16x16x64_i8 v[12:15], v[156:159], v[216:219], v[12:15]
	v_mfma_i32_16x16x64_i8 v[8:11], v[168:171], v[216:219], v[8:11]
	s_setprio 0
	s_setprio 1
	v_mfma_i32_16x16x64_i8 v[52:55], v[172:175], v[188:191], 0
	v_mfma_i32_16x16x64_i8 v[48:51], v[180:183], v[188:191], 0
	v_mfma_i32_16x16x64_i8 v[36:39], v[172:175], v[196:199], 0
	v_mfma_i32_16x16x64_i8 v[32:35], v[180:183], v[196:199], 0
	v_mfma_i32_16x16x64_i8 v[20:23], v[172:175], v[204:207], 0
	v_mfma_i32_16x16x64_i8 v[16:19], v[180:183], v[204:207], 0
	v_mfma_i32_16x16x64_i8 v[4:7], v[172:175], v[212:215], 0
	v_mfma_i32_16x16x64_i8 v[0:3], v[180:183], v[212:215], 0
	v_mfma_i32_16x16x64_i8 v[52:55], v[176:179], v[192:195], v[52:55]
	v_mfma_i32_16x16x64_i8 v[48:51], v[184:187], v[192:195], v[48:51]
	v_mfma_i32_16x16x64_i8 v[36:39], v[176:179], v[200:203], v[36:39]
	v_mfma_i32_16x16x64_i8 v[32:35], v[184:187], v[200:203], v[32:35]
	v_mfma_i32_16x16x64_i8 v[20:23], v[176:179], v[208:211], v[20:23]
	v_mfma_i32_16x16x64_i8 v[16:19], v[184:187], v[208:211], v[16:19]
	v_mfma_i32_16x16x64_i8 v[4:7], v[176:179], v[216:219], v[4:7]
	v_mfma_i32_16x16x64_i8 v[0:3], v[184:187], v[216:219], v[0:3]
	s_setprio 0
	s_barrier
	v_add_u32_e32 v136, s85, v160
	ds_read_b128 v[152:155], v136
	ds_read_b128 v[156:159], v136 offset:1024
	ds_read_b128 v[164:167], v136 offset:2048
	ds_read_b128 v[168:171], v136 offset:3072
	v_add_u32_e32 v136, s84, v160
	ds_read_b128 v[172:175], v136
	ds_read_b128 v[176:179], v136 offset:1024
	ds_read_b128 v[180:183], v136 offset:2048
	ds_read_b128 v[184:187], v136 offset:3072
	s_mov_b32 m0, s68
	v_lshl_add_u64 v[228:229], s[48:49], 0, v[128:129]
	ds_read_b128 v[188:191], v161 offset:32768
	ds_read_b128 v[192:195], v161 offset:33792
	ds_read_b128 v[196:199], v161 offset:34816
	ds_read_b128 v[200:203], v161 offset:35840
	ds_read_b128 v[204:207], v161 offset:36864
	ds_read_b128 v[208:211], v161 offset:37888
	ds_read_b128 v[212:215], v161 offset:38912
	ds_read_b128 v[216:219], v161 offset:39936
	global_load_lds_dwordx4 v[228:229], off
	v_lshl_add_u64 v[228:229], s[48:49], 0, v[132:133]
	s_mov_b32 m0, s69
	s_nop 0
	global_load_lds_dwordx4 v[228:229], off
	s_waitcnt vmcnt(8)
	s_waitcnt lgkmcnt(0)
	s_barrier
; #define PG8_STAGE(bufoff, gbase, voff) do { _Pragma("unroll") for (int _i = 0; _i < 2; ++_i) \
;         __builtin_amdgcn_global_load_lds((const unsigned*)((const char*)(gbase) + (voff)[_i]), (LAS unsigned*)(lds + (bufoff) + ldsw + _i * 8192), 16, 0, 0); } while (0)
; #define PG8_LDA(dst, b, h) do { _Pragma("unroll") for (int m = 0; m < 4; ++m) _Pragma("unroll") for (int k = 0; k < 2; ++k) dst[m][k] = *(const LAS bf16x8*)(lds + PG8_SA(b, h) + aoff + m * 2048 + k * 1024); } while (0)
; #define PG8_WAIT_V(n) asm volatile("s_waitcnt vmcnt(" #n ")" ::: "memory")
; #define PG8_WAIT_L(n) asm volatile("s_waitcnt lgkmcnt(" #n ")" ::: "memory")
; #define PG8_BAR __builtin_amdgcn_s_barrier()
; #define PG8_SCHED __builtin_amdgcn_sched_barrier(0)
;     ...
;             PG8_WAIT_V(8); PG8_WAIT_L(0); PG8_BAR; PG8_MMA(0, 0, At, B0); PG8_MMA(0, 1, At, B1); PG8_BAR; PG8_SCHED;
;             PG8_LDA(At, 1, 1); PG8_STAGE(PG8_SB(1, 0), b3, voffB); PG8_STAGE(PG8_SB(1, 1), b3 + hstep, voffB); PG8_STAGE(PG8_SA(1, 0), a3, voffA);
;             PG8_WAIT_V(8); PG8_WAIT_L(0); PG8_BAR; PG8_MMA(1, 0, At, B0); PG8_MMA(1, 1, At, B1); PG8_BAR; PG8_SCHED;
;         }
	s_setprio 1
	s_waitcnt lgkmcnt(0)
	v_mfma_i32_16x16x64_i8 v[124:127], v[152:155], v[188:191], v[124:127]
	v_mfma_i32_16x16x64_i8 v[120:123], v[164:167], v[188:191], v[120:123]
	v_mfma_i32_16x16x64_i8 v[108:111], v[152:155], v[196:199], v[108:111]
	v_mfma_i32_16x16x64_i8 v[104:107], v[164:167], v[196:199], v[104:107]
	v_mfma_i32_16x16x64_i8 v[92:95], v[152:155], v[204:207], v[92:95]
	v_mfma_i32_16x16x64_i8 v[88:91], v[164:167], v[204:207], v[88:91]
	v_mfma_i32_16x16x64_i8 v[76:79], v[152:155], v[212:215], v[76:79]
	v_mfma_i32_16x16x64_i8 v[72:75], v[164:167], v[212:215], v[72:75]
	v_mfma_i32_16x16x64_i8 v[124:127], v[156:159], v[192:195], v[124:127]
	v_mfma_i32_16x16x64_i8 v[120:123], v[168:171], v[192:195], v[120:123]
	v_mfma_i32_16x16x64_i8 v[108:111], v[156:159], v[200:203], v[108:111]
	v_mfma_i32_16x16x64_i8 v[104:107], v[168:171], v[200:203], v[104:107]
	v_mfma_i32_16x16x64_i8 v[92:95], v[156:159], v[208:211], v[92:95]
	v_mfma_i32_16x16x64_i8 v[88:91], v[168:171], v[208:211], v[88:91]
	v_mfma_i32_16x16x64_i8 v[76:79], v[156:159], v[216:219], v[76:79]
	v_mfma_i32_16x16x64_i8 v[72:75], v[168:171], v[216:219], v[72:75]
	s_setprio 0
	s_setprio 1
	v_mfma_i32_16x16x64_i8 v[116:119], v[172:175], v[188:191], v[116:119]
	v_mfma_i32_16x16x64_i8 v[112:115], v[180:183], v[188:191], v[112:115]
	v_mfma_i32_16x16x64_i8 v[100:103], v[172:175], v[196:199], v[100:103]
	v_mfma_i32_16x16x64_i8 v[96:99], v[180:183], v[196:199], v[96:99]
	v_mfma_i32_16x16x64_i8 v[84:87], v[172:175], v[204:207], v[84:87]
	v_mfma_i32_16x16x64_i8 v[80:83], v[180:183], v[204:207], v[80:83]
	v_mfma_i32_16x16x64_i8 v[68:71], v[172:175], v[212:215], v[68:71]
	v_mfma_i32_16x16x64_i8 v[64:67], v[180:183], v[212:215], v[64:67]
	v_mfma_i32_16x16x64_i8 v[116:119], v[176:179], v[192:195], v[116:119]
	v_mfma_i32_16x16x64_i8 v[112:115], v[184:187], v[192:195], v[112:115]
	v_mfma_i32_16x16x64_i8 v[100:103], v[176:179], v[200:203], v[100:103]
	v_mfma_i32_16x16x64_i8 v[96:99], v[184:187], v[200:203], v[96:99]
	v_mfma_i32_16x16x64_i8 v[84:87], v[176:179], v[208:211], v[84:87]
	v_mfma_i32_16x16x64_i8 v[80:83], v[184:187], v[208:211], v[80:83]
	v_mfma_i32_16x16x64_i8 v[68:71], v[176:179], v[216:219], v[68:71]
	v_mfma_i32_16x16x64_i8 v[64:67], v[184:187], v[216:219], v[64:67]
	s_setprio 0
	s_barrier
	s_mov_b32 m0, s83
	v_lshl_add_u64 v[220:221], v[220:221], 0, s[14:15]
	ds_read_b128 v[188:191], v161 offset:49152
	ds_read_b128 v[192:195], v161 offset:50176
	ds_read_b128 v[196:199], v161 offset:51200
	ds_read_b128 v[200:203], v161 offset:52224
	ds_read_b128 v[204:207], v161 offset:53248
	ds_read_b128 v[208:211], v161 offset:54272
	ds_read_b128 v[212:215], v161 offset:55296
	ds_read_b128 v[216:219], v161 offset:56320
	global_load_lds_dwordx4 v[220:221], off
	v_lshl_add_u64 v[220:221], v[222:223], 0, s[14:15]
	s_mov_b32 m0, s82
	s_nop 0
	global_load_lds_dwordx4 v[220:221], off
	v_lshl_add_u64 v[220:221], s[46:47], 0, v[130:131]
	s_mov_b32 m0, s91
	s_nop 0
	global_load_lds_dwordx4 v[220:221], off
	v_lshl_add_u64 v[220:221], s[46:47], 0, v[134:135]
	s_mov_b32 m0, s90
	s_nop 0
	global_load_lds_dwordx4 v[220:221], off
	v_lshl_add_u64 v[220:221], v[224:225], 0, s[14:15]
	s_mov_b32 m0, s72
	s_nop 0
	global_load_lds_dwordx4 v[220:221], off
	v_lshl_add_u64 v[220:221], v[226:227], 0, s[14:15]
	s_mov_b32 m0, s73
	s_nop 0
	global_load_lds_dwordx4 v[220:221], off
	s_waitcnt vmcnt(8)
	s_waitcnt lgkmcnt(0)
	s_barrier
	s_setprio 1
	s_waitcnt lgkmcnt(0)
	v_mfma_i32_16x16x64_i8 v[60:63], v[152:155], v[188:191], v[60:63]
	v_mfma_i32_16x16x64_i8 v[56:59], v[164:167], v[188:191], v[56:59]
	v_mfma_i32_16x16x64_i8 v[44:47], v[152:155], v[196:199], v[44:47]
	v_mfma_i32_16x16x64_i8 v[40:43], v[164:167], v[196:199], v[40:43]
	v_mfma_i32_16x16x64_i8 v[28:31], v[152:155], v[204:207], v[28:31]
	v_mfma_i32_16x16x64_i8 v[24:27], v[164:167], v[204:207], v[24:27]
	v_mfma_i32_16x16x64_i8 v[12:15], v[152:155], v[212:215], v[12:15]
	v_mfma_i32_16x16x64_i8 v[8:11], v[164:167], v[212:215], v[8:11]
	v_mfma_i32_16x16x64_i8 v[60:63], v[156:159], v[192:195], v[60:63]
	v_mfma_i32_16x16x64_i8 v[56:59], v[168:171], v[192:195], v[56:59]
	v_mfma_i32_16x16x64_i8 v[44:47], v[156:159], v[200:203], v[44:47]
	v_mfma_i32_16x16x64_i8 v[40:43], v[168:171], v[200:203], v[40:43]
	v_mfma_i32_16x16x64_i8 v[28:31], v[156:159], v[208:211], v[28:31]
	v_mfma_i32_16x16x64_i8 v[24:27], v[168:171], v[208:211], v[24:27]
	v_mfma_i32_16x16x64_i8 v[12:15], v[156:159], v[216:219], v[12:15]
	v_mfma_i32_16x16x64_i8 v[8:11], v[168:171], v[216:219], v[8:11]
	s_setprio 0
	s_setprio 1
	v_mfma_i32_16x16x64_i8 v[52:55], v[172:175], v[188:191], v[52:55]
	v_mfma_i32_16x16x64_i8 v[48:51], v[180:183], v[188:191], v[48:51]
	v_mfma_i32_16x16x64_i8 v[36:39], v[172:175], v[196:199], v[36:39]
	v_mfma_i32_16x16x64_i8 v[32:35], v[180:183], v[196:199], v[32:35]
	v_mfma_i32_16x16x64_i8 v[20:23], v[172:175], v[204:207], v[20:23]
	v_mfma_i32_16x16x64_i8 v[16:19], v[180:183], v[204:207], v[16:19]
	v_mfma_i32_16x16x64_i8 v[4:7], v[172:175], v[212:215], v[4:7]
	v_mfma_i32_16x16x64_i8 v[0:3], v[180:183], v[212:215], v[0:3]
	v_mfma_i32_16x16x64_i8 v[52:55], v[176:179], v[192:195], v[52:55]
	v_mfma_i32_16x16x64_i8 v[48:51], v[184:187], v[192:195], v[48:51]
	v_mfma_i32_16x16x64_i8 v[36:39], v[176:179], v[200:203], v[36:39]
	v_mfma_i32_16x16x64_i8 v[32:35], v[184:187], v[200:203], v[32:35]
	v_mfma_i32_16x16x64_i8 v[20:23], v[176:179], v[208:211], v[20:23]
	v_mfma_i32_16x16x64_i8 v[16:19], v[184:187], v[208:211], v[16:19]
	v_mfma_i32_16x16x64_i8 v[4:7], v[176:179], v[216:219], v[4:7]
	v_mfma_i32_16x16x64_i8 v[0:3], v[184:187], v[216:219], v[0:3]
	s_setprio 0
	s_barrier
	s_movk_i32 s48, 0x100
	s_andn2_b64 vcc, exec, s[44:45]
	s_mov_b64 s[46:47], -1
	s_mov_b64 s[44:45], 0
	s_cbranch_vccz .LBB0_4054

; #define PG8_STAGE(bufoff, gbase, voff) do { _Pragma("unroll") for (int _i = 0; _i < 2; ++_i) \
;         __builtin_amdgcn_global_load_lds((const unsigned*)((const char*)(gbase) + (voff)[_i]), (LAS unsigned*)(lds + (bufoff) + ldsw + _i * 8192), 16, 0, 0); } while (0)
; #define PG8_LDA(dst, b, h) do { _Pragma("unroll") for (int m = 0; m < 4; ++m) _Pragma("unroll") for (int k = 0; k < 2; ++k) dst[m][k] = *(const LAS bf16x8*)(lds + PG8_SA(b, h) + aoff + m * 2048 + k * 1024); } while (0)
; #define PG8_LDB(dst, b, h) do { _Pragma("unroll") for (int n = 0; n < 2; ++n) _Pragma("unroll") for (int k = 0; k < 2; ++k) dst[n][k] = *(const LAS bf16x8*)(lds + PG8_SB(b, h) + boff + n * 2048 + k * 1024); } while (0)
; #define PG8_SCHED __builtin_amdgcn_sched_barrier(0)
;     __device__ __forceinline__ bool next(int i, Unit& u) const {
;         const long L = (long)i * G + c; if (L >= nwg) return false;
;         int wgid = (int)L; { const int q = nwg / NXCD, r = nwg % NXCD, xcd = wgid % NXCD, off = wgid / NXCD; wgid = (xcd < r ? xcd * (q + 1) : r * (q + 1) + (xcd - r) * q) + off; }
;         const int nig = WGM * nN, gid = wgid / nig, fm = gid * WGM, gsz = (nM - fm) < WGM ? (nM - fm) : WGM;
;         u.pm = fm + ((wgid % nig) % gsz); u.pn = (wgid % nig) / gsz; u.e = 0; u.kt0 = 0; u.nkt = nt; u.buf = 0;
;     ...
;     for (;;) {
;         const bool has_next = S.next(ui + 1, nxt);
;         const char* nA = has_next ? (const char*)g.A + (size_t)nxt.pm * tstep + (size_t)nxt.kt0 * kstep : cA; const char* nB = has_next ? (const char*)g.Bt + (size_t)nxt.e * g.estride + (size_t)nxt.pn * tstep + (size_t)nxt.kt0 * kstep : cB;
;         const int nt = cur.nkt;
;         for (int t = 0; t < nt; t += 2) {
;             const bool last = (t == nt - 2);
;             const char* a1 = cA + (size_t)(t + 1) * kstep;
;             const char* a2 = last ? nA : cA + (size_t)(t + 2) * kstep; const char* b2 = last ? nB : cB + (size_t)(t + 2) * kstep;
;             const char* a3 = a2 + kstep; const char* b3 = b2 + kstep;
;             PG8_LDB(B0, 0, 0); PG8_LDB(B1, 0, 1); PG8_SCHED; PG8_LDA(At, 0, 0); PG8_STAGE(PG8_SA(1, 1), a1 + hstep, voffA);
.LBB0_4131:
	v_add_u32_e32 v144, s71, v147
	ds_read_b128 v[154:157], v144
	ds_read_b128 v[158:161], v144 offset:1024
	ds_read_b128 v[162:165], v144 offset:2048
	ds_read_b128 v[166:169], v144 offset:3072
	v_add_u32_e32 v144, s72, v147
	ds_read_b128 v[170:173], v144
	ds_read_b128 v[174:177], v144 offset:1024
	ds_read_b128 v[178:181], v144 offset:2048
	ds_read_b128 v[182:185], v144 offset:3072
	ds_read_b128 v[186:189], v148
	ds_read_b128 v[190:193], v148 offset:1024
	ds_read_b128 v[194:197], v148 offset:2048
	ds_read_b128 v[198:201], v148 offset:3072
	ds_read_b128 v[202:205], v148 offset:4096
	ds_read_b128 v[206:209], v148 offset:5120
	ds_read_b128 v[210:213], v148 offset:6144
	ds_read_b128 v[214:217], v148 offset:7168
	s_add_i32 s75, s75, 1
	s_mul_i32 s2, s75, s54
	s_mul_hi_u32 s3, s75, s33
	s_add_i32 s3, s3, s2
	s_mul_i32 s2, s75, s33
	s_add_u32 s28, s2, s22
	s_addc_u32 s29, s3, s35
	v_cmp_gt_i64_e32 vcc, s[28:29], v[142:143]
	v_cmp_lt_i64_e64 s[2:3], s[28:29], v[140:141]
	s_cbranch_vccnz .LBB0_4137
	s_ashr_i32 s14, s28, 31
	s_lshr_b32 s14, s14, 29
	s_add_i32 s14, s28, s14
	s_and_b32 s24, s14, -8
	s_sub_i32 s26, s28, s24
	s_cmp_gt_i32 s26, -1
	s_mov_b64 s[24:25], -1
	s_cbranch_scc0 .LBB0_4134
	s_lshl_b32 s27, s26, 6
	s_mov_b64 s[24:25], 0

; #define PG8_STAGE(bufoff, gbase, voff) do { _Pragma("unroll") for (int _i = 0; _i < 2; ++_i) \
;         __builtin_amdgcn_global_load_lds((const unsigned*)((const char*)(gbase) + (voff)[_i]), (LAS unsigned*)(lds + (bufoff) + ldsw + _i * 8192), 16, 0, 0); } while (0)
; #define PG8_LDA(dst, b, h) do { _Pragma("unroll") for (int m = 0; m < 4; ++m) _Pragma("unroll") for (int k = 0; k < 2; ++k) dst[m][k] = *(const LAS bf16x8*)(lds + PG8_SA(b, h) + aoff + m * 2048 + k * 1024); } while (0)
; #define PG8_LDB(dst, b, h) do { _Pragma("unroll") for (int n = 0; n < 2; ++n) _Pragma("unroll") for (int k = 0; k < 2; ++k) dst[n][k] = *(const LAS bf16x8*)(lds + PG8_SB(b, h) + boff + n * 2048 + k * 1024); } while (0)
; #define PG8_WAIT_V(n) asm volatile("s_waitcnt vmcnt(" #n ")" ::: "memory")
; #define PG8_WAIT_L(n) asm volatile("s_waitcnt lgkmcnt(" #n ")" ::: "memory")
; #define PG8_BAR __builtin_amdgcn_s_barrier()
; #define PG8_SCHED __builtin_amdgcn_sched_barrier(0)
;     ...
;         const char* nA = has_next ? (const char*)g.A + (size_t)nxt.pm * tstep + (size_t)nxt.kt0 * kstep : cA; const char* nB = has_next ? (const char*)g.Bt + (size_t)nxt.e * g.estride + (size_t)nxt.pn * tstep + (size_t)nxt.kt0 * kstep : cB;
;         const int nt = cur.nkt;
;         for (int t = 0; t < nt; t += 2) {
;             const bool last = (t == nt - 2);
;             const char* a1 = cA + (size_t)(t + 1) * kstep;
;             const char* a2 = last ? nA : cA + (size_t)(t + 2) * kstep; const char* b2 = last ? nB : cB + (size_t)(t + 2) * kstep;
;             const char* a3 = a2 + kstep; const char* b3 = b2 + kstep;
;             PG8_LDB(B0, 0, 0); PG8_LDB(B1, 0, 1); PG8_SCHED; PG8_LDA(At, 0, 0); PG8_STAGE(PG8_SA(1, 1), a1 + hstep, voffA);
;             PG8_WAIT_V(8); PG8_WAIT_L(0); PG8_BAR; PG8_MMA(0, 0, At, B0); PG8_MMA(0, 1, At, B1); PG8_BAR; PG8_SCHED;
;             PG8_LDA(At, 0, 1); PG8_STAGE(PG8_SB(0, 0), b2, voffB); PG8_STAGE(PG8_SB(0, 1), b2 + hstep, voffB); PG8_STAGE(PG8_SA(0, 0), a2, voffA);
.LBB0_4137:
	s_ashr_i32 s27, s26, 31
	s_lshl_b64 s[28:29], s[26:27], 17
	s_add_u32 s28, s23, s28
	s_addc_u32 s29, s34, s29
	s_and_b64 s[30:31], s[2:3], exec
	s_cselect_b32 s14, s29, s39
	s_cselect_b32 s27, s28, s38
	s_ashr_i32 s25, s24, 31
	s_lshl_b64 s[30:31], s[24:25], 17
	s_add_u32 s30, s55, s30
	s_addc_u32 s31, s60, s31
	s_and_b64 s[40:41], s[2:3], exec
	s_cselect_b32 s25, s31, s37
	s_cselect_b32 s76, s30, s36
	s_mov_b32 s44, 0
	s_mov_b64 s[40:41], -1
	s_mov_b64 s[42:43], 0
	s_add_u32 s45, s38, s44
	s_addc_u32 s50, s39, 0
	s_add_u32 s48, s45, 0x100
	s_addc_u32 s49, s50, 0
	s_and_b64 s[46:47], s[42:43], exec
	s_cselect_b32 s47, s14, s49
	s_cselect_b32 s46, s27, s48
	s_add_u32 s44, s36, s44
	s_addc_u32 s48, s37, 0
	s_add_u32 s44, s44, 0x100
	s_addc_u32 s48, s48, 0
	s_and_b64 s[42:43], s[42:43], exec
	s_cselect_b32 s49, s25, s48
	s_cselect_b32 s48, s76, s44
	s_add_u32 s58, s45, 0x10080
	s_addc_u32 s59, s50, 0
	s_add_i32 s84, s71, s61
	s_add_i32 m0, s62, 0xc000
	s_add_i32 s87, s62, 0xe000
	s_add_i32 s81, s84, 0x2000
	s_add_u32 s50, s48, 0x10000
	s_addc_u32 s51, s49, 0
	s_add_i32 s83, s72, s61
	s_add_i32 s82, s83, 0x2000
	s_add_i32 s80, 0, 0x18000
	s_add_i32 s79, 0, 0x1c000
	s_add_u32 s44, s46, 0x10000
	s_addc_u32 s45, s47, 0
	s_add_i32 s78, s80, s61
	s_add_i32 s77, s78, 0x2000
	s_add_u32 s42, s48, 0x10080
	s_addc_u32 s43, s49, 0
	s_add_i32 s86, s79, s61
	s_add_i32 s85, s86, 0x2000
	v_lshl_add_u64 v[144:145], s[58:59], 0, v[128:129]
	global_load_lds_dwordx4 v[144:145], off
	v_lshl_add_u64 v[144:145], s[58:59], 0, v[132:133]
	s_mov_b32 m0, s87
	s_nop 0
	global_load_lds_dwordx4 v[144:145], off
	s_waitcnt vmcnt(8)
	s_waitcnt lgkmcnt(0)
	s_barrier
	s_setprio 1
	s_waitcnt lgkmcnt(0)
	v_mfma_i32_16x16x64_i8 v[124:127], v[154:157], v[186:189], 0
	v_mfma_i32_16x16x64_i8 v[120:123], v[162:165], v[186:189], 0
	v_mfma_i32_16x16x64_i8 v[108:111], v[154:157], v[194:197], 0
	v_mfma_i32_16x16x64_i8 v[104:107], v[162:165], v[194:197], 0
	v_mfma_i32_16x16x64_i8 v[92:95], v[154:157], v[202:205], 0
	v_mfma_i32_16x16x64_i8 v[88:91], v[162:165], v[202:205], 0
	v_mfma_i32_16x16x64_i8 v[76:79], v[154:157], v[210:213], 0
	v_mfma_i32_16x16x64_i8 v[72:75], v[162:165], v[210:213], 0
	v_mfma_i32_16x16x64_i8 v[124:127], v[158:161], v[190:193], v[124:127]
	v_mfma_i32_16x16x64_i8 v[120:123], v[166:169], v[190:193], v[120:123]
	v_mfma_i32_16x16x64_i8 v[108:111], v[158:161], v[198:201], v[108:111]
	v_mfma_i32_16x16x64_i8 v[104:107], v[166:169], v[198:201], v[104:107]
	v_mfma_i32_16x16x64_i8 v[92:95], v[158:161], v[206:209], v[92:95]
	v_mfma_i32_16x16x64_i8 v[88:91], v[166:169], v[206:209], v[88:91]
	v_mfma_i32_16x16x64_i8 v[76:79], v[158:161], v[214:217], v[76:79]
	v_mfma_i32_16x16x64_i8 v[72:75], v[166:169], v[214:217], v[72:75]
	s_setprio 0
	s_setprio 1
	v_mfma_i32_16x16x64_i8 v[116:119], v[170:173], v[186:189], 0
	v_mfma_i32_16x16x64_i8 v[112:115], v[178:181], v[186:189], 0
	v_mfma_i32_16x16x64_i8 v[100:103], v[170:173], v[194:197], 0
	v_mfma_i32_16x16x64_i8 v[96:99], v[178:181], v[194:197], 0
	v_mfma_i32_16x16x64_i8 v[84:87], v[170:173], v[202:205], 0
	v_mfma_i32_16x16x64_i8 v[80:83], v[178:181], v[202:205], 0
	v_mfma_i32_16x16x64_i8 v[68:71], v[170:173], v[210:213], 0
	v_mfma_i32_16x16x64_i8 v[64:67], v[178:181], v[210:213], 0
	v_mfma_i32_16x16x64_i8 v[116:119], v[174:177], v[190:193], v[116:119]
	v_mfma_i32_16x16x64_i8 v[112:115], v[182:185], v[190:193], v[112:115]
	v_mfma_i32_16x16x64_i8 v[100:103], v[174:177], v[198:201], v[100:103]
	v_mfma_i32_16x16x64_i8 v[96:99], v[182:185], v[198:201], v[96:99]
	v_mfma_i32_16x16x64_i8 v[84:87], v[174:177], v[206:209], v[84:87]
	v_mfma_i32_16x16x64_i8 v[80:83], v[182:185], v[206:209], v[80:83]
	v_mfma_i32_16x16x64_i8 v[68:71], v[174:177], v[214:217], v[68:71]
	v_mfma_i32_16x16x64_i8 v[64:67], v[182:185], v[214:217], v[64:67]
	s_setprio 0
	s_barrier
	s_mov_b32 m0, s84
	v_lshl_add_u64 v[144:145], s[48:49], 0, v[130:131]
	ds_read_b128 v[186:189], v148 offset:16384
	ds_read_b128 v[190:193], v148 offset:17408
	ds_read_b128 v[194:197], v148 offset:18432
	ds_read_b128 v[198:201], v148 offset:19456
	ds_read_b128 v[202:205], v148 offset:20480
	ds_read_b128 v[206:209], v148 offset:21504
	ds_read_b128 v[210:213], v148 offset:22528
	ds_read_b128 v[214:217], v148 offset:23552
	global_load_lds_dwordx4 v[144:145], off
	v_lshl_add_u64 v[218:219], s[48:49], 0, v[134:135]
	s_mov_b32 m0, s81
	v_lshl_add_u64 v[220:221], s[50:51], 0, v[130:131]
	global_load_lds_dwordx4 v[218:219], off
	s_mov_b32 m0, s83
	v_lshl_add_u64 v[222:223], s[46:47], 0, v[132:133]
	global_load_lds_dwordx4 v[220:221], off
	v_lshl_add_u64 v[220:221], s[50:51], 0, v[134:135]
	s_mov_b32 m0, s82
	s_nop 0
	global_load_lds_dwordx4 v[220:221], off
	v_lshl_add_u64 v[220:221], s[46:47], 0, v[128:129]
	s_mov_b32 m0, s62
	s_nop 0
	global_load_lds_dwordx4 v[220:221], off
	s_mov_b32 m0, s63
	s_nop 0
	global_load_lds_dwordx4 v[222:223], off
	s_waitcnt vmcnt(8)
	s_waitcnt lgkmcnt(0)
	s_barrier
; #define PG8_STAGE(bufoff, gbase, voff) do { _Pragma("unroll") for (int _i = 0; _i < 2; ++_i) \
;         __builtin_amdgcn_global_load_lds((const unsigned*)((const char*)(gbase) + (voff)[_i]), (LAS unsigned*)(lds + (bufoff) + ldsw + _i * 8192), 16, 0, 0); } while (0)
; #define PG8_LDA(dst, b, h) do { _Pragma("unroll") for (int m = 0; m < 4; ++m) _Pragma("unroll") for (int k = 0; k < 2; ++k) dst[m][k] = *(const LAS bf16x8*)(lds + PG8_SA(b, h) + aoff + m * 2048 + k * 1024); } while (0)
; #define PG8_LDB(dst, b, h) do { _Pragma("unroll") for (int n = 0; n < 2; ++n) _Pragma("unroll") for (int k = 0; k < 2; ++k) dst[n][k] = *(const LAS bf16x8*)(lds + PG8_SB(b, h) + boff + n * 2048 + k * 1024); } while (0)
; #define PG8_WAIT_V(n) asm volatile("s_waitcnt vmcnt(" #n ")" ::: "memory")
; #define PG8_WAIT_L(n) asm volatile("s_waitcnt lgkmcnt(" #n ")" ::: "memory")
; #define PG8_BAR __builtin_amdgcn_s_barrier()
; #define PG8_SCHED __builtin_amdgcn_sched_barrier(0)
;     ...
;             PG8_LDA(At, 0, 1); PG8_STAGE(PG8_SB(0, 0), b2, voffB); PG8_STAGE(PG8_SB(0, 1), b2 + hstep, voffB); PG8_STAGE(PG8_SA(0, 0), a2, voffA);
;             PG8_WAIT_V(8); PG8_WAIT_L(0); PG8_BAR; PG8_MMA(1, 0, At, B0); PG8_MMA(1, 1, At, B1); PG8_BAR; PG8_SCHED;
;             PG8_LDB(B0, 1, 0); PG8_LDB(B1, 1, 1); PG8_SCHED; PG8_LDA(At, 1, 0); PG8_STAGE(PG8_SA(0, 1), a2 + hstep, voffA);
;             PG8_WAIT_V(8); PG8_WAIT_L(0); PG8_BAR; PG8_MMA(0, 0, At, B0); PG8_MMA(0, 1, At, B1); PG8_BAR; PG8_SCHED;
	s_setprio 1
	s_waitcnt lgkmcnt(0)
	v_mfma_i32_16x16x64_i8 v[60:63], v[154:157], v[186:189], 0
	v_mfma_i32_16x16x64_i8 v[56:59], v[162:165], v[186:189], 0
	v_mfma_i32_16x16x64_i8 v[44:47], v[154:157], v[194:197], 0
	v_mfma_i32_16x16x64_i8 v[40:43], v[162:165], v[194:197], 0
	v_mfma_i32_16x16x64_i8 v[28:31], v[154:157], v[202:205], 0
	v_mfma_i32_16x16x64_i8 v[24:27], v[162:165], v[202:205], 0
	v_mfma_i32_16x16x64_i8 v[12:15], v[154:157], v[210:213], 0
	v_mfma_i32_16x16x64_i8 v[8:11], v[162:165], v[210:213], 0
	v_mfma_i32_16x16x64_i8 v[60:63], v[158:161], v[190:193], v[60:63]
	v_mfma_i32_16x16x64_i8 v[56:59], v[166:169], v[190:193], v[56:59]
	v_mfma_i32_16x16x64_i8 v[44:47], v[158:161], v[198:201], v[44:47]
	v_mfma_i32_16x16x64_i8 v[40:43], v[166:169], v[198:201], v[40:43]
	v_mfma_i32_16x16x64_i8 v[28:31], v[158:161], v[206:209], v[28:31]
	v_mfma_i32_16x16x64_i8 v[24:27], v[166:169], v[206:209], v[24:27]
	v_mfma_i32_16x16x64_i8 v[12:15], v[158:161], v[214:217], v[12:15]
	v_mfma_i32_16x16x64_i8 v[8:11], v[166:169], v[214:217], v[8:11]
	s_setprio 0
	s_setprio 1
	v_mfma_i32_16x16x64_i8 v[52:55], v[170:173], v[186:189], 0
	v_mfma_i32_16x16x64_i8 v[48:51], v[178:181], v[186:189], 0
	v_mfma_i32_16x16x64_i8 v[36:39], v[170:173], v[194:197], 0
	v_mfma_i32_16x16x64_i8 v[32:35], v[178:181], v[194:197], 0
	v_mfma_i32_16x16x64_i8 v[20:23], v[170:173], v[202:205], 0
	v_mfma_i32_16x16x64_i8 v[16:19], v[178:181], v[202:205], 0
	v_mfma_i32_16x16x64_i8 v[4:7], v[170:173], v[210:213], 0
	v_mfma_i32_16x16x64_i8 v[0:3], v[178:181], v[210:213], 0
	v_mfma_i32_16x16x64_i8 v[52:55], v[174:177], v[190:193], v[52:55]
	v_mfma_i32_16x16x64_i8 v[48:51], v[182:185], v[190:193], v[48:51]
	v_mfma_i32_16x16x64_i8 v[36:39], v[174:177], v[198:201], v[36:39]
	v_mfma_i32_16x16x64_i8 v[32:35], v[182:185], v[198:201], v[32:35]
	v_mfma_i32_16x16x64_i8 v[20:23], v[174:177], v[206:209], v[20:23]
	v_mfma_i32_16x16x64_i8 v[16:19], v[182:185], v[206:209], v[16:19]
	v_mfma_i32_16x16x64_i8 v[4:7], v[174:177], v[214:217], v[4:7]
	v_mfma_i32_16x16x64_i8 v[0:3], v[182:185], v[214:217], v[0:3]
	s_setprio 0
	s_barrier
	v_add_u32_e32 v166, s80, v147
	v_add_u32_e32 v182, s79, v147
	ds_read_b128 v[154:157], v166
	ds_read_b128 v[158:161], v166 offset:1024
	ds_read_b128 v[162:165], v166 offset:2048
	ds_read_b128 v[166:169], v166 offset:3072
	ds_read_b128 v[170:173], v182
	ds_read_b128 v[174:177], v182 offset:1024
	ds_read_b128 v[178:181], v182 offset:2048
	ds_read_b128 v[182:185], v182 offset:3072
	s_mov_b32 m0, s64
	v_lshl_add_u64 v[224:225], s[44:45], 0, v[128:129]
	ds_read_b128 v[186:189], v148 offset:32768
	ds_read_b128 v[190:193], v148 offset:33792
	ds_read_b128 v[194:197], v148 offset:34816
	ds_read_b128 v[198:201], v148 offset:35840
	ds_read_b128 v[202:205], v148 offset:36864
	ds_read_b128 v[206:209], v148 offset:37888
	ds_read_b128 v[210:213], v148 offset:38912
	ds_read_b128 v[214:217], v148 offset:39936
	global_load_lds_dwordx4 v[224:225], off
	v_lshl_add_u64 v[224:225], s[44:45], 0, v[132:133]
	s_mov_b32 m0, s65
	s_nop 0
	global_load_lds_dwordx4 v[224:225], off
	s_waitcnt vmcnt(8)
	s_waitcnt lgkmcnt(0)
	s_barrier
	s_setprio 1
	s_waitcnt lgkmcnt(0)
	v_mfma_i32_16x16x64_i8 v[124:127], v[154:157], v[186:189], v[124:127]
	v_mfma_i32_16x16x64_i8 v[120:123], v[162:165], v[186:189], v[120:123]
	v_mfma_i32_16x16x64_i8 v[108:111], v[154:157], v[194:197], v[108:111]
	v_mfma_i32_16x16x64_i8 v[104:107], v[162:165], v[194:197], v[104:107]
	v_mfma_i32_16x16x64_i8 v[92:95], v[154:157], v[202:205], v[92:95]
	v_mfma_i32_16x16x64_i8 v[88:91], v[162:165], v[202:205], v[88:91]
	v_mfma_i32_16x16x64_i8 v[76:79], v[154:157], v[210:213], v[76:79]
	v_mfma_i32_16x16x64_i8 v[72:75], v[162:165], v[210:213], v[72:75]
	v_mfma_i32_16x16x64_i8 v[124:127], v[158:161], v[190:193], v[124:127]
	v_mfma_i32_16x16x64_i8 v[120:123], v[166:169], v[190:193], v[120:123]
	v_mfma_i32_16x16x64_i8 v[108:111], v[158:161], v[198:201], v[108:111]
	v_mfma_i32_16x16x64_i8 v[104:107], v[166:169], v[198:201], v[104:107]
	v_mfma_i32_16x16x64_i8 v[92:95], v[158:161], v[206:209], v[92:95]
	v_mfma_i32_16x16x64_i8 v[88:91], v[166:169], v[206:209], v[88:91]
	v_mfma_i32_16x16x64_i8 v[76:79], v[158:161], v[214:217], v[76:79]
	v_mfma_i32_16x16x64_i8 v[72:75], v[166:169], v[214:217], v[72:75]
	s_setprio 0
	s_setprio 1
	v_mfma_i32_16x16x64_i8 v[116:119], v[170:173], v[186:189], v[116:119]
	v_mfma_i32_16x16x64_i8 v[112:115], v[178:181], v[186:189], v[112:115]
	v_mfma_i32_16x16x64_i8 v[100:103], v[170:173], v[194:197], v[100:103]
	v_mfma_i32_16x16x64_i8 v[96:99], v[178:181], v[194:197], v[96:99]
	v_mfma_i32_16x16x64_i8 v[84:87], v[170:173], v[202:205], v[84:87]
	v_mfma_i32_16x16x64_i8 v[80:83], v[178:181], v[202:205], v[80:83]
	v_mfma_i32_16x16x64_i8 v[68:71], v[170:173], v[210:213], v[68:71]
	v_mfma_i32_16x16x64_i8 v[64:67], v[178:181], v[210:213], v[64:67]
	v_mfma_i32_16x16x64_i8 v[116:119], v[174:177], v[190:193], v[116:119]
	v_mfma_i32_16x16x64_i8 v[112:115], v[182:185], v[190:193], v[112:115]
	v_mfma_i32_16x16x64_i8 v[100:103], v[174:177], v[198:201], v[100:103]
	v_mfma_i32_16x16x64_i8 v[96:99], v[182:185], v[198:201], v[96:99]
	v_mfma_i32_16x16x64_i8 v[84:87], v[174:177], v[206:209], v[84:87]
	v_mfma_i32_16x16x64_i8 v[80:83], v[182:185], v[206:209], v[80:83]
	v_mfma_i32_16x16x64_i8 v[68:71], v[174:177], v[214:217], v[68:71]
	v_mfma_i32_16x16x64_i8 v[64:67], v[182:185], v[214:217], v[64:67]
	s_setprio 0
	s_barrier
; #define PG8_STAGE(bufoff, gbase, voff) do { _Pragma("unroll") for (int _i = 0; _i < 2; ++_i) \
;         __builtin_amdgcn_global_load_lds((const unsigned*)((const char*)(gbase) + (voff)[_i]), (LAS unsigned*)(lds + (bufoff) + ldsw + _i * 8192), 16, 0, 0); } while (0)
; #define PG8_LDA(dst, b, h) do { _Pragma("unroll") for (int m = 0; m < 4; ++m) _Pragma("unroll") for (int k = 0; k < 2; ++k) dst[m][k] = *(const LAS bf16x8*)(lds + PG8_SA(b, h) + aoff + m * 2048 + k * 1024); } while (0)
; #define PG8_WAIT_V(n) asm volatile("s_waitcnt vmcnt(" #n ")" ::: "memory")
; #define PG8_WAIT_L(n) asm volatile("s_waitcnt lgkmcnt(" #n ")" ::: "memory")
; #define PG8_BAR __builtin_amdgcn_s_barrier()
; #define PG8_SCHED __builtin_amdgcn_sched_barrier(0)
;     ...
;             PG8_LDA(At, 1, 1); PG8_STAGE(PG8_SB(1, 0), b3, voffB); PG8_STAGE(PG8_SB(1, 1), b3 + hstep, voffB); PG8_STAGE(PG8_SA(1, 0), a3, voffA);
;             PG8_WAIT_V(8); PG8_WAIT_L(0); PG8_BAR; PG8_MMA(1, 0, At, B0); PG8_MMA(1, 1, At, B1); PG8_BAR; PG8_SCHED;
	s_mov_b32 m0, s78
	v_lshl_add_u64 v[144:145], v[144:145], 0, s[18:19]
	ds_read_b128 v[186:189], v148 offset:49152
	ds_read_b128 v[190:193], v148 offset:50176
	ds_read_b128 v[194:197], v148 offset:51200
	ds_read_b128 v[198:201], v148 offset:52224
	ds_read_b128 v[202:205], v148 offset:53248
	ds_read_b128 v[206:209], v148 offset:54272
	ds_read_b128 v[210:213], v148 offset:55296
	ds_read_b128 v[214:217], v148 offset:56320
	global_load_lds_dwordx4 v[144:145], off
	v_lshl_add_u64 v[144:145], v[218:219], 0, s[18:19]
	s_mov_b32 m0, s77
	s_nop 0
	global_load_lds_dwordx4 v[144:145], off
	v_lshl_add_u64 v[144:145], s[42:43], 0, v[130:131]
	s_mov_b32 m0, s86
	s_nop 0
	global_load_lds_dwordx4 v[144:145], off
	v_lshl_add_u64 v[144:145], s[42:43], 0, v[134:135]
	s_mov_b32 m0, s85
	s_nop 0
	global_load_lds_dwordx4 v[144:145], off
	v_lshl_add_u64 v[144:145], v[220:221], 0, s[18:19]
	s_mov_b32 m0, s68
	s_nop 0
	global_load_lds_dwordx4 v[144:145], off
	v_lshl_add_u64 v[144:145], v[222:223], 0, s[18:19]
	s_mov_b32 m0, s69
	s_nop 0
	global_load_lds_dwordx4 v[144:145], off
	s_waitcnt vmcnt(8)
	s_waitcnt lgkmcnt(0)
	s_barrier
	s_setprio 1
	s_waitcnt lgkmcnt(0)
	v_mfma_i32_16x16x64_i8 v[60:63], v[154:157], v[186:189], v[60:63]
	v_mfma_i32_16x16x64_i8 v[56:59], v[162:165], v[186:189], v[56:59]
	v_mfma_i32_16x16x64_i8 v[44:47], v[154:157], v[194:197], v[44:47]
	v_mfma_i32_16x16x64_i8 v[40:43], v[162:165], v[194:197], v[40:43]
	v_mfma_i32_16x16x64_i8 v[28:31], v[154:157], v[202:205], v[28:31]
	v_mfma_i32_16x16x64_i8 v[24:27], v[162:165], v[202:205], v[24:27]
	v_mfma_i32_16x16x64_i8 v[12:15], v[154:157], v[210:213], v[12:15]
	v_mfma_i32_16x16x64_i8 v[8:11], v[162:165], v[210:213], v[8:11]
	v_mfma_i32_16x16x64_i8 v[60:63], v[158:161], v[190:193], v[60:63]
	v_mfma_i32_16x16x64_i8 v[56:59], v[166:169], v[190:193], v[56:59]
	v_mfma_i32_16x16x64_i8 v[44:47], v[158:161], v[198:201], v[44:47]
	v_mfma_i32_16x16x64_i8 v[40:43], v[166:169], v[198:201], v[40:43]
	v_mfma_i32_16x16x64_i8 v[28:31], v[158:161], v[206:209], v[28:31]
	v_mfma_i32_16x16x64_i8 v[24:27], v[166:169], v[206:209], v[24:27]
	v_mfma_i32_16x16x64_i8 v[12:15], v[158:161], v[214:217], v[12:15]
	v_mfma_i32_16x16x64_i8 v[8:11], v[166:169], v[214:217], v[8:11]
	s_setprio 0
	s_setprio 1
	v_mfma_i32_16x16x64_i8 v[52:55], v[170:173], v[186:189], v[52:55]
	v_mfma_i32_16x16x64_i8 v[48:51], v[178:181], v[186:189], v[48:51]
	v_mfma_i32_16x16x64_i8 v[36:39], v[170:173], v[194:197], v[36:39]
	v_mfma_i32_16x16x64_i8 v[32:35], v[178:181], v[194:197], v[32:35]
	v_mfma_i32_16x16x64_i8 v[20:23], v[170:173], v[202:205], v[20:23]
	v_mfma_i32_16x16x64_i8 v[16:19], v[178:181], v[202:205], v[16:19]
	v_mfma_i32_16x16x64_i8 v[4:7], v[170:173], v[210:213], v[4:7]
	v_mfma_i32_16x16x64_i8 v[0:3], v[178:181], v[210:213], v[0:3]
	v_mfma_i32_16x16x64_i8 v[52:55], v[174:177], v[190:193], v[52:55]
	v_mfma_i32_16x16x64_i8 v[48:51], v[182:185], v[190:193], v[48:51]
	v_mfma_i32_16x16x64_i8 v[36:39], v[174:177], v[198:201], v[36:39]
	v_mfma_i32_16x16x64_i8 v[32:35], v[182:185], v[198:201], v[32:35]
	v_mfma_i32_16x16x64_i8 v[20:23], v[174:177], v[206:209], v[20:23]
	v_mfma_i32_16x16x64_i8 v[16:19], v[182:185], v[206:209], v[16:19]
	v_mfma_i32_16x16x64_i8 v[4:7], v[174:177], v[214:217], v[4:7]
	v_mfma_i32_16x16x64_i8 v[0:3], v[182:185], v[214:217], v[0:3]
	s_setprio 0
	s_barrier
	s_movk_i32 s44, 0x100
	s_andn2_b64 vcc, exec, s[40:41]
	s_mov_b64 s[42:43], -1
	s_mov_b64 s[40:41], 0
	s_cbranch_vccz .LBB0_4138

; #define PG8_STAGE(bufoff, gbase, voff) do { _Pragma("unroll") for (int _i = 0; _i < 2; ++_i) \
;         __builtin_amdgcn_global_load_lds((const unsigned*)((const char*)(gbase) + (voff)[_i]), (LAS unsigned*)(lds + (bufoff) + ldsw + _i * 8192), 16, 0, 0); } while (0)
; #define PG8_LDA(dst, b, h) do { _Pragma("unroll") for (int m = 0; m < 4; ++m) _Pragma("unroll") for (int k = 0; k < 2; ++k) dst[m][k] = *(const LAS bf16x8*)(lds + PG8_SA(b, h) + aoff + m * 2048 + k * 1024); } while (0)
; #define PG8_LDB(dst, b, h) do { _Pragma("unroll") for (int n = 0; n < 2; ++n) _Pragma("unroll") for (int k = 0; k < 2; ++k) dst[n][k] = *(const LAS bf16x8*)(lds + PG8_SB(b, h) + boff + n * 2048 + k * 1024); } while (0)
; #define PG8_SCHED __builtin_amdgcn_sched_barrier(0)
;     __device__ __forceinline__ bool next(int i, Unit& u) const {
;         const long L = (long)i * G + c; if (L >= nwg) return false;
;         int wgid = (int)L; { const int q = nwg / NXCD, r = nwg % NXCD, xcd = wgid % NXCD, off = wgid / NXCD; wgid = (xcd < r ? xcd * (q + 1) : r * (q + 1) + (xcd - r) * q) + off; }
;         const int nig = WGM * nN, gid = wgid / nig, fm = gid * WGM, gsz = (nM - fm) < WGM ? (nM - fm) : WGM;
;         u.pm = fm + ((wgid % nig) % gsz); u.pn = (wgid % nig) / gsz; u.e = 0; u.kt0 = 0; u.nkt = nt; u.buf = 0;
;     ...
;             PG8_LDB(B0, 0, 0); PG8_LDB(B1, 0, 1); PG8_SCHED; PG8_LDA(At, 0, 0); PG8_STAGE(PG8_SA(1, 1), a1 + hstep, voffA);
.LBB0_4155:
	v_add_u32_e32 v142, s66, v144
	ds_read_b128 v[152:155], v142
	ds_read_b128 v[156:159], v142 offset:1024
	ds_read_b128 v[160:163], v142 offset:2048
	ds_read_b128 v[164:167], v142 offset:3072
	v_add_u32_e32 v142, s67, v144
	ds_read_b128 v[168:171], v142
	ds_read_b128 v[172:175], v142 offset:1024
	ds_read_b128 v[176:179], v142 offset:2048
	ds_read_b128 v[180:183], v142 offset:3072
	ds_read_b128 v[184:187], v147
	ds_read_b128 v[188:191], v147 offset:1024
	ds_read_b128 v[192:195], v147 offset:2048
	ds_read_b128 v[196:199], v147 offset:3072
	ds_read_b128 v[200:203], v147 offset:4096
	ds_read_b128 v[204:207], v147 offset:5120
	ds_read_b128 v[208:211], v147 offset:6144
	ds_read_b128 v[212:215], v147 offset:7168
	s_add_i32 s62, s62, 1
	s_mul_i32 s2, s62, s54
	s_mul_hi_u32 s3, s62, s33
	s_add_i32 s3, s3, s2
	s_mul_i32 s2, s62, s33
	s_add_u32 s6, s2, s22
	s_addc_u32 s7, s3, s19
	v_cmp_gt_i64_e32 vcc, s[6:7], v[140:141]
	v_cmp_lt_i64_e64 s[2:3], s[6:7], v[138:139]
	s_cbranch_vccnz .LBB0_4161
	s_ashr_i32 s7, s6, 31
	s_lshr_b32 s7, s7, 29
	s_add_i32 s24, s6, s7
	s_and_b32 s7, s24, -8
	s_sub_i32 s25, s6, s7
	s_cmp_gt_i32 s25, -1
	s_mov_b64 s[6:7], -1
	s_cbranch_scc0 .LBB0_4158
	s_lshl_b32 s26, s25, 6
	s_mov_b64 s[6:7], 0

; #define PG8_STAGE(bufoff, gbase, voff) do { _Pragma("unroll") for (int _i = 0; _i < 2; ++_i) \
;         __builtin_amdgcn_global_load_lds((const unsigned*)((const char*)(gbase) + (voff)[_i]), (LAS unsigned*)(lds + (bufoff) + ldsw + _i * 8192), 16, 0, 0); } while (0)
; #define PG8_LDA(dst, b, h) do { _Pragma("unroll") for (int m = 0; m < 4; ++m) _Pragma("unroll") for (int k = 0; k < 2; ++k) dst[m][k] = *(const LAS bf16x8*)(lds + PG8_SA(b, h) + aoff + m * 2048 + k * 1024); } while (0)
; #define PG8_LDB(dst, b, h) do { _Pragma("unroll") for (int n = 0; n < 2; ++n) _Pragma("unroll") for (int k = 0; k < 2; ++k) dst[n][k] = *(const LAS bf16x8*)(lds + PG8_SB(b, h) + boff + n * 2048 + k * 1024); } while (0)
; #define PG8_WAIT_V(n) asm volatile("s_waitcnt vmcnt(" #n ")" ::: "memory")
; #define PG8_WAIT_L(n) asm volatile("s_waitcnt lgkmcnt(" #n ")" ::: "memory")
; #define PG8_BAR __builtin_amdgcn_s_barrier()
; #define PG8_SCHED __builtin_amdgcn_sched_barrier(0)
;     ...
;         const char* nA = has_next ? (const char*)g.A + (size_t)nxt.pm * tstep + (size_t)nxt.kt0 * kstep : cA; const char* nB = has_next ? (const char*)g.Bt + (size_t)nxt.e * g.estride + (size_t)nxt.pn * tstep + (size_t)nxt.kt0 * kstep : cB;
;         const int nt = cur.nkt;
;         for (int t = 0; t < nt; t += 2) {
;             const bool last = (t == nt - 2);
;             const char* a1 = cA + (size_t)(t + 1) * kstep;
;             const char* a2 = last ? nA : cA + (size_t)(t + 2) * kstep; const char* b2 = last ? nB : cB + (size_t)(t + 2) * kstep;
;             const char* a3 = a2 + kstep; const char* b3 = b2 + kstep;
;             PG8_LDB(B0, 0, 0); PG8_LDB(B1, 0, 1); PG8_SCHED; PG8_LDA(At, 0, 0); PG8_STAGE(PG8_SA(1, 1), a1 + hstep, voffA);
;             PG8_WAIT_V(8); PG8_WAIT_L(0); PG8_BAR; PG8_MMA(0, 0, At, B0); PG8_MMA(0, 1, At, B1); PG8_BAR; PG8_SCHED;
;             PG8_LDA(At, 0, 1); PG8_STAGE(PG8_SB(0, 0), b2, voffB); PG8_STAGE(PG8_SB(0, 1), b2 + hstep, voffB); PG8_STAGE(PG8_SA(0, 0), a2, voffA);
.LBB0_4161:
	s_ashr_i32 s27, s26, 31
	s_lshl_b64 s[6:7], s[26:27], 17
	s_add_u32 s28, s23, s6
	s_addc_u32 s29, s34, s7
	s_and_b64 s[6:7], s[2:3], exec
	s_cselect_b32 s27, s29, s39
	s_cselect_b32 s70, s28, s38
	s_ashr_i32 s25, s24, 31
	s_lshl_b64 s[6:7], s[24:25], 17
	s_add_u32 s30, s21, s6
	s_addc_u32 s31, s35, s7
	s_and_b64 s[6:7], s[2:3], exec
	s_cselect_b32 s25, s31, s37
	s_cselect_b32 s71, s30, s36
	s_mov_b32 s42, 0
	s_mov_b64 s[6:7], -1
	s_mov_b64 s[40:41], 0
	s_add_u32 s43, s38, s42
	s_addc_u32 s48, s39, 0
	s_add_u32 s46, s43, 0x100
	s_addc_u32 s47, s48, 0
	s_and_b64 s[44:45], s[40:41], exec
	s_cselect_b32 s45, s27, s47
	s_cselect_b32 s44, s70, s46
	s_add_u32 s42, s36, s42
	s_addc_u32 s46, s37, 0
	s_add_u32 s42, s42, 0x100
	s_addc_u32 s46, s46, 0
	s_and_b64 s[40:41], s[40:41], exec
	s_cselect_b32 s47, s25, s46
	s_cselect_b32 s46, s71, s42
	s_add_u32 s50, s43, 0x10080
	s_addc_u32 s51, s48, 0
	s_add_i32 s79, s66, s55
	s_add_i32 m0, s58, 0xc000
	s_add_i32 s82, s58, 0xe000
	s_add_i32 s76, s79, 0x2000
	s_add_u32 s48, s46, 0x10000
	s_addc_u32 s49, s47, 0
	s_add_i32 s78, s67, s55
	s_add_i32 s77, s78, 0x2000
	s_add_i32 s75, 0, 0x18000
	s_add_i32 s74, 0, 0x1c000
	s_add_u32 s42, s44, 0x10000
	s_addc_u32 s43, s45, 0
	s_add_i32 s73, s75, s55
	s_add_i32 s72, s73, 0x2000
	s_add_u32 s40, s46, 0x10080
	s_addc_u32 s41, s47, 0
	s_add_i32 s81, s74, s55
	s_add_i32 s80, s81, 0x2000
	v_lshl_add_u64 v[142:143], s[50:51], 0, v[128:129]
	global_load_lds_dwordx4 v[142:143], off
	v_lshl_add_u64 v[142:143], s[50:51], 0, v[132:133]
	s_mov_b32 m0, s82
	s_nop 0
	global_load_lds_dwordx4 v[142:143], off
	s_waitcnt vmcnt(8)
	s_waitcnt lgkmcnt(0)
	s_barrier
	s_setprio 1
	s_waitcnt lgkmcnt(0)
	v_mfma_i32_16x16x64_i8 v[124:127], v[184:187], v[152:155], 0
	v_mfma_i32_16x16x64_i8 v[120:123], v[184:187], v[160:163], 0
	v_mfma_i32_16x16x64_i8 v[108:111], v[192:195], v[152:155], 0
	v_mfma_i32_16x16x64_i8 v[104:107], v[192:195], v[160:163], 0
	v_mfma_i32_16x16x64_i8 v[92:95], v[200:203], v[152:155], 0
	v_mfma_i32_16x16x64_i8 v[88:91], v[200:203], v[160:163], 0
	v_mfma_i32_16x16x64_i8 v[76:79], v[208:211], v[152:155], 0
	v_mfma_i32_16x16x64_i8 v[72:75], v[208:211], v[160:163], 0
	v_mfma_i32_16x16x64_i8 v[124:127], v[188:191], v[156:159], v[124:127]
	v_mfma_i32_16x16x64_i8 v[120:123], v[188:191], v[164:167], v[120:123]
	v_mfma_i32_16x16x64_i8 v[108:111], v[196:199], v[156:159], v[108:111]
	v_mfma_i32_16x16x64_i8 v[104:107], v[196:199], v[164:167], v[104:107]
	v_mfma_i32_16x16x64_i8 v[92:95], v[204:207], v[156:159], v[92:95]
	v_mfma_i32_16x16x64_i8 v[88:91], v[204:207], v[164:167], v[88:91]
	v_mfma_i32_16x16x64_i8 v[76:79], v[212:215], v[156:159], v[76:79]
	v_mfma_i32_16x16x64_i8 v[72:75], v[212:215], v[164:167], v[72:75]
	s_setprio 0
	s_setprio 1
	v_mfma_i32_16x16x64_i8 v[116:119], v[184:187], v[168:171], 0
	v_mfma_i32_16x16x64_i8 v[112:115], v[184:187], v[176:179], 0
	v_mfma_i32_16x16x64_i8 v[100:103], v[192:195], v[168:171], 0
	v_mfma_i32_16x16x64_i8 v[96:99], v[192:195], v[176:179], 0
	v_mfma_i32_16x16x64_i8 v[84:87], v[200:203], v[168:171], 0
	v_mfma_i32_16x16x64_i8 v[80:83], v[200:203], v[176:179], 0
	v_mfma_i32_16x16x64_i8 v[68:71], v[208:211], v[168:171], 0
	v_mfma_i32_16x16x64_i8 v[64:67], v[208:211], v[176:179], 0
	v_mfma_i32_16x16x64_i8 v[116:119], v[188:191], v[172:175], v[116:119]
	v_mfma_i32_16x16x64_i8 v[112:115], v[188:191], v[180:183], v[112:115]
	v_mfma_i32_16x16x64_i8 v[100:103], v[196:199], v[172:175], v[100:103]
	v_mfma_i32_16x16x64_i8 v[96:99], v[196:199], v[180:183], v[96:99]
	v_mfma_i32_16x16x64_i8 v[84:87], v[204:207], v[172:175], v[84:87]
	v_mfma_i32_16x16x64_i8 v[80:83], v[204:207], v[180:183], v[80:83]
	v_mfma_i32_16x16x64_i8 v[68:71], v[212:215], v[172:175], v[68:71]
	v_mfma_i32_16x16x64_i8 v[64:67], v[212:215], v[180:183], v[64:67]
	s_setprio 0
	s_barrier
	s_mov_b32 m0, s79
	v_lshl_add_u64 v[142:143], s[46:47], 0, v[130:131]
	ds_read_b128 v[184:187], v147 offset:16384
	ds_read_b128 v[188:191], v147 offset:17408
	ds_read_b128 v[192:195], v147 offset:18432
	ds_read_b128 v[196:199], v147 offset:19456
	ds_read_b128 v[200:203], v147 offset:20480
	ds_read_b128 v[204:207], v147 offset:21504
	ds_read_b128 v[208:211], v147 offset:22528
	ds_read_b128 v[212:215], v147 offset:23552
	global_load_lds_dwordx4 v[142:143], off
	v_lshl_add_u64 v[216:217], s[46:47], 0, v[134:135]
	s_mov_b32 m0, s76
	v_lshl_add_u64 v[218:219], s[48:49], 0, v[130:131]
	global_load_lds_dwordx4 v[216:217], off
	s_mov_b32 m0, s78
	v_lshl_add_u64 v[220:221], s[44:45], 0, v[132:133]
	global_load_lds_dwordx4 v[218:219], off
	v_lshl_add_u64 v[218:219], s[48:49], 0, v[134:135]
	s_mov_b32 m0, s77
	s_nop 0
	global_load_lds_dwordx4 v[218:219], off
	v_lshl_add_u64 v[218:219], s[44:45], 0, v[128:129]
	s_mov_b32 m0, s58
	s_nop 0
	global_load_lds_dwordx4 v[218:219], off
	s_mov_b32 m0, s59
	s_nop 0
	global_load_lds_dwordx4 v[220:221], off
	s_waitcnt vmcnt(8)
	s_waitcnt lgkmcnt(0)
	s_barrier
; #define PG8_STAGE(bufoff, gbase, voff) do { _Pragma("unroll") for (int _i = 0; _i < 2; ++_i) \
;         __builtin_amdgcn_global_load_lds((const unsigned*)((const char*)(gbase) + (voff)[_i]), (LAS unsigned*)(lds + (bufoff) + ldsw + _i * 8192), 16, 0, 0); } while (0)
; #define PG8_LDA(dst, b, h) do { _Pragma("unroll") for (int m = 0; m < 4; ++m) _Pragma("unroll") for (int k = 0; k < 2; ++k) dst[m][k] = *(const LAS bf16x8*)(lds + PG8_SA(b, h) + aoff + m * 2048 + k * 1024); } while (0)
; #define PG8_LDB(dst, b, h) do { _Pragma("unroll") for (int n = 0; n < 2; ++n) _Pragma("unroll") for (int k = 0; k < 2; ++k) dst[n][k] = *(const LAS bf16x8*)(lds + PG8_SB(b, h) + boff + n * 2048 + k * 1024); } while (0)
; #define PG8_WAIT_V(n) asm volatile("s_waitcnt vmcnt(" #n ")" ::: "memory")
; #define PG8_WAIT_L(n) asm volatile("s_waitcnt lgkmcnt(" #n ")" ::: "memory")
; #define PG8_BAR __builtin_amdgcn_s_barrier()
; #define PG8_SCHED __builtin_amdgcn_sched_barrier(0)
;     ...
;             PG8_LDA(At, 0, 1); PG8_STAGE(PG8_SB(0, 0), b2, voffB); PG8_STAGE(PG8_SB(0, 1), b2 + hstep, voffB); PG8_STAGE(PG8_SA(0, 0), a2, voffA);
;             PG8_WAIT_V(8); PG8_WAIT_L(0); PG8_BAR; PG8_MMA(1, 0, At, B0); PG8_MMA(1, 1, At, B1); PG8_BAR; PG8_SCHED;
;             PG8_LDB(B0, 1, 0); PG8_LDB(B1, 1, 1); PG8_SCHED; PG8_LDA(At, 1, 0); PG8_STAGE(PG8_SA(0, 1), a2 + hstep, voffA);
;             PG8_WAIT_V(8); PG8_WAIT_L(0); PG8_BAR; PG8_MMA(0, 0, At, B0); PG8_MMA(0, 1, At, B1); PG8_BAR; PG8_SCHED;
	s_setprio 1
	s_waitcnt lgkmcnt(0)
	v_mfma_i32_16x16x64_i8 v[60:63], v[184:187], v[152:155], 0
	v_mfma_i32_16x16x64_i8 v[56:59], v[184:187], v[160:163], 0
	v_mfma_i32_16x16x64_i8 v[44:47], v[192:195], v[152:155], 0
	v_mfma_i32_16x16x64_i8 v[40:43], v[192:195], v[160:163], 0
	v_mfma_i32_16x16x64_i8 v[28:31], v[200:203], v[152:155], 0
	v_mfma_i32_16x16x64_i8 v[24:27], v[200:203], v[160:163], 0
	v_mfma_i32_16x16x64_i8 v[12:15], v[208:211], v[152:155], 0
	v_mfma_i32_16x16x64_i8 v[8:11], v[208:211], v[160:163], 0
	v_mfma_i32_16x16x64_i8 v[60:63], v[188:191], v[156:159], v[60:63]
	v_mfma_i32_16x16x64_i8 v[56:59], v[188:191], v[164:167], v[56:59]
	v_mfma_i32_16x16x64_i8 v[44:47], v[196:199], v[156:159], v[44:47]
	v_mfma_i32_16x16x64_i8 v[40:43], v[196:199], v[164:167], v[40:43]
	v_mfma_i32_16x16x64_i8 v[28:31], v[204:207], v[156:159], v[28:31]
	v_mfma_i32_16x16x64_i8 v[24:27], v[204:207], v[164:167], v[24:27]
	v_mfma_i32_16x16x64_i8 v[12:15], v[212:215], v[156:159], v[12:15]
	v_mfma_i32_16x16x64_i8 v[8:11], v[212:215], v[164:167], v[8:11]
	s_setprio 0
	s_setprio 1
	v_mfma_i32_16x16x64_i8 v[52:55], v[184:187], v[168:171], 0
	v_mfma_i32_16x16x64_i8 v[48:51], v[184:187], v[176:179], 0
	v_mfma_i32_16x16x64_i8 v[36:39], v[192:195], v[168:171], 0
	v_mfma_i32_16x16x64_i8 v[32:35], v[192:195], v[176:179], 0
	v_mfma_i32_16x16x64_i8 v[20:23], v[200:203], v[168:171], 0
	v_mfma_i32_16x16x64_i8 v[16:19], v[200:203], v[176:179], 0
	v_mfma_i32_16x16x64_i8 v[4:7], v[208:211], v[168:171], 0
	v_mfma_i32_16x16x64_i8 v[0:3], v[208:211], v[176:179], 0
	v_mfma_i32_16x16x64_i8 v[52:55], v[188:191], v[172:175], v[52:55]
	v_mfma_i32_16x16x64_i8 v[48:51], v[188:191], v[180:183], v[48:51]
	v_mfma_i32_16x16x64_i8 v[36:39], v[196:199], v[172:175], v[36:39]
	v_mfma_i32_16x16x64_i8 v[32:35], v[196:199], v[180:183], v[32:35]
	v_mfma_i32_16x16x64_i8 v[20:23], v[204:207], v[172:175], v[20:23]
	v_mfma_i32_16x16x64_i8 v[16:19], v[204:207], v[180:183], v[16:19]
	v_mfma_i32_16x16x64_i8 v[4:7], v[212:215], v[172:175], v[4:7]
	v_mfma_i32_16x16x64_i8 v[0:3], v[212:215], v[180:183], v[0:3]
	s_setprio 0
	s_barrier
	v_add_u32_e32 v151, s75, v144
	ds_read_b128 v[152:155], v151
	ds_read_b128 v[156:159], v151 offset:1024
	ds_read_b128 v[160:163], v151 offset:2048
	ds_read_b128 v[164:167], v151 offset:3072
	v_add_u32_e32 v151, s74, v144
	ds_read_b128 v[168:171], v151
	ds_read_b128 v[172:175], v151 offset:1024
	ds_read_b128 v[176:179], v151 offset:2048
	ds_read_b128 v[180:183], v151 offset:3072
	s_mov_b32 m0, s60
	v_lshl_add_u64 v[222:223], s[42:43], 0, v[128:129]
	ds_read_b128 v[184:187], v147 offset:32768
	ds_read_b128 v[188:191], v147 offset:33792
	ds_read_b128 v[192:195], v147 offset:34816
	ds_read_b128 v[196:199], v147 offset:35840
	ds_read_b128 v[200:203], v147 offset:36864
	ds_read_b128 v[204:207], v147 offset:37888
	ds_read_b128 v[208:211], v147 offset:38912
	ds_read_b128 v[212:215], v147 offset:39936
	global_load_lds_dwordx4 v[222:223], off
	v_lshl_add_u64 v[222:223], s[42:43], 0, v[132:133]
	s_mov_b32 m0, s61
	s_nop 0
	global_load_lds_dwordx4 v[222:223], off
	s_waitcnt vmcnt(8)
	s_waitcnt lgkmcnt(0)
	s_barrier
	s_setprio 1
	s_waitcnt lgkmcnt(0)
	v_mfma_i32_16x16x64_i8 v[124:127], v[184:187], v[152:155], v[124:127]
	v_mfma_i32_16x16x64_i8 v[120:123], v[184:187], v[160:163], v[120:123]
	v_mfma_i32_16x16x64_i8 v[108:111], v[192:195], v[152:155], v[108:111]
	v_mfma_i32_16x16x64_i8 v[104:107], v[192:195], v[160:163], v[104:107]
	v_mfma_i32_16x16x64_i8 v[92:95], v[200:203], v[152:155], v[92:95]
	v_mfma_i32_16x16x64_i8 v[88:91], v[200:203], v[160:163], v[88:91]
	v_mfma_i32_16x16x64_i8 v[76:79], v[208:211], v[152:155], v[76:79]
	v_mfma_i32_16x16x64_i8 v[72:75], v[208:211], v[160:163], v[72:75]
	v_mfma_i32_16x16x64_i8 v[124:127], v[188:191], v[156:159], v[124:127]
	v_mfma_i32_16x16x64_i8 v[120:123], v[188:191], v[164:167], v[120:123]
	v_mfma_i32_16x16x64_i8 v[108:111], v[196:199], v[156:159], v[108:111]
	v_mfma_i32_16x16x64_i8 v[104:107], v[196:199], v[164:167], v[104:107]
	v_mfma_i32_16x16x64_i8 v[92:95], v[204:207], v[156:159], v[92:95]
	v_mfma_i32_16x16x64_i8 v[88:91], v[204:207], v[164:167], v[88:91]
	v_mfma_i32_16x16x64_i8 v[76:79], v[212:215], v[156:159], v[76:79]
	v_mfma_i32_16x16x64_i8 v[72:75], v[212:215], v[164:167], v[72:75]
	s_setprio 0
	s_setprio 1
	v_mfma_i32_16x16x64_i8 v[116:119], v[184:187], v[168:171], v[116:119]
	v_mfma_i32_16x16x64_i8 v[112:115], v[184:187], v[176:179], v[112:115]
	v_mfma_i32_16x16x64_i8 v[100:103], v[192:195], v[168:171], v[100:103]
	v_mfma_i32_16x16x64_i8 v[96:99], v[192:195], v[176:179], v[96:99]
	v_mfma_i32_16x16x64_i8 v[84:87], v[200:203], v[168:171], v[84:87]
	v_mfma_i32_16x16x64_i8 v[80:83], v[200:203], v[176:179], v[80:83]
	v_mfma_i32_16x16x64_i8 v[68:71], v[208:211], v[168:171], v[68:71]
	v_mfma_i32_16x16x64_i8 v[64:67], v[208:211], v[176:179], v[64:67]
	v_mfma_i32_16x16x64_i8 v[116:119], v[188:191], v[172:175], v[116:119]
	v_mfma_i32_16x16x64_i8 v[112:115], v[188:191], v[180:183], v[112:115]
	v_mfma_i32_16x16x64_i8 v[100:103], v[196:199], v[172:175], v[100:103]
	v_mfma_i32_16x16x64_i8 v[96:99], v[196:199], v[180:183], v[96:99]
	v_mfma_i32_16x16x64_i8 v[84:87], v[204:207], v[172:175], v[84:87]
	v_mfma_i32_16x16x64_i8 v[80:83], v[204:207], v[180:183], v[80:83]
	v_mfma_i32_16x16x64_i8 v[68:71], v[212:215], v[172:175], v[68:71]
	v_mfma_i32_16x16x64_i8 v[64:67], v[212:215], v[180:183], v[64:67]
	s_setprio 0
	s_barrier
; #define PG8_STAGE(bufoff, gbase, voff) do { _Pragma("unroll") for (int _i = 0; _i < 2; ++_i) \
;         __builtin_amdgcn_global_load_lds((const unsigned*)((const char*)(gbase) + (voff)[_i]), (LAS unsigned*)(lds + (bufoff) + ldsw + _i * 8192), 16, 0, 0); } while (0)
; #define PG8_LDA(dst, b, h) do { _Pragma("unroll") for (int m = 0; m < 4; ++m) _Pragma("unroll") for (int k = 0; k < 2; ++k) dst[m][k] = *(const LAS bf16x8*)(lds + PG8_SA(b, h) + aoff + m * 2048 + k * 1024); } while (0)
; #define PG8_WAIT_V(n) asm volatile("s_waitcnt vmcnt(" #n ")" ::: "memory")
; #define PG8_WAIT_L(n) asm volatile("s_waitcnt lgkmcnt(" #n ")" ::: "memory")
; #define PG8_BAR __builtin_amdgcn_s_barrier()
; #define PG8_SCHED __builtin_amdgcn_sched_barrier(0)
;     ...
;             PG8_LDA(At, 1, 1); PG8_STAGE(PG8_SB(1, 0), b3, voffB); PG8_STAGE(PG8_SB(1, 1), b3 + hstep, voffB); PG8_STAGE(PG8_SA(1, 0), a3, voffA);
;             PG8_WAIT_V(8); PG8_WAIT_L(0); PG8_BAR; PG8_MMA(1, 0, At, B0); PG8_MMA(1, 1, At, B1); PG8_BAR; PG8_SCHED;
	s_mov_b32 m0, s73
	v_lshl_add_u64 v[142:143], v[142:143], 0, s[14:15]
	ds_read_b128 v[184:187], v147 offset:49152
	ds_read_b128 v[188:191], v147 offset:50176
	ds_read_b128 v[192:195], v147 offset:51200
	ds_read_b128 v[196:199], v147 offset:52224
	ds_read_b128 v[200:203], v147 offset:53248
	ds_read_b128 v[204:207], v147 offset:54272
	ds_read_b128 v[208:211], v147 offset:55296
	ds_read_b128 v[212:215], v147 offset:56320
	global_load_lds_dwordx4 v[142:143], off
	v_lshl_add_u64 v[142:143], v[216:217], 0, s[14:15]
	s_mov_b32 m0, s72
	s_nop 0
	global_load_lds_dwordx4 v[142:143], off
	v_lshl_add_u64 v[142:143], s[40:41], 0, v[130:131]
	s_mov_b32 m0, s81
	s_nop 0
	global_load_lds_dwordx4 v[142:143], off
	v_lshl_add_u64 v[142:143], s[40:41], 0, v[134:135]
	s_mov_b32 m0, s80
	s_nop 0
	global_load_lds_dwordx4 v[142:143], off
	v_lshl_add_u64 v[142:143], v[218:219], 0, s[14:15]
	s_mov_b32 m0, s64
	s_nop 0
	global_load_lds_dwordx4 v[142:143], off
	v_lshl_add_u64 v[142:143], v[220:221], 0, s[14:15]
	s_mov_b32 m0, s65
	s_nop 0
	global_load_lds_dwordx4 v[142:143], off
	s_waitcnt vmcnt(8)
	s_waitcnt lgkmcnt(0)
	s_barrier
	s_setprio 1
	s_waitcnt lgkmcnt(0)
	v_mfma_i32_16x16x64_i8 v[60:63], v[184:187], v[152:155], v[60:63]
	v_mfma_i32_16x16x64_i8 v[56:59], v[184:187], v[160:163], v[56:59]
	v_mfma_i32_16x16x64_i8 v[44:47], v[192:195], v[152:155], v[44:47]
	v_mfma_i32_16x16x64_i8 v[40:43], v[192:195], v[160:163], v[40:43]
	v_mfma_i32_16x16x64_i8 v[28:31], v[200:203], v[152:155], v[28:31]
	v_mfma_i32_16x16x64_i8 v[24:27], v[200:203], v[160:163], v[24:27]
	v_mfma_i32_16x16x64_i8 v[12:15], v[208:211], v[152:155], v[12:15]
	v_mfma_i32_16x16x64_i8 v[8:11], v[208:211], v[160:163], v[8:11]
	v_mfma_i32_16x16x64_i8 v[60:63], v[188:191], v[156:159], v[60:63]
	v_mfma_i32_16x16x64_i8 v[56:59], v[188:191], v[164:167], v[56:59]
	v_mfma_i32_16x16x64_i8 v[44:47], v[196:199], v[156:159], v[44:47]
	v_mfma_i32_16x16x64_i8 v[40:43], v[196:199], v[164:167], v[40:43]
	v_mfma_i32_16x16x64_i8 v[28:31], v[204:207], v[156:159], v[28:31]
	v_mfma_i32_16x16x64_i8 v[24:27], v[204:207], v[164:167], v[24:27]
	v_mfma_i32_16x16x64_i8 v[12:15], v[212:215], v[156:159], v[12:15]
	v_mfma_i32_16x16x64_i8 v[8:11], v[212:215], v[164:167], v[8:11]
	s_setprio 0
	s_setprio 1
	v_mfma_i32_16x16x64_i8 v[52:55], v[184:187], v[168:171], v[52:55]
	v_mfma_i32_16x16x64_i8 v[48:51], v[184:187], v[176:179], v[48:51]
	v_mfma_i32_16x16x64_i8 v[36:39], v[192:195], v[168:171], v[36:39]
	v_mfma_i32_16x16x64_i8 v[32:35], v[192:195], v[176:179], v[32:35]
	v_mfma_i32_16x16x64_i8 v[20:23], v[200:203], v[168:171], v[20:23]
	v_mfma_i32_16x16x64_i8 v[16:19], v[200:203], v[176:179], v[16:19]
	v_mfma_i32_16x16x64_i8 v[4:7], v[208:211], v[168:171], v[4:7]
	v_mfma_i32_16x16x64_i8 v[0:3], v[208:211], v[176:179], v[0:3]
	v_mfma_i32_16x16x64_i8 v[52:55], v[188:191], v[172:175], v[52:55]
	v_mfma_i32_16x16x64_i8 v[48:51], v[188:191], v[180:183], v[48:51]
	v_mfma_i32_16x16x64_i8 v[36:39], v[196:199], v[172:175], v[36:39]
	v_mfma_i32_16x16x64_i8 v[32:35], v[196:199], v[180:183], v[32:35]
	v_mfma_i32_16x16x64_i8 v[20:23], v[204:207], v[172:175], v[20:23]
	v_mfma_i32_16x16x64_i8 v[16:19], v[204:207], v[180:183], v[16:19]
	v_mfma_i32_16x16x64_i8 v[4:7], v[212:215], v[172:175], v[4:7]
	v_mfma_i32_16x16x64_i8 v[0:3], v[212:215], v[180:183], v[0:3]
	s_setprio 0
	s_barrier
	s_movk_i32 s42, 0x100
	s_andn2_b64 vcc, exec, s[6:7]
	s_mov_b64 s[40:41], -1
	s_mov_b64 s[6:7], 0
	s_cbranch_vccz .LBB0_4162

; #define PG8_STAGE(bufoff, gbase, voff) do { _Pragma("unroll") for (int _i = 0; _i < 2; ++_i) \
;         __builtin_amdgcn_global_load_lds((const unsigned*)((const char*)(gbase) + (voff)[_i]), (LAS unsigned*)(lds + (bufoff) + ldsw + _i * 8192), 16, 0, 0); } while (0)
; #define PG8_LDA(dst, b, h) do { _Pragma("unroll") for (int m = 0; m < 4; ++m) _Pragma("unroll") for (int k = 0; k < 2; ++k) dst[m][k] = *(const LAS bf16x8*)(lds + PG8_SA(b, h) + aoff + m * 2048 + k * 1024); } while (0)
; #define PG8_LDB(dst, b, h) do { _Pragma("unroll") for (int n = 0; n < 2; ++n) _Pragma("unroll") for (int k = 0; k < 2; ++k) dst[n][k] = *(const LAS bf16x8*)(lds + PG8_SB(b, h) + boff + n * 2048 + k * 1024); } while (0)
; #define PG8_SCHED __builtin_amdgcn_sched_barrier(0)
;     __device__ __forceinline__ bool next(int i, Unit& u) const {
;         const long L = (long)i * G + c; if (L >= nwg) return false;
;         int wgid = (int)L; { const int q = nwg / NXCD, r = nwg % NXCD, xcd = wgid % NXCD, off = wgid / NXCD; wgid = (xcd < r ? xcd * (q + 1) : r * (q + 1) + (xcd - r) * q) + off; }
;         const int nig = WGM * nN, gid = wgid / nig, fm = gid * WGM, gsz = (nM - fm) < WGM ? (nM - fm) : WGM;
;         u.pm = fm + ((wgid % nig) % gsz); u.pn = (wgid % nig) / gsz; u.e = 0; u.kt0 = 0; u.nkt = nt; u.buf = 0;
;     ...
;             PG8_LDB(B0, 0, 0); PG8_LDB(B1, 0, 1); PG8_SCHED; PG8_LDA(At, 0, 0); PG8_STAGE(PG8_SA(1, 1), a1 + hstep, voffA);
.LBB0_4495:
	ds_read_b128 v[24:27], v187
	ds_read_b128 v[28:31], v187 offset:1024
	ds_read_b128 v[16:19], v187 offset:2048
	ds_read_b128 v[20:23], v187 offset:3072
	ds_read_b128 v[8:11], v188
	ds_read_b128 v[12:15], v188 offset:1024
	ds_read_b128 v[4:7], v188 offset:3072
	ds_read_b128 v[176:179], v189
	ds_read_b128 v[180:183], v189 offset:1024
	ds_read_b128 v[192:195], v189 offset:2048
	ds_read_b128 v[196:199], v189 offset:3072
	ds_read_b128 v[200:203], v189 offset:4096
	ds_read_b128 v[204:207], v189 offset:5120
	ds_read_b128 v[208:211], v189 offset:6144
	ds_read_b128 v[212:215], v189 offset:7168
	s_add_i32 s54, s54, 1
	s_mul_i32 s2, s54, s59
	s_mul_hi_u32 s3, s54, s33
	s_add_i32 s3, s3, s2
	s_mul_i32 s2, s54, s33
	s_add_u32 s38, s2, s22
	s_addc_u32 s39, s3, s23
	v_cmp_gt_i64_e32 vcc, s[38:39], v[174:175]
	v_cmp_lt_i64_e64 s[2:3], s[38:39], v[172:173]
	s_cbranch_vccnz .LBB0_4501
	s_ashr_i32 s30, s38, 31
	s_lshr_b32 s30, s30, 29
	s_add_i32 s36, s38, s30
	s_and_b32 s30, s36, -8
	s_sub_i32 s37, s38, s30
	s_cmp_gt_i32 s37, -1
	s_mov_b64 s[30:31], -1
	s_cbranch_scc0 .LBB0_4498
	s_lshl_b32 s38, s37, 6
	s_mov_b64 s[30:31], 0

; #define PG8_STAGE(bufoff, gbase, voff) do { _Pragma("unroll") for (int _i = 0; _i < 2; ++_i) \
;         __builtin_amdgcn_global_load_lds((const unsigned*)((const char*)(gbase) + (voff)[_i]), (LAS unsigned*)(lds + (bufoff) + ldsw + _i * 8192), 16, 0, 0); } while (0)
; #define PG8_LDA(dst, b, h) do { _Pragma("unroll") for (int m = 0; m < 4; ++m) _Pragma("unroll") for (int k = 0; k < 2; ++k) dst[m][k] = *(const LAS bf16x8*)(lds + PG8_SA(b, h) + aoff + m * 2048 + k * 1024); } while (0)
; #define PG8_LDB(dst, b, h) do { _Pragma("unroll") for (int n = 0; n < 2; ++n) _Pragma("unroll") for (int k = 0; k < 2; ++k) dst[n][k] = *(const LAS bf16x8*)(lds + PG8_SB(b, h) + boff + n * 2048 + k * 1024); } while (0)
; #define PG8_WAIT_V(n) asm volatile("s_waitcnt vmcnt(" #n ")" ::: "memory")
; #define PG8_WAIT_L(n) asm volatile("s_waitcnt lgkmcnt(" #n ")" ::: "memory")
; #define PG8_BAR __builtin_amdgcn_s_barrier()
; #define PG8_SCHED __builtin_amdgcn_sched_barrier(0)
;     ...
;         const char* nA = has_next ? (const char*)g.A + (size_t)nxt.pm * tstep + (size_t)nxt.kt0 * kstep : cA; const char* nB = has_next ? (const char*)g.Bt + (size_t)nxt.e * g.estride + (size_t)nxt.pn * tstep + (size_t)nxt.kt0 * kstep : cB;
;         const int nt = cur.nkt;
;         for (int t = 0; t < nt; t += 2) {
;             const bool last = (t == nt - 2);
;             const char* a1 = cA + (size_t)(t + 1) * kstep;
;             const char* a2 = last ? nA : cA + (size_t)(t + 2) * kstep; const char* b2 = last ? nB : cB + (size_t)(t + 2) * kstep;
;             const char* a3 = a2 + kstep; const char* b3 = b2 + kstep;
;             PG8_LDB(B0, 0, 0); PG8_LDB(B1, 0, 1); PG8_SCHED; PG8_LDA(At, 0, 0); PG8_STAGE(PG8_SA(1, 1), a1 + hstep, voffA);
;             PG8_WAIT_V(8); PG8_WAIT_L(0); PG8_BAR; PG8_MMA(0, 0, At, B0); PG8_MMA(0, 1, At, B1); PG8_BAR; PG8_SCHED;
;             PG8_LDA(At, 0, 1); PG8_STAGE(PG8_SB(0, 0), b2, voffB); PG8_STAGE(PG8_SB(0, 1), b2 + hstep, voffB); PG8_STAGE(PG8_SA(0, 0), a2, voffA);
;             PG8_WAIT_V(8); PG8_WAIT_L(0); PG8_BAR; PG8_MMA(1, 0, At, B0); PG8_MMA(1, 1, At, B1); PG8_BAR; PG8_SCHED;
.LBB0_4501:
	s_ashr_i32 s37, s36, 31
	s_lshl_b64 s[38:39], s[36:37], 19
	s_add_u32 s38, s25, s38
	s_addc_u32 s39, s27, s39
	s_and_b64 s[40:41], s[2:3], exec
	s_cselect_b32 s37, s39, s43
	s_cselect_b32 s63, s38, s42
	s_ashr_i32 s31, s30, 31
	s_lshl_b64 s[40:41], s[30:31], 19
	s_add_u32 s40, s29, s40
	s_addc_u32 s41, s34, s41
	s_and_b64 s[46:47], s[2:3], exec
	s_cselect_b32 s31, s41, s45
	s_cselect_b32 s64, s40, s44
	s_add_u32 s42, s42, 0x40080
	s_addc_u32 s43, s43, 0
	s_add_u32 s65, s44, 0x100
	s_addc_u32 s66, s45, 0
	s_mov_b32 s67, -2
	ds_read_b128 v[0:3], v188 offset:2048
	s_add_u32 s44, s42, 0xfffc0080
	s_addc_u32 s45, s43, -1
	s_cmp_eq_u32 s67, 12
	s_cselect_b32 s47, s37, s45
	s_cselect_b32 s46, s63, s44
	s_cselect_b32 s45, s31, s66
	s_cselect_b32 s44, s64, s65
	v_lshl_add_u64 v[216:217], s[42:43], 0, v[168:169]
	s_add_i32 m0, s48, 0xc000
	global_load_lds_dwordx4 v[216:217], off
	v_lshl_add_u64 v[216:217], s[42:43], 0, v[170:171]
	s_add_i32 m0, s48, 0xe000
	s_nop 0
	global_load_lds_dwordx4 v[216:217], off
	s_waitcnt vmcnt(8)
	s_waitcnt lgkmcnt(0)
	s_barrier
	s_setprio 1
	s_waitcnt lgkmcnt(0)
	v_mfma_scale_f32_16x16x128_f8f6f4 v[156:159], v[24:31], v[176:183], 0, v190, v190 op_sel_hi:[0,0,0]
	v_mfma_scale_f32_16x16x128_f8f6f4 v[152:155], v[16:23], v[176:183], 0, v190, v190 op_sel_hi:[0,0,0]
	v_mfma_scale_f32_16x16x128_f8f6f4 v[140:143], v[24:31], v[192:199], 0, v190, v190 op_sel_hi:[0,0,0]
	v_mfma_scale_f32_16x16x128_f8f6f4 v[136:139], v[16:23], v[192:199], 0, v190, v190 op_sel_hi:[0,0,0]
	v_mfma_scale_f32_16x16x128_f8f6f4 v[124:127], v[24:31], v[200:207], 0, v190, v190 op_sel_hi:[0,0,0]
	v_mfma_scale_f32_16x16x128_f8f6f4 v[120:123], v[16:23], v[200:207], 0, v190, v190 op_sel_hi:[0,0,0]
	v_mfma_scale_f32_16x16x128_f8f6f4 v[108:111], v[24:31], v[208:215], 0, v190, v190 op_sel_hi:[0,0,0]
	v_mfma_scale_f32_16x16x128_f8f6f4 v[104:107], v[16:23], v[208:215], 0, v190, v190 op_sel_hi:[0,0,0]
	s_setprio 0
	s_setprio 1
	v_mfma_scale_f32_16x16x128_f8f6f4 v[148:151], v[8:15], v[176:183], 0, v190, v190 op_sel_hi:[0,0,0]
	v_mfma_scale_f32_16x16x128_f8f6f4 v[144:147], v[0:7], v[176:183], 0, v190, v190 op_sel_hi:[0,0,0]
	v_mfma_scale_f32_16x16x128_f8f6f4 v[132:135], v[8:15], v[192:199], 0, v190, v190 op_sel_hi:[0,0,0]
	v_mfma_scale_f32_16x16x128_f8f6f4 v[128:131], v[0:7], v[192:199], 0, v190, v190 op_sel_hi:[0,0,0]
	v_mfma_scale_f32_16x16x128_f8f6f4 v[116:119], v[8:15], v[200:207], 0, v190, v190 op_sel_hi:[0,0,0]
	v_mfma_scale_f32_16x16x128_f8f6f4 v[112:115], v[0:7], v[200:207], 0, v190, v190 op_sel_hi:[0,0,0]
	v_mfma_scale_f32_16x16x128_f8f6f4 v[100:103], v[8:15], v[208:215], 0, v190, v190 op_sel_hi:[0,0,0]
	v_mfma_scale_f32_16x16x128_f8f6f4 v[96:99], v[0:7], v[208:215], 0, v190, v190 op_sel_hi:[0,0,0]
	s_setprio 0
	s_barrier
	s_add_i32 s68, s60, s35
	v_lshl_add_u64 v[176:177], s[44:45], 0, v[162:163]
	s_mov_b32 m0, s68
	ds_read_b128 v[192:195], v189 offset:16384
	ds_read_b128 v[196:199], v189 offset:17408
	ds_read_b128 v[200:203], v189 offset:18432
	ds_read_b128 v[204:207], v189 offset:19456
	ds_read_b128 v[208:211], v189 offset:20480
	ds_read_b128 v[212:215], v189 offset:21504
	ds_read_b128 v[216:219], v189 offset:22528
	ds_read_b128 v[220:223], v189 offset:23552
	global_load_lds_dwordx4 v[176:177], off
	s_add_i32 m0, s68, 0x2000
	s_add_u32 s68, s44, 0x40000
	v_lshl_add_u64 v[178:179], s[44:45], 0, v[166:167]
	s_addc_u32 s69, s45, 0
	s_add_i32 s70, s61, s35
	global_load_lds_dwordx4 v[178:179], off
	v_lshl_add_u64 v[180:181], s[68:69], 0, v[162:163]
	s_mov_b32 m0, s70
	v_lshl_add_u64 v[182:183], s[46:47], 0, v[164:165]
	global_load_lds_dwordx4 v[180:181], off
	v_lshl_add_u64 v[180:181], s[68:69], 0, v[166:167]
	s_add_i32 m0, s70, 0x2000
	s_nop 0
	global_load_lds_dwordx4 v[180:181], off
	v_lshl_add_u64 v[180:181], s[46:47], 0, v[160:161]
	s_mov_b32 m0, s48
	s_nop 0
	global_load_lds_dwordx4 v[180:181], off
	s_mov_b32 m0, s49
	s_nop 0
	global_load_lds_dwordx4 v[182:183], off
	s_waitcnt vmcnt(8)
	s_waitcnt lgkmcnt(0)
	s_barrier
	s_setprio 1
	s_waitcnt lgkmcnt(0)
	v_mfma_scale_f32_16x16x128_f8f6f4 v[92:95], v[24:31], v[192:199], 0, v190, v190 op_sel_hi:[0,0,0]
	v_mfma_scale_f32_16x16x128_f8f6f4 v[88:91], v[16:23], v[192:199], 0, v190, v190 op_sel_hi:[0,0,0]
	v_mfma_scale_f32_16x16x128_f8f6f4 v[76:79], v[24:31], v[200:207], 0, v190, v190 op_sel_hi:[0,0,0]
	v_mfma_scale_f32_16x16x128_f8f6f4 v[72:75], v[16:23], v[200:207], 0, v190, v190 op_sel_hi:[0,0,0]
	v_mfma_scale_f32_16x16x128_f8f6f4 v[60:63], v[24:31], v[208:215], 0, v190, v190 op_sel_hi:[0,0,0]
	v_mfma_scale_f32_16x16x128_f8f6f4 v[56:59], v[16:23], v[208:215], 0, v190, v190 op_sel_hi:[0,0,0]
	v_mfma_scale_f32_16x16x128_f8f6f4 v[44:47], v[24:31], v[216:223], 0, v190, v190 op_sel_hi:[0,0,0]
	v_mfma_scale_f32_16x16x128_f8f6f4 v[40:43], v[16:23], v[216:223], 0, v190, v190 op_sel_hi:[0,0,0]
	s_setprio 0
	s_setprio 1
	v_mfma_scale_f32_16x16x128_f8f6f4 v[84:87], v[8:15], v[192:199], 0, v190, v190 op_sel_hi:[0,0,0]
	v_mfma_scale_f32_16x16x128_f8f6f4 v[80:83], v[0:7], v[192:199], 0, v190, v190 op_sel_hi:[0,0,0]
	v_mfma_scale_f32_16x16x128_f8f6f4 v[68:71], v[8:15], v[200:207], 0, v190, v190 op_sel_hi:[0,0,0]
	v_mfma_scale_f32_16x16x128_f8f6f4 v[64:67], v[0:7], v[200:207], 0, v190, v190 op_sel_hi:[0,0,0]
	v_mfma_scale_f32_16x16x128_f8f6f4 v[52:55], v[8:15], v[208:215], 0, v190, v190 op_sel_hi:[0,0,0]
	v_mfma_scale_f32_16x16x128_f8f6f4 v[48:51], v[0:7], v[208:215], 0, v190, v190 op_sel_hi:[0,0,0]
	v_mfma_scale_f32_16x16x128_f8f6f4 v[36:39], v[8:15], v[216:223], 0, v190, v190 op_sel_hi:[0,0,0]
	v_mfma_scale_f32_16x16x128_f8f6f4 v[32:35], v[0:7], v[216:223], 0, v190, v190 op_sel_hi:[0,0,0]
	s_setprio 0
	s_barrier
; #define PG8_STAGE(bufoff, gbase, voff) do { _Pragma("unroll") for (int _i = 0; _i < 2; ++_i) \
;         __builtin_amdgcn_global_load_lds((const unsigned*)((const char*)(gbase) + (voff)[_i]), (LAS unsigned*)(lds + (bufoff) + ldsw + _i * 8192), 16, 0, 0); } while (0)
; #define PG8_LDA(dst, b, h) do { _Pragma("unroll") for (int m = 0; m < 4; ++m) _Pragma("unroll") for (int k = 0; k < 2; ++k) dst[m][k] = *(const LAS bf16x8*)(lds + PG8_SA(b, h) + aoff + m * 2048 + k * 1024); } while (0)
; #define PG8_LDB(dst, b, h) do { _Pragma("unroll") for (int n = 0; n < 2; ++n) _Pragma("unroll") for (int k = 0; k < 2; ++k) dst[n][k] = *(const LAS bf16x8*)(lds + PG8_SB(b, h) + boff + n * 2048 + k * 1024); } while (0)
; #define PG8_WAIT_V(n) asm volatile("s_waitcnt vmcnt(" #n ")" ::: "memory")
; #define PG8_WAIT_L(n) asm volatile("s_waitcnt lgkmcnt(" #n ")" ::: "memory")
; #define PG8_BAR __builtin_amdgcn_s_barrier()
; #define PG8_SCHED __builtin_amdgcn_sched_barrier(0)
;     ...
;             PG8_LDB(B0, 1, 0); PG8_LDB(B1, 1, 1); PG8_SCHED; PG8_LDA(At, 1, 0); PG8_STAGE(PG8_SA(0, 1), a2 + hstep, voffA);
;             PG8_WAIT_V(8); PG8_WAIT_L(0); PG8_BAR; PG8_MMA(0, 0, At, B0); PG8_MMA(0, 1, At, B1); PG8_BAR; PG8_SCHED;
;             PG8_LDA(At, 1, 1); PG8_STAGE(PG8_SB(1, 0), b3, voffB); PG8_STAGE(PG8_SB(1, 1), b3 + hstep, voffB); PG8_STAGE(PG8_SA(1, 0), a3, voffA);
;             PG8_WAIT_V(8); PG8_WAIT_L(0); PG8_BAR; PG8_MMA(1, 0, At, B0); PG8_MMA(1, 1, At, B1); PG8_BAR; PG8_SCHED;
	s_add_i32 s68, 0, 0x18000
	s_add_i32 s69, 0, 0x1c000
	v_add_u32_e32 v12, s68, v185
	v_add_u32_e32 v28, s69, v185
	ds_read_b128 v[0:3], v12
	ds_read_b128 v[4:7], v12 offset:1024
	ds_read_b128 v[8:11], v12 offset:2048
	ds_read_b128 v[12:15], v12 offset:3072
	ds_read_b128 v[16:19], v28
	ds_read_b128 v[20:23], v28 offset:1024
	ds_read_b128 v[24:27], v28 offset:2048
	ds_read_b128 v[28:31], v28 offset:3072
	s_add_u32 s46, s46, 0x40000
	s_addc_u32 s47, s47, 0
	s_mov_b32 m0, s50
	v_lshl_add_u64 v[224:225], s[46:47], 0, v[160:161]
	ds_read_b128 v[192:195], v189 offset:32768
	ds_read_b128 v[196:199], v189 offset:33792
	ds_read_b128 v[200:203], v189 offset:34816
	ds_read_b128 v[204:207], v189 offset:35840
	ds_read_b128 v[208:211], v189 offset:36864
	ds_read_b128 v[212:215], v189 offset:37888
	ds_read_b128 v[216:219], v189 offset:38912
	ds_read_b128 v[220:223], v189 offset:39936
	global_load_lds_dwordx4 v[224:225], off
	v_lshl_add_u64 v[224:225], s[46:47], 0, v[164:165]
	s_mov_b32 m0, s51
	s_nop 0
	global_load_lds_dwordx4 v[224:225], off
	s_waitcnt vmcnt(8)
	s_waitcnt lgkmcnt(0)
	s_barrier
	s_setprio 1
	s_waitcnt lgkmcnt(0)
	v_mfma_scale_f32_16x16x128_f8f6f4 v[156:159], v[0:7], v[192:199], v[156:159], v190, v190 op_sel_hi:[0,0,0]
	v_mfma_scale_f32_16x16x128_f8f6f4 v[152:155], v[8:15], v[192:199], v[152:155], v190, v190 op_sel_hi:[0,0,0]
	v_mfma_scale_f32_16x16x128_f8f6f4 v[140:143], v[0:7], v[200:207], v[140:143], v190, v190 op_sel_hi:[0,0,0]
	v_mfma_scale_f32_16x16x128_f8f6f4 v[136:139], v[8:15], v[200:207], v[136:139], v190, v190 op_sel_hi:[0,0,0]
	v_mfma_scale_f32_16x16x128_f8f6f4 v[124:127], v[0:7], v[208:215], v[124:127], v190, v190 op_sel_hi:[0,0,0]
	v_mfma_scale_f32_16x16x128_f8f6f4 v[120:123], v[8:15], v[208:215], v[120:123], v190, v190 op_sel_hi:[0,0,0]
	v_mfma_scale_f32_16x16x128_f8f6f4 v[108:111], v[0:7], v[216:223], v[108:111], v190, v190 op_sel_hi:[0,0,0]
	v_mfma_scale_f32_16x16x128_f8f6f4 v[104:107], v[8:15], v[216:223], v[104:107], v190, v190 op_sel_hi:[0,0,0]
	s_setprio 0
	s_setprio 1
	v_mfma_scale_f32_16x16x128_f8f6f4 v[148:151], v[16:23], v[192:199], v[148:151], v190, v190 op_sel_hi:[0,0,0]
	v_mfma_scale_f32_16x16x128_f8f6f4 v[144:147], v[24:31], v[192:199], v[144:147], v190, v190 op_sel_hi:[0,0,0]
	v_mfma_scale_f32_16x16x128_f8f6f4 v[132:135], v[16:23], v[200:207], v[132:135], v190, v190 op_sel_hi:[0,0,0]
	v_mfma_scale_f32_16x16x128_f8f6f4 v[128:131], v[24:31], v[200:207], v[128:131], v190, v190 op_sel_hi:[0,0,0]
	v_mfma_scale_f32_16x16x128_f8f6f4 v[116:119], v[16:23], v[208:215], v[116:119], v190, v190 op_sel_hi:[0,0,0]
	v_mfma_scale_f32_16x16x128_f8f6f4 v[112:115], v[24:31], v[208:215], v[112:115], v190, v190 op_sel_hi:[0,0,0]
	v_mfma_scale_f32_16x16x128_f8f6f4 v[100:103], v[16:23], v[216:223], v[100:103], v190, v190 op_sel_hi:[0,0,0]
	v_mfma_scale_f32_16x16x128_f8f6f4 v[96:99], v[24:31], v[216:223], v[96:99], v190, v190 op_sel_hi:[0,0,0]
	s_setprio 0
	s_barrier
	s_add_i32 s46, s68, s35
	v_lshl_add_u64 v[176:177], v[176:177], 0, s[18:19]
	s_mov_b32 m0, s46
	ds_read_b128 v[192:195], v189 offset:49152
	ds_read_b128 v[196:199], v189 offset:50176
	ds_read_b128 v[200:203], v189 offset:51200
	ds_read_b128 v[204:207], v189 offset:52224
	ds_read_b128 v[208:211], v189 offset:53248
	ds_read_b128 v[212:215], v189 offset:54272
	ds_read_b128 v[216:219], v189 offset:55296
	ds_read_b128 v[220:223], v189 offset:56320
	global_load_lds_dwordx4 v[176:177], off
	s_add_i32 m0, s46, 0x2000
	s_add_u32 s44, s44, 0x40080
	v_lshl_add_u64 v[176:177], v[178:179], 0, s[18:19]
	s_addc_u32 s45, s45, 0
	s_add_i32 s46, s69, s35
	global_load_lds_dwordx4 v[176:177], off
	v_lshl_add_u64 v[176:177], s[44:45], 0, v[162:163]
	s_mov_b32 m0, s46
	s_nop 0
	global_load_lds_dwordx4 v[176:177], off
	v_lshl_add_u64 v[176:177], s[44:45], 0, v[166:167]
	s_add_i32 m0, s46, 0x2000
	s_nop 0
	global_load_lds_dwordx4 v[176:177], off
	v_lshl_add_u64 v[176:177], v[180:181], 0, s[18:19]
	s_mov_b32 m0, s55
	s_nop 0
	global_load_lds_dwordx4 v[176:177], off
	v_lshl_add_u64 v[176:177], v[182:183], 0, s[18:19]
	s_mov_b32 m0, s58
	s_nop 0
	global_load_lds_dwordx4 v[176:177], off
	s_waitcnt vmcnt(8)
	s_waitcnt lgkmcnt(0)
	s_barrier
	s_setprio 1
	s_waitcnt lgkmcnt(0)
	v_mfma_scale_f32_16x16x128_f8f6f4 v[92:95], v[0:7], v[192:199], v[92:95], v190, v190 op_sel_hi:[0,0,0]
	v_mfma_scale_f32_16x16x128_f8f6f4 v[88:91], v[8:15], v[192:199], v[88:91], v190, v190 op_sel_hi:[0,0,0]
	v_mfma_scale_f32_16x16x128_f8f6f4 v[76:79], v[0:7], v[200:207], v[76:79], v190, v190 op_sel_hi:[0,0,0]
	v_mfma_scale_f32_16x16x128_f8f6f4 v[72:75], v[8:15], v[200:207], v[72:75], v190, v190 op_sel_hi:[0,0,0]
	v_mfma_scale_f32_16x16x128_f8f6f4 v[60:63], v[0:7], v[208:215], v[60:63], v190, v190 op_sel_hi:[0,0,0]
	v_mfma_scale_f32_16x16x128_f8f6f4 v[56:59], v[8:15], v[208:215], v[56:59], v190, v190 op_sel_hi:[0,0,0]
	v_mfma_scale_f32_16x16x128_f8f6f4 v[44:47], v[0:7], v[216:223], v[44:47], v190, v190 op_sel_hi:[0,0,0]
	v_mfma_scale_f32_16x16x128_f8f6f4 v[40:43], v[8:15], v[216:223], v[40:43], v190, v190 op_sel_hi:[0,0,0]
	s_setprio 0
	s_setprio 1
	v_mfma_scale_f32_16x16x128_f8f6f4 v[84:87], v[16:23], v[192:199], v[84:87], v190, v190 op_sel_hi:[0,0,0]
	v_mfma_scale_f32_16x16x128_f8f6f4 v[80:83], v[24:31], v[192:199], v[80:83], v190, v190 op_sel_hi:[0,0,0]
	v_mfma_scale_f32_16x16x128_f8f6f4 v[68:71], v[16:23], v[200:207], v[68:71], v190, v190 op_sel_hi:[0,0,0]
	v_mfma_scale_f32_16x16x128_f8f6f4 v[64:67], v[24:31], v[200:207], v[64:67], v190, v190 op_sel_hi:[0,0,0]
	v_mfma_scale_f32_16x16x128_f8f6f4 v[52:55], v[16:23], v[208:215], v[52:55], v190, v190 op_sel_hi:[0,0,0]
	v_mfma_scale_f32_16x16x128_f8f6f4 v[48:51], v[24:31], v[208:215], v[48:51], v190, v190 op_sel_hi:[0,0,0]
	v_mfma_scale_f32_16x16x128_f8f6f4 v[36:39], v[16:23], v[216:223], v[36:39], v190, v190 op_sel_hi:[0,0,0]
	v_mfma_scale_f32_16x16x128_f8f6f4 v[32:35], v[24:31], v[216:223], v[32:35], v190, v190 op_sel_hi:[0,0,0]
	s_setprio 0
	s_barrier
	s_add_i32 s67, s67, 2
	s_add_u32 s42, s42, 0x100
	s_addc_u32 s43, s43, 0
	s_add_u32 s65, s65, 0x100
	s_addc_u32 s66, s66, 0
	s_cmp_gt_u32 s67, 13
	s_cbranch_scc0 .LBB0_4502

;     __device__ __forceinline__ void init(int nM, int nN_, int nt, int G, int v_, const int* ts_) { nN = nN_; ts = ts_; v = v_; splitk_plan(nM, nN, nt, G, main_m, s); R = (nM - main_m) * nN; nkt = nt / s; }
; __device__ __forceinline__ void splitk_plan(int nM, int nN, int nt, int G, int& main_m, int& s) {
;     main_m = ((nM * nN) / G) * G / nN; const int R = (nM - main_m) * nN; s = 1;
; __global__ void __launch_bounds__(512, 2) fwd_kernel(Params P) {
;     ...
;     if (IN(13)) {
;         int main_m, sk; pg8::splitk_plan(meta[0], 8, FFE / 128, G, main_m, sk);
;         pg8::Gemm g{(const bf16_t*)(ws + WS_ACT1), (const bf16_t*)(ws + WS_W_MD), FFE / 2, (size_t)2048 * FFE};
;         { pg8::TileOrder S; S.init(main_m, 8, G, cid, meta + 1, FFE / 128);
.LBB0_4799:
	s_waitcnt lgkmcnt(0)
	s_cmp_lt_i32 s8, 14
	s_cselect_b64 s[2:3], -1, 0
	s_cmp_gt_i32 s9, 13
	s_cselect_b64 s[4:5], -1, 0
	s_and_b64 s[2:3], s[2:3], s[4:5]
	s_andn2_b64 vcc, exec, s[2:3]
	s_cbranch_vccnz .LBB0_4887
	s_waitcnt vmcnt(0)
	v_mov_b32_e32 v161, 0
	global_load_dword v0, v161, s[6:7]
	s_abs_i32 s35, s33
	v_cvt_f32_u32_e32 v1, s35
	s_sub_i32 s2, 0, s35
	v_mbcnt_lo_u32_b32 v10, -1, 0
	v_mbcnt_hi_u32_b32 v10, -1, v10
	v_rcp_iflag_f32_e32 v1, v1
	s_nop 0
	v_mul_f32_e32 v1, 0x4f7ffffe, v1
	v_cvt_u32_f32_e32 v1, v1
	s_nop 0
	v_readfirstlane_b32 s40, v1
	s_mul_i32 s2, s2, s40
	s_mul_hi_u32 s2, s40, s2
	s_add_i32 s40, s40, s2
	s_waitcnt vmcnt(0)
	v_readfirstlane_b32 s2, v0
	s_lshl_b32 s2, s2, 3
	s_abs_i32 s4, s2
	s_mul_hi_u32 s5, s4, s40
	s_mul_i32 s5, s5, s35
	s_sub_i32 s4, s4, s5
	s_ashr_i32 s3, s2, 31
	s_sub_i32 s5, s4, s35
	s_cmp_ge_u32 s4, s35
	s_cselect_b32 s4, s5, s4
	s_sub_i32 s5, s4, s35
	s_cmp_ge_u32 s4, s35
	s_cselect_b32 s4, s5, s4
	s_xor_b32 s4, s4, s3
	s_sub_i32 s3, s3, s4
	s_add_i32 s2, s2, s3
	s_ashr_i32 s3, s2, 31
	s_lshr_b32 s3, s3, 29
	s_add_i32 s2, s2, s3
	s_ashr_i32 s23, s2, 3
	s_add_u32 s29, s56, 0x4b000000
	s_addc_u32 s34, s57, 0
	s_add_u32 s8, s56, 0x24000000
	s_addc_u32 s9, s57, 0
	s_and_b32 s2, s2, -8
	v_add_u32_e32 v0, s96, v10
	s_cmp_ge_i32 s22, s2
	v_readfirstlane_b32 s3, v0
	s_cbranch_scc1 .LBB0_4820
; #define PG8_STAGE(bufoff, gbase, voff) do { _Pragma("unroll") for (int _i = 0; _i < 2; ++_i) \
;         __builtin_amdgcn_global_load_lds((const unsigned*)((const char*)(gbase) + (voff)[_i]), (LAS unsigned*)(lds + (bufoff) + ldsw + _i * 8192), 16, 0, 0); } while (0)
;     __device__ __forceinline__ bool next(int i, Unit& u) const {
;         const long L = (long)i * G + c; if (L >= nwg) return false;
;         int wgid = (int)L; { const int q = nwg / NXCD, r = nwg % NXCD, xcd = wgid % NXCD, off = wgid / NXCD; wgid = (xcd < r ? xcd * (q + 1) : r * (q + 1) + (xcd - r) * q) + off; }
;         const int nig = WGM * nN, gid = wgid / nig, fm = gid * WGM, gsz = (nM - fm) < WGM ? (nM - fm) : WGM;
;         u.pm = fm + ((wgid % nig) % gsz); u.pn = (wgid % nig) / gsz; u.e = 0; u.kt0 = 0; u.nkt = nt; u.buf = 0;
;         if (ts) { int e = 0;
; #pragma unroll
;             for (int j = 1; j < 8; ++j) e += (u.pm >= ts[j]) ? 1 : 0;
;             u.e = e; }
;     ...
;     unsigned voffA[2], voffB[2];
; #pragma unroll
;     for (int i = 0; i < 2; ++i) { int R, C; stage_rc(tid * 16 + i * 8192, R, C); const int Rb = Epi::PERM ? ((R & ~31) + perm32(R & 31)) : R;
;         voffA[i] = (unsigned)(R * K + C) * 2u; voffB[i] = (unsigned)(Rb * K + C) * 2u; }
;     const size_t kstep = (size_t)(BK * 2);
;     const size_t hstep = (size_t)HALF * K * 2;
;     const size_t tstep = 2 * hstep;
;     const unsigned ldsw = (unsigned)wid * 1024u;
;     const int aoff = lds_byte(wr * 64 + fr, fq * 8), boff = lds_byte(wc * 32 + fr, fq * 8);
;     ...
;     Unit cur, nxt; int ui = 0;
;     if (!S.next(0, cur)) return;
;     const int sc1_ = 0x7F7F7F7F; (void)sc1_;
;     f32x4 acc[2][2][4][2];
; #pragma unroll
;     for (int a = 0; a < 2; ++a)
; #pragma unroll
;         for (int b = 0; b < 2; ++b)
; #pragma unroll
;             for (int m = 0; m < 4; ++m)
; #pragma unroll
;                 for (int n = 0; n < 2; ++n) acc[a][b][m][n] = (f32x4){0.f, 0.f, 0.f, 0.f};
;     bf16x8 At[4][2], B0[2][2], B1[2][2];
;     const char* cA = (const char*)g.A + (size_t)cur.pm * tstep + (size_t)cur.kt0 * kstep; const char* cB = (const char*)g.Bt + (size_t)cur.e * g.estride + (size_t)cur.pn * tstep + (size_t)cur.kt0 * kstep;
;     PG8_STAGE(PG8_SB(0, 0), cB, voffB); PG8_STAGE(PG8_SB(0, 1), cB + hstep, voffB); PG8_STAGE(PG8_SA(0, 0), cA, voffA); PG8_STAGE(PG8_SA(0, 1), cA + hstep, voffA);
;     if (wr == 1) PG8_BAR;
	s_ashr_i32 s41, s22, 31
	s_lshr_b32 s5, s41, 29
	s_add_i32 s5, s22, s5
	s_ashr_i32 s10, s5, 3
	s_and_b32 s5, s5, -8
	s_sub_i32 s5, s22, s5
	s_lshr_b32 s11, s5, 31
	s_add_i32 s11, s23, s11
	s_mul_i32 s5, s11, s5
	s_add_i32 s10, s5, s10
	s_ashr_i32 s5, s10, 31
	s_lshr_b32 s5, s5, 26
	s_add_i32 s11, s10, s5
	s_ashr_i32 s5, s11, 6
	s_lshl_b32 s12, s5, 3
	s_sub_i32 s5, s23, s12
	s_min_i32 s13, s5, 8
	s_abs_i32 s14, s13
	v_cvt_f32_u32_e32 v1, s14
	s_sub_i32 s16, 0, s14
	s_andn2_b32 s11, s11, 63
	s_sub_i32 s10, s10, s11
	v_rcp_iflag_f32_e32 v1, v1
	s_abs_i32 s11, s10
	s_ashr_i32 s5, s3, 6
	s_xor_b32 s15, s10, s13
	v_mul_f32_e32 v1, 0x4f7ffffe, v1
	v_cvt_u32_f32_e32 v1, v1
	s_ashr_i32 s4, s3, 8
	s_lshl_b32 s42, s5, 10
	s_ashr_i32 s15, s15, 31
	v_readfirstlane_b32 s17, v1
	s_mul_i32 s16, s16, s17
	s_mul_hi_u32 s16, s17, s16
	s_add_i32 s17, s17, s16
	s_mul_hi_u32 s16, s11, s17
	s_mul_i32 s17, s16, s14
	s_sub_i32 s11, s11, s17
	s_add_i32 s18, s16, 1
	s_sub_i32 s17, s11, s14
	s_cmp_ge_u32 s11, s14
	s_cselect_b32 s16, s18, s16
	s_cselect_b32 s11, s17, s11
	s_add_i32 s17, s16, 1
	s_cmp_ge_u32 s11, s14
	v_mov_b32_e32 v2, 0xf62000
	s_cselect_b32 s11, s17, s16
	s_xor_b32 s11, s11, s15
	global_load_dwordx4 v[2:5], v2, s[56:57] offset:8
	s_sub_i32 s64, s11, s15
	s_mul_i32 s11, s64, s13
	s_sub_i32 s10, s10, s11
	s_add_i32 s65, s12, s10
	s_add_u32 s10, s56, 0xf62008
	s_addc_u32 s11, s57, 0
	global_load_dwordx3 v[6:8], v161, s[10:11] offset:16
	global_load_dwordx4 v[240:243], v161, s[10:11]
	global_load_dwordx3 v[244:246], v161, s[10:11] offset:16
	v_lshlrev_b32_e32 v1, 4, v0
	v_bfe_i32 v11, v0, 27, 1
	v_ashrrev_i32_e32 v12, 31, v0
	v_add_u32_e32 v15, 0x2000, v1
	v_lshrrev_b32_e32 v11, 22, v11
	v_lshrrev_b32_e32 v12, 26, v12
	v_ashrrev_i32_e32 v13, 31, v15
	v_add_u32_e32 v11, v1, v11
	v_add_u32_e32 v0, v0, v12
	v_lshrrev_b32_e32 v12, 22, v13
	v_and_b32_e32 v11, 0xfffffc00, v11
	v_ashrrev_i32_e32 v13, 6, v0
	v_add_u32_e32 v0, v15, v12
	v_sub_u32_e32 v1, v1, v11
	v_lshlrev_b32_e32 v12, 3, v13
	v_ashrrev_i32_e32 v11, 10, v0
	v_lshrrev_b32_e32 v0, 4, v1
	v_and_b32_e32 v16, -16, v12
	v_mul_i32_i24_e32 v12, 0x400, v11
	v_lshlrev_b32_e32 v17, 3, v11
	v_bitop3_b32 v0, v0, v1, 32 bitop3:0x6c
	v_sub_u32_e32 v1, v15, v12
	v_and_b32_e32 v19, -16, v17
	v_ashrrev_i32_e32 v15, 31, v0
	v_lshrrev_b32_e32 v17, 4, v1
	v_lshlrev_b32_e32 v18, 5, v11
	v_lshrrev_b32_e32 v15, 26, v15
	v_bitop3_b32 v1, v17, v1, 32 bitop3:0x6c
	v_and_b32_e32 v12, 32, v18
	v_add_u32_e32 v17, v0, v15
	v_ashrrev_i32_e32 v18, 31, v1
	v_ashrrev_i32_e32 v15, 6, v17
	v_and_b32_e32 v17, 0xc0, v17
	v_lshrrev_b32_e32 v18, 26, v18
	s_mov_b32 s12, 0x7fffe0
	s_movk_i32 s26, 0xe00
	v_mov_b32_e32 v9, 1
	v_add_u32_e32 v16, v15, v16
	v_and_b32_e32 v20, 3, v15
	v_sub_u32_e32 v0, v0, v17
	v_add_u32_e32 v17, v1, v18
	v_lshlrev_b32_e32 v14, 5, v13
	v_and_or_b32 v18, v16, s12, v20
	v_lshrrev_b32_e32 v20, 2, v16
	v_lshlrev_b32_e32 v21, 1, v16
	v_ashrrev_i16_sdwa v0, v9, sext(v0) dst_sel:DWORD dst_unused:UNUSED_PAD src0_sel:DWORD src1_sel:BYTE_0
	v_mul_lo_u32 v22, v16, s26
	v_ashrrev_i32_e32 v16, 6, v17
	v_and_b32_e32 v23, 0xc0, v17
	v_and_b32_e32 v14, 32, v14
	v_and_b32_e32 v20, 4, v20
	v_and_b32_e32 v21, 24, v21
	v_bfe_i32 v17, v0, 0, 16
	v_add_u32_e32 v0, v16, v19
	v_sub_u32_e32 v1, v1, v23
	v_and_b32_e32 v19, 3, v16
	v_or3_b32 v18, v18, v20, v21
	v_add_u32_e32 v20, v14, v17
	v_lshrrev_b32_e32 v21, 2, v0
	v_lshlrev_b32_e32 v23, 1, v0
	v_ashrrev_i16_sdwa v1, v9, sext(v1) dst_sel:DWORD dst_unused:UNUSED_PAD src0_sel:DWORD src1_sel:BYTE_0
	v_and_or_b32 v19, v0, s12, v19
	v_mul_u32_u24_e32 v9, 0xe00, v18
	v_add_lshl_u32 v162, v20, v22, 1
	v_and_b32_e32 v21, 4, v21
	v_and_b32_e32 v22, 24, v23
	v_bfe_i32 v18, v1, 0, 16
	v_mul_lo_u32 v0, v0, s26
	v_or3_b32 v1, v19, v21, v22
	v_add_u32_e32 v19, v12, v18
	v_mul_u32_u24_e32 v1, 0xe00, v1
	v_add_lshl_u32 v164, v19, v0, 1
	s_waitcnt vmcnt(1)
	v_cmp_ge_i32_e32 vcc, s65, v4
	v_add_lshl_u32 v166, v1, v19, 1
	s_mov_b32 s43, 0xe00000
	v_cndmask_b32_e64 v0, 0, 1, vcc
	v_cmp_ge_i32_e32 vcc, s65, v5
	v_lshlrev_b32_e32 v0, 2, v0
	s_mul_hi_i32 s13, s64, 0x1c0000
	v_cndmask_b32_e64 v1, 0, 1, vcc
	v_lshlrev_b32_e32 v1, 3, v1
	v_cmp_ge_i32_e32 vcc, s65, v3
	v_or_b32_e32 v0, v1, v0
	s_mul_i32 s12, s64, 0x1c0000
	v_cndmask_b32_e64 v1, 0, 1, vcc
	v_cmp_ge_i32_e32 vcc, s65, v2
	v_lshlrev_b32_e32 v1, 1, v1
	s_add_i32 s44, s42, 0
	v_cndmask_b32_e64 v2, 0, 1, vcc
	v_or_b32_e32 v1, v2, v1
	v_and_b32_e32 v1, 3, v1
	s_waitcnt vmcnt(0)
	v_cmp_ge_i32_e32 vcc, s65, v8
	v_or_b32_e32 v0, v1, v0
	v_and_b32_e32 v0, 15, v0
	v_cndmask_b32_e64 v1, 0, 1, vcc
	v_cmp_ge_i32_e32 vcc, s65, v7
	v_bcnt_u32_b32 v0, v0, 0
	v_add_lshl_u32 v9, v9, v20, 1
	v_addc_co_u32_e32 v1, vcc, 0, v1, vcc
	v_cmp_ge_i32_e32 vcc, s65, v6
	s_add_i32 m0, s44, 0x10000
	s_mul_i32 s17, s65, 0x1c0000
	v_addc_co_u32_e32 v0, vcc, v1, v0, vcc
	v_mul_lo_u32 v160, v0, s43
	v_lshl_add_u64 v[0:1], s[8:9], 0, v[160:161]
	v_lshl_add_u64 v[0:1], v[0:1], 0, s[12:13]
	s_mul_hi_i32 s16, s65, 0x1c0000
	v_readfirstlane_b32 s12, v0
	v_readfirstlane_b32 s13, v1
	v_mov_b32_e32 v160, v9
	v_mov_b32_e32 v167, v161
	v_mov_b32_e32 v163, v161
	v_mov_b32_e32 v165, v161
	v_lshl_add_u64 v[6:7], v[0:1], 0, v[166:167]
	global_load_lds_dwordx4 v9, s[12:13]
	s_add_i32 m0, s44, 0x12000
	s_nop 0
	global_load_lds_dwordx4 v166, s[12:13]
	s_mov_b64 s[12:13], 0xe0000
	v_lshl_add_u64 v[2:3], v[0:1], 0, s[12:13]
	s_add_i32 m0, s44, 0x14000
	v_readfirstlane_b32 s14, v2
	v_readfirstlane_b32 s15, v3
	s_nop 4
	global_load_lds_dwordx4 v9, s[14:15]
	s_add_i32 m0, s44, 0x16000
	s_add_u32 s30, s29, s17
	s_addc_u32 s31, s34, s16
	s_add_i32 s45, s44, 0x2000
	global_load_lds_dwordx4 v166, s[14:15]
	s_mov_b32 m0, s44
	s_add_u32 s14, s30, 0xe0000
	global_load_lds_dwordx4 v162, s[30:31]
	s_mov_b32 m0, s45
	s_addc_u32 s15, s31, 0
	s_add_i32 s46, s44, 0x4000
	global_load_lds_dwordx4 v164, s[30:31]
	s_mov_b32 m0, s46
	s_add_i32 s47, s44, 0x6000
	global_load_lds_dwordx4 v162, s[14:15]
	s_mov_b32 m0, s47
	s_cmp_eq_u32 s4, 1
	global_load_lds_dwordx4 v164, s[14:15]
	v_lshl_add_u64 v[8:9], v[0:1], 0, v[160:161]
	v_lshl_add_u64 v[2:3], s[30:31], 0, v[162:163]
	s_cselect_b64 s[14:15], -1, 0
	s_cmp_lg_u32 s4, 1
	v_lshl_add_u64 v[4:5], s[30:31], 0, v[164:165]
	s_cbranch_scc1 .LBB0_4803
	s_barrier

; #define PG8_STAGE(bufoff, gbase, voff) do { _Pragma("unroll") for (int _i = 0; _i < 2; ++_i) \
;         __builtin_amdgcn_global_load_lds((const unsigned*)((const char*)(gbase) + (voff)[_i]), (LAS unsigned*)(lds + (bufoff) + ldsw + _i * 8192), 16, 0, 0); } while (0)
; #define PG8_LDA(dst, b, h) do { _Pragma("unroll") for (int m = 0; m < 4; ++m) _Pragma("unroll") for (int k = 0; k < 2; ++k) dst[m][k] = *(const LAS bf16x8*)(lds + PG8_SA(b, h) + aoff + m * 2048 + k * 1024); } while (0)
; #define PG8_LDB(dst, b, h) do { _Pragma("unroll") for (int n = 0; n < 2; ++n) _Pragma("unroll") for (int k = 0; k < 2; ++k) dst[n][k] = *(const LAS bf16x8*)(lds + PG8_SB(b, h) + boff + n * 2048 + k * 1024); } while (0)
; #define PG8_SCHED __builtin_amdgcn_sched_barrier(0)
;     __device__ __forceinline__ bool next(int i, Unit& u) const {
;         const long L = (long)i * G + c; if (L >= nwg) return false;
;         int wgid = (int)L; { const int q = nwg / NXCD, r = nwg % NXCD, xcd = wgid % NXCD, off = wgid / NXCD; wgid = (xcd < r ? xcd * (q + 1) : r * (q + 1) + (xcd - r) * q) + off; }
;         const int nig = WGM * nN, gid = wgid / nig, fm = gid * WGM, gsz = (nM - fm) < WGM ? (nM - fm) : WGM;
;         u.pm = fm + ((wgid % nig) % gsz); u.pn = (wgid % nig) / gsz; u.e = 0; u.kt0 = 0; u.nkt = nt; u.buf = 0;
;         if (ts) { int e = 0;
; #pragma unroll
;             for (int j = 1; j < 8; ++j) e += (u.pm >= ts[j]) ? 1 : 0;
;             u.e = e; }
;     ...
;             PG8_LDB(B0, 0, 0); PG8_LDB(B1, 0, 1); PG8_SCHED; PG8_LDA(At, 0, 0); PG8_STAGE(PG8_SA(1, 1), a1 + hstep, voffA);
.LBB0_4806:
	ds_read_b128 v[24:27], v168
	ds_read_b128 v[28:31], v168 offset:1024
	ds_read_b128 v[16:19], v168 offset:2048
	ds_read_b128 v[20:23], v168 offset:3072
	ds_read_b128 v[12:15], v193 offset:1024
	ds_read_b128 v[182:185], v194
	ds_read_b128 v[186:189], v194 offset:1024
	ds_read_b128 v[198:201], v194 offset:2048
	ds_read_b128 v[202:205], v194 offset:3072
	ds_read_b128 v[206:209], v194 offset:4096
	ds_read_b128 v[210:213], v194 offset:5120
	ds_read_b128 v[214:217], v194 offset:6144
	ds_read_b128 v[218:221], v194 offset:7168
	s_add_i32 s50, s50, 1
	s_mul_i32 s2, s50, s51
	s_mul_hi_u32 s3, s50, s33
	s_add_i32 s3, s3, s2
	s_mul_i32 s2, s50, s33
	s_add_u32 s2, s2, s22
	s_addc_u32 s3, s3, s41
	v_cmp_ge_i64_e32 vcc, s[2:3], v[174:175]
	v_cmp_lt_i64_e64 s[4:5], s[2:3], v[174:175]
	s_cbranch_vccnz .LBB0_4808
	s_ashr_i32 s3, s2, 31
	s_lshr_b32 s3, s3, 29
	s_add_i32 s3, s2, s3
	s_ashr_i32 s36, s3, 3
	s_and_b32 s3, s3, -8
	s_sub_i32 s2, s2, s3
	s_lshr_b32 s3, s2, 31
	s_add_i32 s3, s23, s3
	s_mul_i32 s2, s3, s2
	s_add_i32 s2, s2, s36
	s_ashr_i32 s3, s2, 31
	s_lshr_b32 s3, s3, 26
	s_add_i32 s3, s2, s3
	s_ashr_i32 s36, s3, 6
	s_lshl_b32 s36, s36, 3
	s_sub_i32 s37, s23, s36
	s_min_i32 s37, s37, 8
	s_abs_i32 s38, s37
	v_cvt_f32_u32_e32 v9, s38
	s_sub_i32 s62, 0, s38
	s_andn2_b32 s3, s3, 63
	s_sub_i32 s2, s2, s3
	v_rcp_iflag_f32_e32 v9, v9
	s_abs_i32 s3, s2
	s_xor_b32 s39, s2, s37
	s_ashr_i32 s39, s39, 31
	v_mul_f32_e32 v9, 0x4f7ffffe, v9
	v_cvt_u32_f32_e32 v9, v9
	s_nop 0
	v_readfirstlane_b32 s63, v9
	s_mul_i32 s62, s62, s63
	s_mul_hi_u32 s62, s63, s62
	s_add_i32 s63, s63, s62
	s_mul_hi_u32 s62, s3, s63
	s_mul_i32 s63, s62, s38
	s_sub_i32 s3, s3, s63
	s_add_i32 s66, s62, 1
	s_sub_i32 s63, s3, s38
	s_cmp_ge_u32 s3, s38
	s_cselect_b32 s62, s66, s62
	s_cselect_b32 s3, s63, s3
	s_add_i32 s63, s62, 1
	s_cmp_ge_u32 s3, s38
	s_cselect_b32 s3, s63, s62
	s_xor_b32 s3, s3, s39
	s_sub_i32 s62, s3, s39
	s_mul_i32 s3, s62, s37
	s_sub_i32 s2, s2, s3
	s_add_i32 s63, s2, s36
	v_cmp_ge_i32_e32 vcc, s63, v240
	s_nop 1
	v_cndmask_b32_e64 v2, 0, 1, vcc
	v_cmp_ge_i32_e32 vcc, s63, v241
	s_nop 1
	v_cndmask_b32_e64 v3, 0, 1, vcc
	v_cmp_ge_i32_e32 vcc, s63, v243
	s_nop 1
	v_cndmask_b32_e64 v5, 0, 1, vcc
	v_cmp_ge_i32_e32 vcc, s63, v245
	s_nop 1
	v_cndmask_b32_e64 v7, 0, 1, vcc
	v_cmp_ge_i32_e32 vcc, s63, v242
	s_nop 1
	v_addc_co_u32_e32 v2, vcc, v3, v2, vcc
	v_cmp_ge_i32_e32 vcc, s63, v244
	s_nop 1
	v_addc_co_u32_e32 v2, vcc, v2, v5, vcc
	v_cmp_ge_i32_e32 vcc, s63, v246
	s_nop 1
	v_addc_co_u32_e32 v197, vcc, v2, v7, vcc

; #define PG8_STAGE(bufoff, gbase, voff) do { _Pragma("unroll") for (int _i = 0; _i < 2; ++_i) \
;         __builtin_amdgcn_global_load_lds((const unsigned*)((const char*)(gbase) + (voff)[_i]), (LAS unsigned*)(lds + (bufoff) + ldsw + _i * 8192), 16, 0, 0); } while (0)
; #define PG8_LDA(dst, b, h) do { _Pragma("unroll") for (int m = 0; m < 4; ++m) _Pragma("unroll") for (int k = 0; k < 2; ++k) dst[m][k] = *(const LAS bf16x8*)(lds + PG8_SA(b, h) + aoff + m * 2048 + k * 1024); } while (0)
; #define PG8_LDB(dst, b, h) do { _Pragma("unroll") for (int n = 0; n < 2; ++n) _Pragma("unroll") for (int k = 0; k < 2; ++k) dst[n][k] = *(const LAS bf16x8*)(lds + PG8_SB(b, h) + boff + n * 2048 + k * 1024); } while (0)
; #define PG8_WAIT_V(n) asm volatile("s_waitcnt vmcnt(" #n ")" ::: "memory")
; #define PG8_WAIT_L(n) asm volatile("s_waitcnt lgkmcnt(" #n ")" ::: "memory")
; #define PG8_BAR __builtin_amdgcn_s_barrier()
; #define PG8_SCHED __builtin_amdgcn_sched_barrier(0)
;     ...
;         const char* nA = has_next ? (const char*)g.A + (size_t)nxt.pm * tstep + (size_t)nxt.kt0 * kstep : cA; const char* nB = has_next ? (const char*)g.Bt + (size_t)nxt.e * g.estride + (size_t)nxt.pn * tstep + (size_t)nxt.kt0 * kstep : cB;
;         const int nt = cur.nkt;
;         for (int t = 0; t < nt; t += 2) {
;             const bool last = (t == nt - 2);
;             const char* a1 = cA + (size_t)(t + 1) * kstep;
;             const char* a2 = last ? nA : cA + (size_t)(t + 2) * kstep; const char* b2 = last ? nB : cB + (size_t)(t + 2) * kstep;
;             const char* a3 = a2 + kstep; const char* b3 = b2 + kstep;
;             PG8_LDB(B0, 0, 0); PG8_LDB(B1, 0, 1); PG8_SCHED; PG8_LDA(At, 0, 0); PG8_STAGE(PG8_SA(1, 1), a1 + hstep, voffA);
;             PG8_WAIT_V(8); PG8_WAIT_L(0); PG8_BAR; PG8_MMA(0, 0, At, B0); PG8_MMA(0, 1, At, B1); PG8_BAR; PG8_SCHED;
;             PG8_LDA(At, 0, 1); PG8_STAGE(PG8_SB(0, 0), b2, voffB); PG8_STAGE(PG8_SB(0, 1), b2 + hstep, voffB); PG8_STAGE(PG8_SA(0, 0), a2, voffA);
;             PG8_WAIT_V(8); PG8_WAIT_L(0); PG8_BAR; PG8_MMA(1, 0, At, B0); PG8_MMA(1, 1, At, B1); PG8_BAR; PG8_SCHED;
.LBB0_4812:
	v_lshl_add_u64 v[178:179], v[0:1], 0, s[26:27]
	s_mov_b32 s66, -2
	ds_read_b128 v[8:11], v193
	ds_read_b128 v[0:3], v193 offset:2048
	ds_read_b128 v[4:7], v193 offset:3072
	s_add_u32 s36, s30, 0x100
	s_addc_u32 s37, s31, 0
	s_cmp_eq_u32 s66, 52
	s_cselect_b64 vcc, -1, 0
	s_cselect_b32 s39, s5, s37
	s_cselect_b32 s38, s4, s36
	v_cndmask_b32_e32 v181, v179, v177, vcc
	v_cndmask_b32_e32 v180, v178, v176, vcc
	v_lshl_add_u64 v[222:223], s[30:31], 0, v[170:171]
	s_add_i32 m0, s44, 0xc000
	global_load_lds_dwordx4 v[222:223], off
	v_lshl_add_u64 v[222:223], s[30:31], 0, v[172:173]
	s_add_i32 m0, s44, 0xe000
	s_nop 0
	global_load_lds_dwordx4 v[222:223], off
	s_waitcnt vmcnt(8)
	s_waitcnt lgkmcnt(0)
	s_barrier
	s_setprio 1
	s_waitcnt lgkmcnt(0)
	v_mfma_scale_f32_16x16x128_f8f6f4 v[156:159], v[24:31], v[182:189], 0, v195, v195 op_sel_hi:[0,0,0]
	v_mfma_scale_f32_16x16x128_f8f6f4 v[152:155], v[16:23], v[182:189], 0, v195, v195 op_sel_hi:[0,0,0]
	v_mfma_scale_f32_16x16x128_f8f6f4 v[140:143], v[24:31], v[198:205], 0, v195, v195 op_sel_hi:[0,0,0]
	v_mfma_scale_f32_16x16x128_f8f6f4 v[136:139], v[16:23], v[198:205], 0, v195, v195 op_sel_hi:[0,0,0]
	v_mfma_scale_f32_16x16x128_f8f6f4 v[124:127], v[24:31], v[206:213], 0, v195, v195 op_sel_hi:[0,0,0]
	v_mfma_scale_f32_16x16x128_f8f6f4 v[120:123], v[16:23], v[206:213], 0, v195, v195 op_sel_hi:[0,0,0]
	v_mfma_scale_f32_16x16x128_f8f6f4 v[108:111], v[24:31], v[214:221], 0, v195, v195 op_sel_hi:[0,0,0]
	v_mfma_scale_f32_16x16x128_f8f6f4 v[104:107], v[16:23], v[214:221], 0, v195, v195 op_sel_hi:[0,0,0]
	s_setprio 0
	s_setprio 1
	v_mfma_scale_f32_16x16x128_f8f6f4 v[148:151], v[8:15], v[182:189], 0, v195, v195 op_sel_hi:[0,0,0]
	v_mfma_scale_f32_16x16x128_f8f6f4 v[144:147], v[0:7], v[182:189], 0, v195, v195 op_sel_hi:[0,0,0]
	v_mfma_scale_f32_16x16x128_f8f6f4 v[132:135], v[8:15], v[198:205], 0, v195, v195 op_sel_hi:[0,0,0]
	v_mfma_scale_f32_16x16x128_f8f6f4 v[128:131], v[0:7], v[198:205], 0, v195, v195 op_sel_hi:[0,0,0]
	v_mfma_scale_f32_16x16x128_f8f6f4 v[116:119], v[8:15], v[206:213], 0, v195, v195 op_sel_hi:[0,0,0]
	v_mfma_scale_f32_16x16x128_f8f6f4 v[112:115], v[0:7], v[206:213], 0, v195, v195 op_sel_hi:[0,0,0]
	v_mfma_scale_f32_16x16x128_f8f6f4 v[100:103], v[8:15], v[214:221], 0, v195, v195 op_sel_hi:[0,0,0]
	v_mfma_scale_f32_16x16x128_f8f6f4 v[96:99], v[0:7], v[214:221], 0, v195, v195 op_sel_hi:[0,0,0]
	s_setprio 0
	s_barrier
	s_add_i32 s30, s54, s42
	v_lshl_add_u64 v[182:183], v[180:181], 0, v[160:161]
	s_mov_b32 m0, s30
	ds_read_b128 v[198:201], v194 offset:16384
	ds_read_b128 v[202:205], v194 offset:17408
	ds_read_b128 v[206:209], v194 offset:18432
	ds_read_b128 v[210:213], v194 offset:19456
	ds_read_b128 v[214:217], v194 offset:20480
	ds_read_b128 v[218:221], v194 offset:21504
	ds_read_b128 v[222:225], v194 offset:22528
	ds_read_b128 v[226:229], v194 offset:23552
	global_load_lds_dwordx4 v[182:183], off
	v_lshl_add_u64 v[184:185], v[180:181], 0, v[166:167]
	s_add_i32 m0, s30, 0x2000
	v_lshl_add_u64 v[186:187], v[180:181], 0, s[12:13]
	s_add_i32 s30, s55, s42
	global_load_lds_dwordx4 v[184:185], off
	v_lshl_add_u64 v[188:189], v[186:187], 0, v[160:161]
	s_mov_b32 m0, s30
	v_lshl_add_u64 v[186:187], v[186:187], 0, v[166:167]
	global_load_lds_dwordx4 v[188:189], off
	s_add_i32 m0, s30, 0x2000
	v_lshl_add_u64 v[188:189], s[38:39], 0, v[164:165]
	global_load_lds_dwordx4 v[186:187], off
	v_lshl_add_u64 v[186:187], s[38:39], 0, v[162:163]
	s_mov_b32 m0, s44
	s_nop 0
	global_load_lds_dwordx4 v[186:187], off
	s_mov_b32 m0, s45
	s_nop 0
	global_load_lds_dwordx4 v[188:189], off
	s_waitcnt vmcnt(8)
	s_waitcnt lgkmcnt(0)
	s_barrier
	s_setprio 1
	s_waitcnt lgkmcnt(0)
	v_mfma_scale_f32_16x16x128_f8f6f4 v[92:95], v[24:31], v[198:205], 0, v195, v195 op_sel_hi:[0,0,0]
	v_mfma_scale_f32_16x16x128_f8f6f4 v[88:91], v[16:23], v[198:205], 0, v195, v195 op_sel_hi:[0,0,0]
	v_mfma_scale_f32_16x16x128_f8f6f4 v[76:79], v[24:31], v[206:213], 0, v195, v195 op_sel_hi:[0,0,0]
	v_mfma_scale_f32_16x16x128_f8f6f4 v[72:75], v[16:23], v[206:213], 0, v195, v195 op_sel_hi:[0,0,0]
	v_mfma_scale_f32_16x16x128_f8f6f4 v[60:63], v[24:31], v[214:221], 0, v195, v195 op_sel_hi:[0,0,0]
	v_mfma_scale_f32_16x16x128_f8f6f4 v[56:59], v[16:23], v[214:221], 0, v195, v195 op_sel_hi:[0,0,0]
	v_mfma_scale_f32_16x16x128_f8f6f4 v[44:47], v[24:31], v[222:229], 0, v195, v195 op_sel_hi:[0,0,0]
	v_mfma_scale_f32_16x16x128_f8f6f4 v[40:43], v[16:23], v[222:229], 0, v195, v195 op_sel_hi:[0,0,0]
	s_setprio 0
	s_setprio 1
	v_mfma_scale_f32_16x16x128_f8f6f4 v[84:87], v[8:15], v[198:205], 0, v195, v195 op_sel_hi:[0,0,0]
	v_mfma_scale_f32_16x16x128_f8f6f4 v[80:83], v[0:7], v[198:205], 0, v195, v195 op_sel_hi:[0,0,0]
	v_mfma_scale_f32_16x16x128_f8f6f4 v[68:71], v[8:15], v[206:213], 0, v195, v195 op_sel_hi:[0,0,0]
	v_mfma_scale_f32_16x16x128_f8f6f4 v[64:67], v[0:7], v[206:213], 0, v195, v195 op_sel_hi:[0,0,0]
	v_mfma_scale_f32_16x16x128_f8f6f4 v[52:55], v[8:15], v[214:221], 0, v195, v195 op_sel_hi:[0,0,0]
	v_mfma_scale_f32_16x16x128_f8f6f4 v[48:51], v[0:7], v[214:221], 0, v195, v195 op_sel_hi:[0,0,0]
	v_mfma_scale_f32_16x16x128_f8f6f4 v[36:39], v[8:15], v[222:229], 0, v195, v195 op_sel_hi:[0,0,0]
	v_mfma_scale_f32_16x16x128_f8f6f4 v[32:35], v[0:7], v[222:229], 0, v195, v195 op_sel_hi:[0,0,0]
	s_setprio 0
	s_barrier
; #define PG8_STAGE(bufoff, gbase, voff) do { _Pragma("unroll") for (int _i = 0; _i < 2; ++_i) \
;         __builtin_amdgcn_global_load_lds((const unsigned*)((const char*)(gbase) + (voff)[_i]), (LAS unsigned*)(lds + (bufoff) + ldsw + _i * 8192), 16, 0, 0); } while (0)
; #define PG8_LDA(dst, b, h) do { _Pragma("unroll") for (int m = 0; m < 4; ++m) _Pragma("unroll") for (int k = 0; k < 2; ++k) dst[m][k] = *(const LAS bf16x8*)(lds + PG8_SA(b, h) + aoff + m * 2048 + k * 1024); } while (0)
; #define PG8_LDB(dst, b, h) do { _Pragma("unroll") for (int n = 0; n < 2; ++n) _Pragma("unroll") for (int k = 0; k < 2; ++k) dst[n][k] = *(const LAS bf16x8*)(lds + PG8_SB(b, h) + boff + n * 2048 + k * 1024); } while (0)
; #define PG8_WAIT_V(n) asm volatile("s_waitcnt vmcnt(" #n ")" ::: "memory")
; #define PG8_WAIT_L(n) asm volatile("s_waitcnt lgkmcnt(" #n ")" ::: "memory")
; #define PG8_BAR __builtin_amdgcn_s_barrier()
; #define PG8_SCHED __builtin_amdgcn_sched_barrier(0)
;     ...
;             PG8_LDB(B0, 1, 0); PG8_LDB(B1, 1, 1); PG8_SCHED; PG8_LDA(At, 1, 0); PG8_STAGE(PG8_SA(0, 1), a2 + hstep, voffA);
;             PG8_WAIT_V(8); PG8_WAIT_L(0); PG8_BAR; PG8_MMA(0, 0, At, B0); PG8_MMA(0, 1, At, B1); PG8_BAR; PG8_SCHED;
;             PG8_LDA(At, 1, 1); PG8_STAGE(PG8_SB(1, 0), b3, voffB); PG8_STAGE(PG8_SB(1, 1), b3 + hstep, voffB); PG8_STAGE(PG8_SA(1, 0), a3, voffA);
;             PG8_WAIT_V(8); PG8_WAIT_L(0); PG8_BAR; PG8_MMA(1, 0, At, B0); PG8_MMA(1, 1, At, B1); PG8_BAR; PG8_SCHED;
;         }
	s_add_i32 s67, 0, 0x18000
	s_add_i32 s68, 0, 0x1c000
	v_add_u32_e32 v12, s67, v191
	v_add_u32_e32 v28, s68, v191
	ds_read_b128 v[0:3], v12
	ds_read_b128 v[4:7], v12 offset:1024
	ds_read_b128 v[8:11], v12 offset:2048
	ds_read_b128 v[12:15], v12 offset:3072
	ds_read_b128 v[16:19], v28
	ds_read_b128 v[20:23], v28 offset:1024
	ds_read_b128 v[24:27], v28 offset:2048
	ds_read_b128 v[28:31], v28 offset:3072
	s_add_u32 s30, s38, 0xe0000
	s_addc_u32 s31, s39, 0
	s_mov_b32 m0, s46
	v_lshl_add_u64 v[230:231], s[30:31], 0, v[162:163]
	ds_read_b128 v[198:201], v194 offset:32768
	ds_read_b128 v[202:205], v194 offset:33792
	ds_read_b128 v[206:209], v194 offset:34816
	ds_read_b128 v[210:213], v194 offset:35840
	ds_read_b128 v[214:217], v194 offset:36864
	ds_read_b128 v[218:221], v194 offset:37888
	ds_read_b128 v[222:225], v194 offset:38912
	ds_read_b128 v[226:229], v194 offset:39936
	global_load_lds_dwordx4 v[230:231], off
	v_lshl_add_u64 v[230:231], s[30:31], 0, v[164:165]
	s_mov_b32 m0, s47
	s_nop 0
	global_load_lds_dwordx4 v[230:231], off
	s_waitcnt vmcnt(8)
	s_waitcnt lgkmcnt(0)
	s_barrier
	s_setprio 1
	s_waitcnt lgkmcnt(0)
	v_mfma_scale_f32_16x16x128_f8f6f4 v[156:159], v[0:7], v[198:205], v[156:159], v195, v195 op_sel_hi:[0,0,0]
	v_mfma_scale_f32_16x16x128_f8f6f4 v[152:155], v[8:15], v[198:205], v[152:155], v195, v195 op_sel_hi:[0,0,0]
	v_mfma_scale_f32_16x16x128_f8f6f4 v[140:143], v[0:7], v[206:213], v[140:143], v195, v195 op_sel_hi:[0,0,0]
	v_mfma_scale_f32_16x16x128_f8f6f4 v[136:139], v[8:15], v[206:213], v[136:139], v195, v195 op_sel_hi:[0,0,0]
	v_mfma_scale_f32_16x16x128_f8f6f4 v[124:127], v[0:7], v[214:221], v[124:127], v195, v195 op_sel_hi:[0,0,0]
	v_mfma_scale_f32_16x16x128_f8f6f4 v[120:123], v[8:15], v[214:221], v[120:123], v195, v195 op_sel_hi:[0,0,0]
	v_mfma_scale_f32_16x16x128_f8f6f4 v[108:111], v[0:7], v[222:229], v[108:111], v195, v195 op_sel_hi:[0,0,0]
	v_mfma_scale_f32_16x16x128_f8f6f4 v[104:107], v[8:15], v[222:229], v[104:107], v195, v195 op_sel_hi:[0,0,0]
	s_setprio 0
	s_setprio 1
	v_mfma_scale_f32_16x16x128_f8f6f4 v[148:151], v[16:23], v[198:205], v[148:151], v195, v195 op_sel_hi:[0,0,0]
	v_mfma_scale_f32_16x16x128_f8f6f4 v[144:147], v[24:31], v[198:205], v[144:147], v195, v195 op_sel_hi:[0,0,0]
	v_mfma_scale_f32_16x16x128_f8f6f4 v[132:135], v[16:23], v[206:213], v[132:135], v195, v195 op_sel_hi:[0,0,0]
	v_mfma_scale_f32_16x16x128_f8f6f4 v[128:131], v[24:31], v[206:213], v[128:131], v195, v195 op_sel_hi:[0,0,0]
	v_mfma_scale_f32_16x16x128_f8f6f4 v[116:119], v[16:23], v[214:221], v[116:119], v195, v195 op_sel_hi:[0,0,0]
	v_mfma_scale_f32_16x16x128_f8f6f4 v[112:115], v[24:31], v[214:221], v[112:115], v195, v195 op_sel_hi:[0,0,0]
	v_mfma_scale_f32_16x16x128_f8f6f4 v[100:103], v[16:23], v[222:229], v[100:103], v195, v195 op_sel_hi:[0,0,0]
	v_mfma_scale_f32_16x16x128_f8f6f4 v[96:99], v[24:31], v[222:229], v[96:99], v195, v195 op_sel_hi:[0,0,0]
	s_setprio 0
	s_barrier
	s_add_i32 s30, s67, s42
	v_lshl_add_u64 v[182:183], v[182:183], 0, s[18:19]
	s_mov_b32 m0, s30
	ds_read_b128 v[198:201], v194 offset:49152
	ds_read_b128 v[202:205], v194 offset:50176
	ds_read_b128 v[206:209], v194 offset:51200
	ds_read_b128 v[210:213], v194 offset:52224
	ds_read_b128 v[214:217], v194 offset:53248
	ds_read_b128 v[218:221], v194 offset:54272
	ds_read_b128 v[222:225], v194 offset:55296
	ds_read_b128 v[226:229], v194 offset:56320
	global_load_lds_dwordx4 v[182:183], off
	v_lshl_add_u64 v[182:183], v[184:185], 0, s[18:19]
	s_add_i32 m0, s30, 0x2000
	v_lshl_add_u64 v[180:181], v[180:181], 0, s[20:21]
	s_add_i32 s30, s68, s42
	global_load_lds_dwordx4 v[182:183], off
	v_lshl_add_u64 v[182:183], v[180:181], 0, v[160:161]
	s_mov_b32 m0, s30
	v_lshl_add_u64 v[180:181], v[180:181], 0, v[166:167]
	global_load_lds_dwordx4 v[182:183], off
	s_add_i32 m0, s30, 0x2000
	s_nop 0
	global_load_lds_dwordx4 v[180:181], off
	v_lshl_add_u64 v[180:181], v[186:187], 0, s[18:19]
	s_mov_b32 m0, s48
	s_nop 0
	global_load_lds_dwordx4 v[180:181], off
	v_lshl_add_u64 v[180:181], v[188:189], 0, s[18:19]
	s_mov_b32 m0, s49
	s_nop 0
	global_load_lds_dwordx4 v[180:181], off
	s_waitcnt vmcnt(8)
	s_waitcnt lgkmcnt(0)
	s_barrier
	s_setprio 1
	s_waitcnt lgkmcnt(0)
	v_mfma_scale_f32_16x16x128_f8f6f4 v[92:95], v[0:7], v[198:205], v[92:95], v195, v195 op_sel_hi:[0,0,0]
	v_mfma_scale_f32_16x16x128_f8f6f4 v[88:91], v[8:15], v[198:205], v[88:91], v195, v195 op_sel_hi:[0,0,0]
	v_mfma_scale_f32_16x16x128_f8f6f4 v[76:79], v[0:7], v[206:213], v[76:79], v195, v195 op_sel_hi:[0,0,0]
	v_mfma_scale_f32_16x16x128_f8f6f4 v[72:75], v[8:15], v[206:213], v[72:75], v195, v195 op_sel_hi:[0,0,0]
	v_mfma_scale_f32_16x16x128_f8f6f4 v[60:63], v[0:7], v[214:221], v[60:63], v195, v195 op_sel_hi:[0,0,0]
	v_mfma_scale_f32_16x16x128_f8f6f4 v[56:59], v[8:15], v[214:221], v[56:59], v195, v195 op_sel_hi:[0,0,0]
	v_mfma_scale_f32_16x16x128_f8f6f4 v[44:47], v[0:7], v[222:229], v[44:47], v195, v195 op_sel_hi:[0,0,0]
	v_mfma_scale_f32_16x16x128_f8f6f4 v[40:43], v[8:15], v[222:229], v[40:43], v195, v195 op_sel_hi:[0,0,0]
	s_setprio 0
	s_setprio 1
	v_mfma_scale_f32_16x16x128_f8f6f4 v[84:87], v[16:23], v[198:205], v[84:87], v195, v195 op_sel_hi:[0,0,0]
	v_mfma_scale_f32_16x16x128_f8f6f4 v[80:83], v[24:31], v[198:205], v[80:83], v195, v195 op_sel_hi:[0,0,0]
	v_mfma_scale_f32_16x16x128_f8f6f4 v[68:71], v[16:23], v[206:213], v[68:71], v195, v195 op_sel_hi:[0,0,0]
	v_mfma_scale_f32_16x16x128_f8f6f4 v[64:67], v[24:31], v[206:213], v[64:67], v195, v195 op_sel_hi:[0,0,0]
	v_mfma_scale_f32_16x16x128_f8f6f4 v[52:55], v[16:23], v[214:221], v[52:55], v195, v195 op_sel_hi:[0,0,0]
	v_mfma_scale_f32_16x16x128_f8f6f4 v[48:51], v[24:31], v[214:221], v[48:51], v195, v195 op_sel_hi:[0,0,0]
	v_mfma_scale_f32_16x16x128_f8f6f4 v[36:39], v[16:23], v[222:229], v[36:39], v195, v195 op_sel_hi:[0,0,0]
	v_mfma_scale_f32_16x16x128_f8f6f4 v[32:35], v[24:31], v[222:229], v[32:35], v195, v195 op_sel_hi:[0,0,0]
	s_setprio 0
	s_barrier
	s_add_i32 s66, s66, 2
	v_lshl_add_u64 v[178:179], v[178:179], 0, s[26:27]
	s_cmp_gt_u32 s66, 53
	s_mov_b64 s[30:31], s[36:37]
	s_cbranch_scc0 .LBB0_4813
